# scan chunk loops: counted vmcnt at loop top (prefetched loads older than the 4 output stores); flat loads/stores of scan state rewritten as global; attention epilogue gamma/gate loads hoisted above th
# speedup vs baseline: 1.0084x; 1.0084x over previous
.LBB0_685:
	ds_bpermute_b32 v0, v188, v175
	ds_bpermute_b32 v1, v188, v174
	s_lshl_b32 s2, s15, 1
	v_mov_b32_e32 v149, v145
	s_add_i32 s28, s28, s78
	s_waitcnt lgkmcnt(1)
	v_add_f32_e32 v0, v175, v0
	ds_bpermute_b32 v2, v187, v0
	s_waitcnt lgkmcnt(1)
	v_add_f32_e32 v1, v174, v1
	ds_bpermute_b32 v3, v187, v1
	s_cmpk_gt_i32 s28, 0x5ff
	s_waitcnt lgkmcnt(1)
	v_add_f32_e32 v0, v0, v2
	s_waitcnt lgkmcnt(0)
	v_add_f32_e32 v1, v1, v3
	v_rcp_f32_e32 v10, v0
	v_rcp_f32_e32 v0, v1
	s_nop 0
	v_mul_f32_e32 v12, v190, v0
	v_pk_mul_f32 v[2:3], v[78:79], v[12:13] op_sel_hi:[1,0]
	v_pk_mul_f32 v[6:7], v[70:71], v[12:13] op_sel_hi:[1,0]
	v_pk_fma_f32 v[4:5], v[74:75], v[10:11], v[2:3] op_sel_hi:[1,0,1] neg_lo:[0,0,1] neg_hi:[0,0,1]
	v_lshl_add_u64 v[2:3], s[4:5], 0, v[152:153]
	v_lshl_add_u64 v[2:3], v[2:3], 0, s[2:3]
	v_lshl_add_u64 v[2:3], v[2:3], 0, v[148:149]
	global_load_dwordx2 v[74:75], v[2:3], off
	v_pk_fma_f32 v[66:67], v[66:67], v[10:11], v[6:7] op_sel_hi:[1,0,1] neg_lo:[0,0,1] neg_hi:[0,0,1]
	global_load_dwordx4 v[6:9], v[146:147], off
	v_pk_mul_f32 v[68:69], v[68:69], v[12:13] op_sel_hi:[1,0]
	v_pk_mul_f32 v[0:1], v[76:77], v[12:13] op_sel_hi:[1,0]
	v_pk_fma_f32 v[64:65], v[64:65], v[10:11], v[68:69] op_sel_hi:[1,0,1] neg_lo:[0,0,1] neg_hi:[0,0,1]
	v_pk_mul_f32 v[62:63], v[62:63], v[12:13] op_sel_hi:[1,0]
	v_pk_mul_f32 v[68:69], v[64:65], v[64:65]
	v_pk_mul_f32 v[60:61], v[60:61], v[12:13] op_sel_hi:[1,0]
	v_pk_mul_f32 v[54:55], v[54:55], v[12:13] op_sel_hi:[1,0]
	v_pk_mul_f32 v[52:53], v[52:53], v[12:13] op_sel_hi:[1,0]
	v_pk_mul_f32 v[46:47], v[46:47], v[12:13] op_sel_hi:[1,0]
	v_pk_mul_f32 v[44:45], v[44:45], v[12:13] op_sel_hi:[1,0]
	v_pk_mul_f32 v[38:39], v[38:39], v[12:13] op_sel_hi:[1,0]
	v_pk_mul_f32 v[36:37], v[36:37], v[12:13] op_sel_hi:[1,0]
	v_pk_mul_f32 v[30:31], v[30:31], v[12:13] op_sel_hi:[1,0]
	v_pk_mul_f32 v[28:29], v[28:29], v[12:13] op_sel_hi:[1,0]
	v_pk_mul_f32 v[22:23], v[22:23], v[12:13] op_sel_hi:[1,0]
	v_pk_mul_f32 v[12:13], v[20:21], v[12:13] op_sel_hi:[1,0]
	v_pk_fma_f32 v[0:1], v[72:73], v[10:11], v[0:1] op_sel_hi:[1,0,1] neg_lo:[0,0,1] neg_hi:[0,0,1]
	v_pk_mul_f32 v[70:71], v[66:67], v[66:67]
	v_pk_fma_f32 v[58:59], v[58:59], v[10:11], v[62:63] op_sel_hi:[1,0,1] neg_lo:[0,0,1] neg_hi:[0,0,1]
	v_pk_fma_f32 v[56:57], v[56:57], v[10:11], v[60:61] op_sel_hi:[1,0,1] neg_lo:[0,0,1] neg_hi:[0,0,1]
	v_pk_fma_f32 v[50:51], v[50:51], v[10:11], v[54:55] op_sel_hi:[1,0,1] neg_lo:[0,0,1] neg_hi:[0,0,1]
	v_pk_fma_f32 v[48:49], v[48:49], v[10:11], v[52:53] op_sel_hi:[1,0,1] neg_lo:[0,0,1] neg_hi:[0,0,1]
	v_pk_fma_f32 v[42:43], v[42:43], v[10:11], v[46:47] op_sel_hi:[1,0,1] neg_lo:[0,0,1] neg_hi:[0,0,1]
	v_pk_fma_f32 v[40:41], v[40:41], v[10:11], v[44:45] op_sel_hi:[1,0,1] neg_lo:[0,0,1] neg_hi:[0,0,1]
	v_pk_fma_f32 v[34:35], v[34:35], v[10:11], v[38:39] op_sel_hi:[1,0,1] neg_lo:[0,0,1] neg_hi:[0,0,1]
	v_pk_fma_f32 v[32:33], v[32:33], v[10:11], v[36:37] op_sel_hi:[1,0,1] neg_lo:[0,0,1] neg_hi:[0,0,1]
	v_pk_fma_f32 v[26:27], v[26:27], v[10:11], v[30:31] op_sel_hi:[1,0,1] neg_lo:[0,0,1] neg_hi:[0,0,1]
	v_pk_fma_f32 v[24:25], v[24:25], v[10:11], v[28:29] op_sel_hi:[1,0,1] neg_lo:[0,0,1] neg_hi:[0,0,1]
	v_pk_fma_f32 v[18:19], v[18:19], v[10:11], v[22:23] op_sel_hi:[1,0,1] neg_lo:[0,0,1] neg_hi:[0,0,1]
	v_pk_fma_f32 v[10:11], v[16:17], v[10:11], v[12:13] op_sel_hi:[1,0,1] neg_lo:[0,0,1] neg_hi:[0,0,1]
	v_add_f32_e32 v16, v68, v69
	v_add_f32_e32 v16, v70, v16
	v_pk_mul_f32 v[60:61], v[56:57], v[56:57]
	v_add_f32_e32 v16, v71, v16
	v_add_f32_e32 v16, v60, v16
	v_pk_mul_f32 v[62:63], v[58:59], v[58:59]
	v_add_f32_e32 v16, v61, v16
	v_add_f32_e32 v16, v62, v16
	v_pk_mul_f32 v[52:53], v[48:49], v[48:49]
	v_add_f32_e32 v16, v63, v16
	v_add_f32_e32 v16, v52, v16
	v_pk_mul_f32 v[54:55], v[50:51], v[50:51]
	v_add_f32_e32 v16, v53, v16
	v_add_f32_e32 v16, v54, v16
	v_pk_mul_f32 v[44:45], v[40:41], v[40:41]
	v_add_f32_e32 v16, v55, v16
	v_add_f32_e32 v16, v44, v16
	v_pk_mul_f32 v[46:47], v[42:43], v[42:43]
	v_add_f32_e32 v16, v45, v16
	v_add_f32_e32 v16, v46, v16
	v_pk_mul_f32 v[36:37], v[32:33], v[32:33]
	v_add_f32_e32 v16, v47, v16
	v_add_f32_e32 v16, v36, v16
	v_pk_mul_f32 v[38:39], v[34:35], v[34:35]
	v_add_f32_e32 v16, v37, v16
	v_add_f32_e32 v16, v38, v16
	v_pk_mul_f32 v[28:29], v[24:25], v[24:25]
	v_add_f32_e32 v16, v39, v16
	v_add_f32_e32 v16, v28, v16
	v_pk_mul_f32 v[30:31], v[26:27], v[26:27]
	v_add_f32_e32 v16, v29, v16
	v_add_f32_e32 v16, v30, v16
	v_pk_mul_f32 v[12:13], v[10:11], v[10:11]
	v_add_f32_e32 v16, v31, v16
	v_add_f32_e32 v12, v12, v16
	v_pk_mul_f32 v[22:23], v[18:19], v[18:19]
	v_add_f32_e32 v12, v13, v12
	v_add_f32_e32 v12, v22, v12
	v_pk_mul_f32 v[14:15], v[0:1], v[0:1]
	v_add_f32_e32 v12, v23, v12
	v_add_f32_e32 v12, v14, v12
	v_pk_mul_f32 v[72:73], v[4:5], v[4:5]
	v_add_f32_e32 v12, v15, v12
	v_add_f32_e32 v12, v72, v12
	v_add_f32_e32 v12, v73, v12
	global_load_dwordx4 v[244:247], v[146:147], off offset:64
	global_load_dwordx4 v[36:39], v[146:147], off offset:128
	global_load_dwordx4 v[44:47], v[146:147], off offset:192
	global_load_dwordx4 v[52:55], v[146:147], off offset:256
	global_load_dwordx4 v[60:63], v[146:147], off offset:320
	global_load_dwordx4 v[68:71], v[146:147], off offset:384
	global_load_dwordx4 v[76:79], v[146:147], off offset:448
	ds_bpermute_b32 v13, v188, v12
	s_waitcnt vmcnt(8)
	v_and_b32_e32 v23, 0xffff0000, v75
	v_lshlrev_b32_e32 v20, 16, v74
	s_waitcnt lgkmcnt(0)
	v_add_f32_e32 v21, v12, v13
	ds_bpermute_b32 v22, v187, v21
	global_load_dwordx2 v[12:13], v[2:3], off offset:32
	global_load_dwordx2 v[14:15], v[2:3], off offset:64
	global_load_dwordx2 v[16:17], v[2:3], off offset:96
	global_load_dwordx2 v[248:249], v[2:3], off offset:128
	global_load_dwordx2 v[250:251], v[2:3], off offset:160
	global_load_dwordx2 v[252:253], v[2:3], off offset:192
	global_load_dwordx2 v[254:255], v[2:3], off offset:224
	s_waitcnt lgkmcnt(0)
	v_add_f32_e32 v21, v21, v22
	v_fmamk_f32 v21, v21, 0x3c000000, v213
	v_mul_f32_e32 v22, 0x4b800000, v21
	v_cmp_gt_f32_e32 vcc, s27, v21
	s_nop 1
	v_cndmask_b32_e32 v21, v21, v22, vcc
	v_rsq_f32_e32 v28, v21
	v_lshlrev_b32_e32 v22, 16, v75
	v_and_b32_e32 v21, 0xffff0000, v74
	v_mul_f32_e32 v29, 0x45800000, v28
	v_cndmask_b32_e32 v28, v28, v29, vcc
	v_mul_f32_e32 v28, 0x3f4ccccd, v28
	v_pk_mul_f32 v[30:31], v[66:67], v[28:29] op_sel_hi:[1,0]
	v_pk_mul_f32 v[10:11], v[10:11], v[28:29] op_sel_hi:[1,0]
	s_waitcnt vmcnt(14)
	v_pk_mul_f32 v[8:9], v[8:9], v[30:31]
	v_pk_mul_f32 v[4:5], v[4:5], v[28:29] op_sel_hi:[1,0]
	v_pk_mul_f32 v[8:9], v[8:9], v[22:23]
	v_pk_mul_f32 v[22:23], v[64:65], v[28:29] op_sel_hi:[1,0]
	v_pk_mul_f32 v[0:1], v[0:1], v[28:29] op_sel_hi:[1,0]
	v_pk_mul_f32 v[6:7], v[6:7], v[22:23]
	v_pk_mul_f32 v[22:23], v[56:57], v[28:29] op_sel_hi:[1,0]
	v_pk_mul_f32 v[6:7], v[6:7], v[20:21]
	v_pk_mul_f32 v[20:21], v[58:59], v[28:29] op_sel_hi:[1,0]
	v_cvt_pk_bf16_f32 v6, v6, v7
	v_cvt_pk_bf16_f32 v7, v8, v9
	global_store_dwordx2 v[2:3], v[6:7], off
	s_waitcnt vmcnt(7)
	v_lshlrev_b32_e32 v30, 16, v12
	v_and_b32_e32 v31, 0xffff0000, v12
	v_lshlrev_b32_e32 v12, 16, v13
	v_and_b32_e32 v13, 0xffff0000, v13
	v_pk_mul_f32 v[8:9], v[246:247], v[20:21]
	v_pk_mul_f32 v[6:7], v[244:245], v[22:23]
	v_pk_mul_f32 v[8:9], v[8:9], v[12:13]
	v_pk_mul_f32 v[6:7], v[6:7], v[30:31]
	v_pk_mul_f32 v[12:13], v[50:51], v[28:29] op_sel_hi:[1,0]
	v_cvt_pk_bf16_f32 v6, v6, v7
	v_cvt_pk_bf16_f32 v7, v8, v9
	global_store_dwordx2 v[2:3], v[6:7], off offset:32
	v_pk_mul_f32 v[20:21], v[48:49], v[28:29] op_sel_hi:[1,0]
	s_waitcnt vmcnt(7)
	v_lshlrev_b32_e32 v22, 16, v14
	v_and_b32_e32 v23, 0xffff0000, v14
	v_lshlrev_b32_e32 v14, 16, v15
	v_and_b32_e32 v15, 0xffff0000, v15
	v_pk_mul_f32 v[30:31], v[32:33], v[28:29] op_sel_hi:[1,0]
	v_pk_mul_f32 v[8:9], v[38:39], v[12:13]
	v_pk_mul_f32 v[6:7], v[36:37], v[20:21]
	v_pk_mul_f32 v[8:9], v[8:9], v[14:15]
	v_pk_mul_f32 v[6:7], v[6:7], v[22:23]
	v_pk_mul_f32 v[14:15], v[42:43], v[28:29] op_sel_hi:[1,0]
	v_cvt_pk_bf16_f32 v6, v6, v7
	v_cvt_pk_bf16_f32 v7, v8, v9
	global_store_dwordx2 v[2:3], v[6:7], off offset:64
	s_nop 0
	v_pk_mul_f32 v[20:21], v[40:41], v[28:29] op_sel_hi:[1,0]
	s_waitcnt vmcnt(7)
	v_lshlrev_b32_e32 v22, 16, v16
	v_and_b32_e32 v23, 0xffff0000, v16
	v_lshlrev_b32_e32 v16, 16, v17
	v_and_b32_e32 v17, 0xffff0000, v17
	v_pk_mul_f32 v[8:9], v[46:47], v[14:15]
	v_pk_mul_f32 v[6:7], v[44:45], v[20:21]
	v_pk_mul_f32 v[8:9], v[8:9], v[16:17]
	v_pk_mul_f32 v[6:7], v[6:7], v[22:23]
	v_pk_mul_f32 v[22:23], v[34:35], v[28:29] op_sel_hi:[1,0]
	v_cvt_pk_bf16_f32 v6, v6, v7
	v_cvt_pk_bf16_f32 v7, v8, v9
	global_store_dwordx2 v[2:3], v[6:7], off offset:96
	s_nop 0
	s_waitcnt vmcnt(7)
	v_lshlrev_b32_e32 v32, 16, v248
	v_and_b32_e32 v33, 0xffff0000, v248
	v_lshlrev_b32_e32 v12, 16, v249
	v_and_b32_e32 v13, 0xffff0000, v249
	v_pk_mul_f32 v[8:9], v[54:55], v[22:23]
	v_pk_mul_f32 v[6:7], v[52:53], v[30:31]
	v_pk_mul_f32 v[8:9], v[8:9], v[12:13]
	v_pk_mul_f32 v[6:7], v[6:7], v[32:33]
	v_pk_mul_f32 v[12:13], v[26:27], v[28:29] op_sel_hi:[1,0]
	v_cvt_pk_bf16_f32 v6, v6, v7
	v_cvt_pk_bf16_f32 v7, v8, v9
	global_store_dwordx2 v[2:3], v[6:7], off offset:128
	v_pk_mul_f32 v[22:23], v[24:25], v[28:29] op_sel_hi:[1,0]
	s_waitcnt vmcnt(7)
	v_lshlrev_b32_e32 v24, 16, v250
	v_and_b32_e32 v25, 0xffff0000, v250
	v_lshlrev_b32_e32 v14, 16, v251
	v_and_b32_e32 v15, 0xffff0000, v251
	v_pk_mul_f32 v[8:9], v[62:63], v[12:13]
	v_pk_mul_f32 v[6:7], v[60:61], v[22:23]
	v_pk_mul_f32 v[8:9], v[8:9], v[14:15]
	v_pk_mul_f32 v[6:7], v[6:7], v[24:25]
	v_pk_mul_f32 v[12:13], v[18:19], v[28:29] op_sel_hi:[1,0]
	v_cvt_pk_bf16_f32 v6, v6, v7
	v_cvt_pk_bf16_f32 v7, v8, v9
	global_store_dwordx2 v[2:3], v[6:7], off offset:160
	s_waitcnt vmcnt(7)
	v_lshlrev_b32_e32 v14, 16, v252
	v_and_b32_e32 v15, 0xffff0000, v252
	v_lshlrev_b32_e32 v16, 16, v253
	v_and_b32_e32 v17, 0xffff0000, v253
	v_pk_mul_f32 v[8:9], v[12:13], v[70:71]
	v_pk_mul_f32 v[6:7], v[10:11], v[68:69]
	v_pk_mul_f32 v[8:9], v[8:9], v[16:17]
	v_pk_mul_f32 v[6:7], v[6:7], v[14:15]
	s_waitcnt vmcnt(6)
	v_lshlrev_b32_e32 v10, 16, v254
	v_cvt_pk_bf16_f32 v6, v6, v7
	v_cvt_pk_bf16_f32 v7, v8, v9
	global_store_dwordx2 v[2:3], v[6:7], off offset:192
	v_and_b32_e32 v11, 0xffff0000, v254
	v_lshlrev_b32_e32 v12, 16, v255
	v_and_b32_e32 v13, 0xffff0000, v255
	v_pk_mul_f32 v[4:5], v[4:5], v[78:79]
	v_pk_mul_f32 v[0:1], v[0:1], v[76:77]
	v_pk_mul_f32 v[4:5], v[4:5], v[12:13]
	v_pk_mul_f32 v[0:1], v[0:1], v[10:11]
	s_nop 0
	v_cvt_pk_bf16_f32 v0, v0, v1
	v_cvt_pk_bf16_f32 v1, v4, v5
	global_store_dwordx2 v[2:3], v[0:1], off offset:224
	s_cbranch_scc1 .LBB0_713

.LBB0_1041:
	v_ashrrev_i32_e32 v0, 31, v92
	v_lshrrev_b32_e32 v1, 30, v0
	v_add_u32_e32 v1, v92, v1
	v_lshrrev_b32_e32 v0, 27, v0
	v_bfe_u32 v34, v1, 2, 3
	v_add_u32_e32 v0, v92, v0
	v_ashrrev_i32_e32 v32, 5, v0
	v_lshlrev_b32_e32 v0, 2, v34
	global_load_dword v0, v0, s[84:85] offset:32
	v_and_b32_e32 v2, 0x3fffffc, v1
	v_sub_u32_e32 v2, v92, v2
	s_mov_b32 s50, 0x3fb8aa3b
	v_lshlrev_b32_e32 v78, 6, v2
	v_readlane_b32 s80, v241, 18
	v_readlane_b32 s88, v241, 26
	v_readlane_b32 s89, v241, 27
	v_ashrrev_i32_e32 v79, 31, v78
	s_waitcnt vmcnt(0)
	v_mov_b32_e32 v67, v65
	v_mov_b32_e32 v69, v65
	v_mov_b32_e32 v71, v65
	v_readlane_b32 s81, v241, 19
	v_readlane_b32 s82, v241, 20
	v_readlane_b32 s83, v241, 21
	v_readlane_b32 s84, v241, 22
	v_readlane_b32 s85, v241, 23
	v_readlane_b32 s86, v241, 24
	v_readlane_b32 s87, v241, 25
	v_readlane_b32 s90, v241, 28
	v_readlane_b32 s91, v241, 29
	v_readlane_b32 s92, v241, 30
	v_readlane_b32 s93, v241, 31
	v_readlane_b32 s94, v241, 32
	v_readlane_b32 s95, v241, 33
	s_waitcnt vmcnt(0)
	v_mul_f32_e32 v1, 0x3fb8aa3b, v0
	v_fma_f32 v2, v0, s50, -v1
	v_rndne_f32_e32 v3, v1
	v_fmac_f32_e32 v2, 0x32a5705f, v0
	v_sub_f32_e32 v1, v1, v3
	v_add_f32_e32 v1, v1, v2
	v_exp_f32_e32 v1, v1
	v_cvt_i32_f32_e32 v2, v3
	s_mov_b32 s50, 0xc2ce8ed0
	v_cmp_ngt_f32_e32 vcc, s50, v0
	s_mov_b32 s50, 0x42b17218
	v_ldexp_f32 v1, v1, v2
	v_cndmask_b32_e32 v1, 0, v1, vcc
	v_cmp_nlt_f32_e32 vcc, s50, v0
	s_mov_b32 s50, 0x3f2aaaab
	s_nop 0
	v_cndmask_b32_e32 v2, v129, v1, vcc
	v_sub_f32_e32 v3, 1.0, v2
	v_add_f32_e32 v0, -1.0, v3
	v_sub_f32_e32 v1, v0, v3
	v_add_f32_e32 v1, 1.0, v1
	v_sub_f32_e64 v0, -v2, v0
	v_add_f32_e32 v4, v0, v1
	v_frexp_mant_f32_e32 v0, v3
	v_cmp_gt_f32_e32 vcc, s50, v0
	v_cvt_f64_f32_e32 v[0:1], v3
	v_frexp_exp_i32_f64_e32 v0, v[0:1]
	v_subbrev_co_u32_e32 v0, vcc, 0, v0, vcc
	v_sub_u32_e32 v1, 0, v0
	v_ldexp_f32 v3, v3, v1
	v_ldexp_f32 v1, v4, v1
	v_add_f32_e32 v4, -1.0, v3
	v_add_f32_e32 v5, 1.0, v4
	v_sub_f32_e32 v5, v3, v5
	v_add_f32_e32 v5, v1, v5
	v_add_f32_e32 v6, v4, v5
	v_sub_f32_e32 v4, v6, v4
	v_sub_f32_e32 v4, v5, v4
	v_add_f32_e32 v5, 1.0, v3
	v_add_f32_e32 v7, -1.0, v5
	v_sub_f32_e32 v3, v3, v7
	v_add_f32_e32 v1, v1, v3
	v_add_f32_e32 v3, v5, v1
	v_sub_f32_e32 v5, v3, v5
	v_sub_f32_e32 v1, v1, v5
	v_rcp_f32_e32 v5, v3
	v_cvt_f32_i32_e32 v0, v0
	s_mov_b32 s50, 0x3f317218
	v_cmp_nlt_f32_e32 vcc, 1.0, v2
	v_mul_f32_e32 v7, v6, v5
	v_mul_f32_e32 v8, v3, v7
	v_fma_f32 v9, v7, v3, -v8
	v_fmac_f32_e32 v9, v7, v1
	v_add_f32_e32 v10, v8, v9
	v_sub_f32_e32 v11, v6, v10
	v_sub_f32_e32 v6, v6, v11
	v_sub_f32_e32 v8, v10, v8
	v_sub_f32_e32 v6, v6, v10
	v_add_f32_e32 v4, v4, v6
	v_sub_f32_e32 v6, v8, v9
	v_add_f32_e32 v4, v6, v4
	v_add_f32_e32 v6, v11, v4
	v_mul_f32_e32 v8, v5, v6
	v_mul_f32_e32 v9, v3, v8
	v_fma_f32 v3, v8, v3, -v9
	v_fmac_f32_e32 v3, v8, v1
	v_sub_f32_e32 v1, v11, v6
	v_add_f32_e32 v1, v4, v1
	v_add_f32_e32 v4, v9, v3
	v_sub_f32_e32 v10, v6, v4
	v_sub_f32_e32 v6, v6, v10
	v_sub_f32_e32 v9, v4, v9
	v_sub_f32_e32 v4, v6, v4
	v_add_f32_e32 v1, v1, v4
	v_sub_f32_e32 v3, v9, v3
	v_add_f32_e32 v1, v3, v1
	v_add_f32_e32 v3, v7, v8
	v_add_f32_e32 v1, v10, v1
	v_sub_f32_e32 v4, v3, v7
	v_mul_f32_e32 v1, v5, v1
	v_sub_f32_e32 v4, v8, v4
	v_add_f32_e32 v1, v4, v1
	v_mul_f32_e32 v7, 0x3f317218, v0
	v_add_f32_e32 v4, v3, v1
	v_fma_f32 v8, v0, s50, -v7
	v_mul_f32_e32 v5, v4, v4
	v_fmac_f32_e32 v8, 0xb102e308, v0
	v_sub_f32_e32 v0, v4, v3
	v_fmamk_f32 v6, v5, 0x3e9b6dac, v104
	v_sub_f32_e32 v0, v1, v0
	v_add_f32_e32 v1, v7, v8
	v_fmaak_f32 v6, v5, v6, 0x3f2aaada
	v_sub_f32_e32 v3, v1, v7
	v_ldexp_f32 v7, v4, 1
	v_mul_f32_e32 v4, v4, v5
	v_mul_f32_e32 v4, v4, v6
	v_add_f32_e32 v5, v7, v4
	v_sub_f32_e32 v6, v5, v7
	v_ldexp_f32 v0, v0, 1
	v_sub_f32_e32 v4, v4, v6
	v_add_f32_e32 v0, v0, v4
	v_add_f32_e32 v4, v5, v0
	v_sub_f32_e32 v5, v4, v5
	v_sub_f32_e32 v0, v0, v5
	v_add_f32_e32 v5, v1, v4
	v_sub_f32_e32 v6, v5, v1
	v_sub_f32_e32 v7, v5, v6
	v_sub_f32_e32 v3, v8, v3
	v_sub_f32_e32 v1, v1, v7
	v_sub_f32_e32 v4, v4, v6
	v_add_f32_e32 v1, v4, v1
	v_add_f32_e32 v4, v3, v0
	v_sub_f32_e32 v6, v4, v3
	v_sub_f32_e32 v7, v4, v6
	v_sub_f32_e32 v3, v3, v7
	v_sub_f32_e32 v0, v0, v6
	v_add_f32_e32 v1, v4, v1
	v_add_f32_e32 v0, v0, v3
	v_add_f32_e32 v3, v5, v1
	v_sub_f32_e32 v4, v3, v5
	v_sub_f32_e32 v1, v1, v4
	v_add_f32_e32 v0, v0, v1
	v_add_f32_e32 v0, v3, v0
	v_cndmask_b32_e32 v0, v130, v0, vcc
	v_cmp_neq_f32_e32 vcc, 1.0, v2
	s_mov_b32 s50, 0x33800000
	v_cmp_lt_f32_e64 s[54:55], |v2|, s50
	v_cndmask_b32_e32 v0, v131, v0, vcc
	s_mov_b32 s50, 0x8000
	v_cndmask_b32_e64 v0, v0, -v2, s[54:55]
	v_mul_f32_e32 v33, 0x3fb8aa3b, v0
	v_lshlrev_b32_e32 v0, 4, v32
	v_or3_b32 v0, v0, v34, 8
	v_ashrrev_i32_e32 v1, 31, v0
	v_lshlrev_b64 v[0:1], 17, v[0:1]
	v_lshl_add_u64 v[0:1], s[88:89], 0, v[0:1]
	v_lshl_add_u64 v[0:1], v[78:79], 2, v[0:1]
	v_lshl_add_u64 v[0:1], v[0:1], 0, v[66:67]
	v_lshl_add_u64 v[0:1], v[0:1], 0, v[68:69]
	v_lshl_add_u64 v[28:29], v[0:1], 0, v[70:71]
	global_load_dword v4, v[28:29], off
	global_load_dword v5, v[28:29], off offset:1024
	global_load_dword v6, v[28:29], off offset:2048
	global_load_dword v7, v[28:29], off offset:3072
	v_add_co_u32_e32 v8, vcc, s56, v28
	s_nop 1
	v_addc_co_u32_e32 v9, vcc, 0, v29, vcc
	v_add_co_u32_e32 v12, vcc, s50, v28
	s_mov_b32 s50, 0xc000
	s_nop 0
	v_addc_co_u32_e32 v13, vcc, 0, v29, vcc
	v_add_co_u32_e32 v16, vcc, s50, v28
	s_mov_b32 s50, 0x10000
	s_nop 0
	v_addc_co_u32_e32 v17, vcc, 0, v29, vcc
	v_add_co_u32_e32 v20, vcc, s50, v28
	s_mov_b32 s50, 0x14000
	s_nop 0
	v_addc_co_u32_e32 v21, vcc, 0, v29, vcc
	v_add_co_u32_e32 v24, vcc, s50, v28
	global_load_dword v0, v[8:9], off
	global_load_dword v1, v[8:9], off offset:1024
	global_load_dword v2, v[8:9], off offset:2048
	global_load_dword v3, v[8:9], off offset:3072
	v_addc_co_u32_e32 v25, vcc, 0, v29, vcc
	v_add_co_u32_e32 v30, vcc, 0x18000, v28
	global_load_dword v8, v[12:13], off
	global_load_dword v9, v[12:13], off offset:1024
	global_load_dword v10, v[12:13], off offset:2048
	global_load_dword v11, v[12:13], off offset:3072
	v_addc_co_u32_e32 v31, vcc, 0, v29, vcc
	v_add_co_u32_e32 v36, vcc, 0x1c000, v28
	global_load_dword v12, v[16:17], off
	global_load_dword v13, v[16:17], off offset:1024
	global_load_dword v14, v[16:17], off offset:2048
	global_load_dword v15, v[16:17], off offset:3072
	v_addc_co_u32_e32 v37, vcc, 0, v29, vcc
	global_load_dword v16, v[20:21], off
	global_load_dword v17, v[20:21], off offset:1024
	global_load_dword v18, v[20:21], off offset:2048
	global_load_dword v19, v[20:21], off offset:3072
	s_nop 0
	global_load_dword v20, v[24:25], off
	global_load_dword v21, v[24:25], off offset:1024
	global_load_dword v22, v[24:25], off offset:2048
	global_load_dword v23, v[24:25], off offset:3072
	s_nop 0
	global_load_dword v24, v[30:31], off
	global_load_dword v25, v[30:31], off offset:1024
	global_load_dword v26, v[30:31], off offset:2048
	global_load_dword v27, v[30:31], off offset:3072
	global_load_dword v28, v[36:37], off
	global_load_dword v29, v[36:37], off offset:1024
	s_nop 0
	global_load_dword v30, v[36:37], off offset:2048
	global_load_dword v31, v[36:37], off offset:3072
	s_and_saveexec_b64 s[54:55], s[40:41]
	s_cbranch_execz .LBB0_1043
	v_mul_f32_e32 v35, v33, v93
	v_exp_f32_e64 v37, -v35
	v_exp_f32_e32 v36, v35
	ds_write_b64 v105, v[36:37]

.LBB0_1045:
	s_or_b64 exec, exec, s[54:55]
	v_ashrrev_i32_e32 v33, 31, v32
	v_lshlrev_b64 v[36:37], 11, v[32:33]
	s_mov_b64 s[54:55], 0x2000
	v_lshl_add_u64 v[36:37], v[36:37], 0, s[54:55]
	v_lshlrev_b64 v[38:39], 11, v[36:37]
	v_lshlrev_b64 v[36:37], 12, v[36:37]
	v_lshlrev_b32_e32 v64, 8, v34
	v_lshl_add_u64 v[36:37], s[46:47], 0, v[36:37]
	v_lshlrev_b32_e32 v34, 9, v34
	v_mov_b32_e32 v35, v65
	v_lshl_add_u64 v[40:41], s[68:69], 0, v[38:39]
	v_lshl_add_u64 v[38:39], s[44:45], 0, v[38:39]
	v_lshl_add_u64 v[34:35], v[36:37], 0, v[34:35]
	v_lshl_add_u64 v[40:41], v[40:41], 0, v[64:65]
	v_lshl_add_u64 v[38:39], v[38:39], 0, v[64:65]
	v_lshl_add_u64 v[34:35], v[78:79], 1, v[34:35]
	v_mov_b32_e32 v73, v65
	v_mov_b32_e32 v75, v65
	v_lshl_add_u64 v[82:83], v[40:41], 0, v[72:73]
	v_lshl_add_u64 v[84:85], v[38:39], 0, v[72:73]
	v_lshl_add_u64 v[86:87], v[34:35], 0, v[74:75]
	s_mov_b64 s[54:55], 0x7c0000
	v_lshl_add_u64 v[36:37], v[82:83], 0, s[52:53]
	v_lshl_add_u64 v[38:39], v[84:85], 0, s[52:53]
	v_lshl_add_u64 v[34:35], v[86:87], 0, s[54:55]
	s_waitcnt lgkmcnt(0)
	s_barrier
	global_load_dword v67, v[36:37], off
	global_load_dword v71, v[36:37], off offset:2048
	global_load_dword v69, v[38:39], off
	global_load_dword v73, v[38:39], off offset:2048
	v_add_co_u32_e32 v40, vcc, s57, v36
	v_readlane_b32 s80, v241, 37
	s_nop 0
	v_addc_co_u32_e32 v41, vcc, 0, v37, vcc
	v_add_co_u32_e32 v42, vcc, s57, v38
	s_mov_b32 s54, 0
	s_nop 0
	v_addc_co_u32_e32 v43, vcc, 0, v39, vcc
	global_load_dword v75, v[40:41], off
	global_load_dword v136, v[40:41], off offset:2048
	global_load_dword v135, v[42:43], off
	global_load_dword v137, v[42:43], off offset:2048
	v_add_co_u32_e32 v40, vcc, s58, v36
	v_mov_b32_e32 v81, v80
	s_nop 0
	v_addc_co_u32_e32 v41, vcc, 0, v37, vcc
	v_add_co_u32_e32 v42, vcc, s58, v38
	v_lshl_or_b32 v147, v32, 11, v132
	s_nop 0
	v_addc_co_u32_e32 v43, vcc, 0, v39, vcc
	global_load_dword v138, v[40:41], off
	global_load_dword v140, v[40:41], off offset:2048
	global_load_dword v139, v[42:43], off
	global_load_dword v141, v[42:43], off offset:2048
	v_add_co_u32_e32 v40, vcc, s59, v36
	s_mov_b32 s50, 30
	s_nop 0
	v_addc_co_u32_e32 v41, vcc, 0, v37, vcc
	v_add_co_u32_e32 v42, vcc, s59, v38
	v_lshlrev_b32_e32 v88, 1, v64
	s_nop 0
	v_addc_co_u32_e32 v43, vcc, 0, v39, vcc
	global_load_dword v142, v[40:41], off
	global_load_dword v144, v[40:41], off offset:2048
	global_load_dword v143, v[42:43], off
	global_load_dword v145, v[42:43], off offset:2048
	v_add_co_u32_e32 v40, vcc, s56, v36
	v_mov_b32_e32 v148, v103
	s_nop 0
	v_addc_co_u32_e32 v41, vcc, 0, v37, vcc
	v_add_co_u32_e32 v42, vcc, s56, v38
	v_readlane_b32 s84, v241, 41
	s_nop 0
	v_addc_co_u32_e32 v43, vcc, 0, v39, vcc
	global_load_dword v146, v[40:41], off
	global_load_dword v150, v[40:41], off offset:2048
	global_load_dword v149, v[42:43], off
	global_load_dword v151, v[42:43], off offset:2048
	v_add_co_u32_e32 v40, vcc, s60, v36
	v_readlane_b32 s85, v241, 42
	s_nop 0
	v_addc_co_u32_e32 v41, vcc, 0, v37, vcc
	v_add_co_u32_e32 v42, vcc, s60, v38
	v_readlane_b32 s86, v241, 43
	s_nop 0
	v_addc_co_u32_e32 v43, vcc, 0, v39, vcc
	global_load_dword v152, v[40:41], off
	global_load_dword v154, v[40:41], off offset:2048
	global_load_dword v153, v[42:43], off
	global_load_dword v155, v[42:43], off offset:2048
	v_add_co_u32_e32 v40, vcc, s61, v36
	v_readlane_b32 s87, v241, 44
	s_nop 0
	v_addc_co_u32_e32 v41, vcc, 0, v37, vcc
	v_add_co_u32_e32 v42, vcc, s61, v38
	v_readlane_b32 s88, v241, 45
	s_nop 0
	v_addc_co_u32_e32 v43, vcc, 0, v39, vcc
	v_add_co_u32_e32 v36, vcc, s62, v36
	global_load_dword v156, v[40:41], off
	global_load_dword v158, v[40:41], off offset:2048
	global_load_dword v157, v[42:43], off
	global_load_dword v159, v[42:43], off offset:2048
	v_addc_co_u32_e32 v37, vcc, 0, v37, vcc
	v_add_co_u32_e32 v38, vcc, s62, v38
	v_readlane_b32 s89, v241, 46
	s_nop 0
	v_addc_co_u32_e32 v39, vcc, 0, v39, vcc
	global_load_dword v160, v[36:37], off
	global_load_dword v162, v[36:37], off offset:2048
	global_load_dword v161, v[38:39], off
	global_load_dword v163, v[38:39], off offset:2048
	global_load_dword v164, v[34:35], off
	v_add_co_u32_e32 v36, vcc, s57, v34
	v_readlane_b32 s92, v241, 49
	s_nop 0
	v_addc_co_u32_e32 v37, vcc, 0, v35, vcc
	v_add_co_u32_e32 v38, vcc, s58, v34
	v_readlane_b32 s93, v241, 50
	s_nop 0
	v_addc_co_u32_e32 v39, vcc, 0, v35, vcc
	v_add_co_u32_e32 v40, vcc, s59, v34
	v_readlane_b32 s94, v241, 51
	s_nop 0
	v_addc_co_u32_e32 v41, vcc, 0, v35, vcc
	v_add_co_u32_e32 v42, vcc, s56, v34
	v_readlane_b32 s95, v241, 52
	s_nop 0
	v_addc_co_u32_e32 v43, vcc, 0, v35, vcc
	v_add_co_u32_e32 v44, vcc, s60, v34
	v_readlane_b32 s81, v241, 38
	s_nop 0
	v_addc_co_u32_e32 v45, vcc, 0, v35, vcc
	v_add_co_u32_e32 v46, vcc, 0x6000, v34
	v_readlane_b32 s82, v241, 39
	s_nop 0
	v_addc_co_u32_e32 v47, vcc, 0, v35, vcc
	v_add_co_u32_e32 v34, vcc, 0x7000, v34
	v_readlane_b32 s83, v241, 40
	s_nop 0
	v_addc_co_u32_e32 v35, vcc, 0, v35, vcc
	global_load_dword v165, v[36:37], off
	global_load_dword v166, v[38:39], off
	global_load_dword v167, v[40:41], off
	global_load_dword v168, v[42:43], off
	global_load_dword v169, v[44:45], off
	global_load_dword v170, v[46:47], off
	global_load_dword v171, v[34:35], off
	v_readlane_b32 s90, v241, 47
	v_readlane_b32 s91, v241, 48
	s_waitcnt vmcnt(0)
	s_branch .LBB0_1047

.LBB0_1047:
	ds_read_b64 v[32:33], v102
	s_waitcnt vmcnt(4) lgkmcnt(0)
	v_lshlrev_b32_e32 v34, 16, v67
	v_and_b32_e32 v35, 0xffff0000, v67
	v_lshlrev_b32_e32 v36, 16, v69
	v_and_b32_e32 v37, 0xffff0000, v69
	v_pk_mul_f32 v[34:35], v[32:33], v[34:35] op_sel_hi:[0,1]
	v_cvt_pk_bf16_f32 v34, v34, v35
	v_pk_mul_f32 v[32:33], v[32:33], v[36:37] op_sel:[1,0]
	ds_write_b32 v106, v34
	v_cvt_pk_bf16_f32 v34, v32, v33
	ds_write_b32 v106, v34 offset:17408
	ds_read_b64 v[34:35], v107
	v_lshlrev_b32_e32 v36, 16, v71
	v_and_b32_e32 v37, 0xffff0000, v71
	v_lshlrev_b32_e32 v38, 16, v75
	v_and_b32_e32 v39, 0xffff0000, v75
	s_waitcnt lgkmcnt(0)
	v_pk_mul_f32 v[36:37], v[34:35], v[36:37] op_sel_hi:[0,1]
	v_cvt_pk_bf16_f32 v36, v36, v37
	ds_write_b32 v106, v36 offset:272
	v_lshlrev_b32_e32 v36, 16, v73
	v_and_b32_e32 v37, 0xffff0000, v73
	v_pk_mul_f32 v[34:35], v[34:35], v[36:37] op_sel:[1,0]
	v_lshlrev_b32_e32 v40, 16, v136
	v_cvt_pk_bf16_f32 v36, v34, v35
	ds_write_b32 v106, v36 offset:17680
	ds_read_b64 v[36:37], v108
	v_and_b32_e32 v41, 0xffff0000, v136
	v_lshlrev_b32_e32 v42, 16, v138
	v_and_b32_e32 v43, 0xffff0000, v138
	v_lshlrev_b32_e32 v44, 16, v140
	s_waitcnt lgkmcnt(0)
	v_pk_mul_f32 v[38:39], v[36:37], v[38:39] op_sel_hi:[0,1]
	v_cvt_pk_bf16_f32 v38, v38, v39
	ds_write_b32 v106, v38 offset:544
	v_lshlrev_b32_e32 v38, 16, v135
	v_and_b32_e32 v39, 0xffff0000, v135
	v_pk_mul_f32 v[38:39], v[36:37], v[38:39] op_sel:[1,0]
	v_and_b32_e32 v45, 0xffff0000, v140
	v_cvt_pk_bf16_f32 v36, v38, v39
	ds_write_b32 v106, v36 offset:17952
	ds_read_b64 v[36:37], v109
	v_lshlrev_b32_e32 v46, 16, v142
	v_and_b32_e32 v47, 0xffff0000, v142
	v_lshlrev_b32_e32 v48, 16, v144
	v_and_b32_e32 v49, 0xffff0000, v144
	s_waitcnt lgkmcnt(0)
	v_pk_mul_f32 v[40:41], v[36:37], v[40:41] op_sel_hi:[0,1]
	v_cvt_pk_bf16_f32 v40, v40, v41
	ds_write_b32 v106, v40 offset:816
	v_lshlrev_b32_e32 v40, 16, v137
	v_and_b32_e32 v41, 0xffff0000, v137
	v_pk_mul_f32 v[40:41], v[36:37], v[40:41] op_sel:[1,0]
	v_lshlrev_b32_e32 v50, 16, v146
	v_cvt_pk_bf16_f32 v36, v40, v41
	ds_write_b32 v106, v36 offset:18224
	ds_read_b64 v[36:37], v110
	v_and_b32_e32 v51, 0xffff0000, v146
	v_lshlrev_b32_e32 v52, 16, v150
	v_and_b32_e32 v53, 0xffff0000, v150
	v_lshlrev_b32_e32 v54, 16, v152
	s_waitcnt lgkmcnt(0)
	v_pk_mul_f32 v[42:43], v[36:37], v[42:43] op_sel_hi:[0,1]
	v_cvt_pk_bf16_f32 v42, v42, v43
	ds_write_b32 v106, v42 offset:1088
	v_lshlrev_b32_e32 v42, 16, v139
	v_and_b32_e32 v43, 0xffff0000, v139
	v_pk_mul_f32 v[42:43], v[36:37], v[42:43] op_sel:[1,0]
	v_and_b32_e32 v55, 0xffff0000, v152
	v_cvt_pk_bf16_f32 v36, v42, v43
	ds_write_b32 v106, v36 offset:18496
	ds_read_b64 v[36:37], v111
	v_lshlrev_b32_e32 v56, 16, v154
	v_and_b32_e32 v57, 0xffff0000, v154
	v_lshlrev_b32_e32 v58, 16, v156
	v_and_b32_e32 v59, 0xffff0000, v156
	s_waitcnt lgkmcnt(0)
	v_pk_mul_f32 v[44:45], v[36:37], v[44:45] op_sel_hi:[0,1]
	v_cvt_pk_bf16_f32 v44, v44, v45
	ds_write_b32 v106, v44 offset:1360
	v_lshlrev_b32_e32 v44, 16, v141
	v_and_b32_e32 v45, 0xffff0000, v141
	v_pk_mul_f32 v[44:45], v[36:37], v[44:45] op_sel:[1,0]
	v_lshlrev_b32_e32 v60, 16, v158
	v_cvt_pk_bf16_f32 v36, v44, v45
	ds_write_b32 v106, v36 offset:18768
	ds_read_b64 v[36:37], v112
	v_and_b32_e32 v61, 0xffff0000, v158
	v_lshlrev_b32_e32 v62, 16, v160
	v_and_b32_e32 v63, 0xffff0000, v160
	v_lshlrev_b32_e32 v90, 16, v162
	s_waitcnt lgkmcnt(0)
	v_pk_mul_f32 v[46:47], v[36:37], v[46:47] op_sel_hi:[0,1]
	v_cvt_pk_bf16_f32 v46, v46, v47
	ds_write_b32 v106, v46 offset:1632
	v_lshlrev_b32_e32 v46, 16, v143
	v_and_b32_e32 v47, 0xffff0000, v143
	v_pk_mul_f32 v[46:47], v[36:37], v[46:47] op_sel:[1,0]
	v_and_b32_e32 v91, 0xffff0000, v162
	v_cvt_pk_bf16_f32 v36, v46, v47
	ds_write_b32 v106, v36 offset:19040
	ds_read_b64 v[36:37], v113
	v_lshlrev_b32_e32 v77, 16, v169
	v_or_b32_sdwa v174, v168, v77 dst_sel:DWORD dst_unused:UNUSED_PAD src0_sel:WORD_0 src1_sel:DWORD
	s_cmp_gt_u32 s54, 30
	s_waitcnt lgkmcnt(0)
	v_pk_mul_f32 v[48:49], v[36:37], v[48:49] op_sel_hi:[0,1]
	v_cvt_pk_bf16_f32 v48, v48, v49
	ds_write_b32 v106, v48 offset:1904
	v_lshlrev_b32_e32 v48, 16, v145
	v_and_b32_e32 v49, 0xffff0000, v145
	v_pk_mul_f32 v[48:49], v[36:37], v[48:49] op_sel:[1,0]
	s_nop 0
	v_cvt_pk_bf16_f32 v36, v48, v49
	ds_write_b32 v106, v36 offset:19312
	ds_read_b64 v[36:37], v114
	s_waitcnt lgkmcnt(0)
	v_pk_mul_f32 v[50:51], v[36:37], v[50:51] op_sel_hi:[0,1]
	v_cvt_pk_bf16_f32 v50, v50, v51
	ds_write_b32 v106, v50 offset:2176
	v_lshlrev_b32_e32 v50, 16, v149
	v_and_b32_e32 v51, 0xffff0000, v149
	v_pk_mul_f32 v[50:51], v[36:37], v[50:51] op_sel:[1,0]
	s_nop 0
	v_cvt_pk_bf16_f32 v36, v50, v51
	ds_write_b32 v106, v36 offset:19584
	ds_read_b64 v[36:37], v115
	s_waitcnt lgkmcnt(0)
	v_pk_mul_f32 v[52:53], v[36:37], v[52:53] op_sel_hi:[0,1]
	v_cvt_pk_bf16_f32 v52, v52, v53
	ds_write_b32 v106, v52 offset:2448
	v_lshlrev_b32_e32 v52, 16, v151
	v_and_b32_e32 v53, 0xffff0000, v151
	v_pk_mul_f32 v[52:53], v[36:37], v[52:53] op_sel:[1,0]
	s_nop 0
	v_cvt_pk_bf16_f32 v36, v52, v53
	ds_write_b32 v106, v36 offset:19856
	ds_read_b64 v[36:37], v116
	s_waitcnt lgkmcnt(0)
	v_pk_mul_f32 v[54:55], v[36:37], v[54:55] op_sel_hi:[0,1]
	v_cvt_pk_bf16_f32 v54, v54, v55
	ds_write_b32 v106, v54 offset:2720
	v_lshlrev_b32_e32 v54, 16, v153
	v_and_b32_e32 v55, 0xffff0000, v153
	v_pk_mul_f32 v[54:55], v[36:37], v[54:55] op_sel:[1,0]
	s_nop 0
	v_cvt_pk_bf16_f32 v36, v54, v55
	ds_write_b32 v106, v36 offset:20128
	ds_read_b64 v[36:37], v117
	s_waitcnt lgkmcnt(0)
	v_pk_mul_f32 v[56:57], v[36:37], v[56:57] op_sel_hi:[0,1]
	v_cvt_pk_bf16_f32 v56, v56, v57
	ds_write_b32 v106, v56 offset:2992
	v_lshlrev_b32_e32 v56, 16, v155
	v_and_b32_e32 v57, 0xffff0000, v155
	v_pk_mul_f32 v[56:57], v[36:37], v[56:57] op_sel:[1,0]
	s_nop 0
	v_cvt_pk_bf16_f32 v36, v56, v57
	ds_write_b32 v106, v36 offset:20400
	ds_read_b64 v[36:37], v118
	s_waitcnt lgkmcnt(0)
	v_pk_mul_f32 v[58:59], v[36:37], v[58:59] op_sel_hi:[0,1]
	v_cvt_pk_bf16_f32 v58, v58, v59
	ds_write_b32 v106, v58 offset:3264
	v_lshlrev_b32_e32 v58, 16, v157
	v_and_b32_e32 v59, 0xffff0000, v157
	v_pk_mul_f32 v[58:59], v[36:37], v[58:59] op_sel:[1,0]
	s_nop 0
	v_cvt_pk_bf16_f32 v36, v58, v59
	ds_write_b32 v106, v36 offset:20672
	ds_read_b64 v[36:37], v119
	s_waitcnt lgkmcnt(0)
	v_pk_mul_f32 v[60:61], v[36:37], v[60:61] op_sel_hi:[0,1]
	v_cvt_pk_bf16_f32 v60, v60, v61
	ds_write_b32 v106, v60 offset:3536
	v_lshlrev_b32_e32 v60, 16, v159
	v_and_b32_e32 v61, 0xffff0000, v159
	v_pk_mul_f32 v[60:61], v[36:37], v[60:61] op_sel:[1,0]
	s_nop 0
	v_cvt_pk_bf16_f32 v36, v60, v61
	ds_write_b32 v106, v36 offset:20944
	ds_read_b64 v[36:37], v120
	s_waitcnt lgkmcnt(0)
	v_pk_mul_f32 v[62:63], v[36:37], v[62:63] op_sel_hi:[0,1]
	v_cvt_pk_bf16_f32 v62, v62, v63
	ds_write_b32 v106, v62 offset:3808
	v_lshlrev_b32_e32 v62, 16, v161
	v_and_b32_e32 v63, 0xffff0000, v161
	v_pk_mul_f32 v[62:63], v[36:37], v[62:63] op_sel:[1,0]
	s_nop 0
	v_cvt_pk_bf16_f32 v36, v62, v63
	ds_write_b32 v106, v36 offset:21216
	ds_read_b64 v[36:37], v121
	s_waitcnt lgkmcnt(0)
	v_pk_mul_f32 v[90:91], v[36:37], v[90:91] op_sel_hi:[0,1]
	v_cvt_pk_bf16_f32 v64, v90, v91
	v_lshlrev_b32_e32 v90, 16, v163
	v_and_b32_e32 v91, 0xffff0000, v163
	v_pk_mul_f32 v[90:91], v[36:37], v[90:91] op_sel:[1,0]
	ds_write_b32 v106, v64 offset:4080
	v_cvt_pk_bf16_f32 v36, v90, v91
	ds_write_b32 v106, v36 offset:21488
	v_lshlrev_b32_e32 v36, 16, v167
	v_lshlrev_b32_e32 v37, 16, v165
	v_lshlrev_b32_e32 v64, 16, v171
	v_or_b32_sdwa v173, v166, v36 dst_sel:DWORD dst_unused:UNUSED_PAD src0_sel:WORD_0 src1_sel:DWORD
	v_or_b32_sdwa v172, v164, v37 dst_sel:DWORD dst_unused:UNUSED_PAD src0_sel:WORD_0 src1_sel:DWORD
	v_or_b32_sdwa v175, v170, v64 dst_sel:DWORD dst_unused:UNUSED_PAD src0_sel:WORD_0 src1_sel:DWORD
	v_and_b32_e32 v36, 0xffff0000, v167
	v_and_b32_e32 v37, 0xffff0000, v165
	ds_write_b128 v122, v[172:175] offset:35840
	v_or_b32_sdwa v173, v166, v36 dst_sel:DWORD dst_unused:UNUSED_PAD src0_sel:WORD_1 src1_sel:DWORD
	v_or_b32_sdwa v172, v164, v37 dst_sel:DWORD dst_unused:UNUSED_PAD src0_sel:WORD_1 src1_sel:DWORD
	v_and_b32_e32 v36, 0xffff0000, v171
	v_and_b32_e32 v37, 0xffff0000, v169
	v_or_b32_sdwa v175, v170, v36 dst_sel:DWORD dst_unused:UNUSED_PAD src0_sel:WORD_1 src1_sel:DWORD
	v_or_b32_sdwa v174, v168, v37 dst_sel:DWORD dst_unused:UNUSED_PAD src0_sel:WORD_1 src1_sel:DWORD
	ds_write_b128 v122, v[172:175] offset:35984
	s_cbranch_scc1 .LBB0_1046
	s_lshl_b64 s[64:65], s[50:51], 17
	v_lshl_add_u64 v[160:161], v[82:83], 0, s[64:65]
	v_lshl_add_u64 v[162:163], v[84:85], 0, s[64:65]
	s_lshl_b64 s[64:65], s[50:51], 18
	v_lshl_add_u64 v[36:37], v[86:87], 0, s[64:65]
	global_load_dword v67, v[160:161], off
	global_load_dword v69, v[162:163], off
	global_load_dword v71, v[160:161], off offset:2048
	global_load_dword v73, v[162:163], off offset:2048
	v_add_co_u32_e32 v136, vcc, 0x1000, v160
	s_nop 1
	v_addc_co_u32_e32 v137, vcc, 0, v161, vcc
	v_add_co_u32_e32 v138, vcc, 0x1000, v162
	global_load_dword v75, v[136:137], off
	s_nop 0
	v_addc_co_u32_e32 v139, vcc, 0, v163, vcc
	v_add_co_u32_e32 v140, vcc, 0x2000, v160
	global_load_dword v135, v[138:139], off
	s_nop 0
	global_load_dword v136, v[136:137], off offset:2048
	s_nop 0
	global_load_dword v137, v[138:139], off offset:2048
	v_addc_co_u32_e32 v141, vcc, 0, v161, vcc
	v_add_co_u32_e32 v142, vcc, 0x2000, v162
	global_load_dword v138, v[140:141], off
	s_nop 0
	v_addc_co_u32_e32 v143, vcc, 0, v163, vcc
	v_add_co_u32_e32 v144, vcc, 0x3000, v160
	global_load_dword v139, v[142:143], off
	s_nop 0
	global_load_dword v140, v[140:141], off offset:2048
	s_nop 0
	global_load_dword v141, v[142:143], off offset:2048
	v_addc_co_u32_e32 v145, vcc, 0, v161, vcc
	v_add_co_u32_e32 v150, vcc, 0x3000, v162
	global_load_dword v142, v[144:145], off
	s_nop 0
	v_addc_co_u32_e32 v151, vcc, 0, v163, vcc
	global_load_dword v143, v[150:151], off
	s_nop 0
	global_load_dword v144, v[144:145], off offset:2048
	s_nop 0
	global_load_dword v145, v[150:151], off offset:2048
	v_add_co_u32_e32 v150, vcc, s56, v160
	s_nop 1
	v_addc_co_u32_e32 v151, vcc, 0, v161, vcc
	v_add_co_u32_e32 v152, vcc, s56, v162
	global_load_dword v146, v[150:151], off
	s_nop 0
	v_addc_co_u32_e32 v153, vcc, 0, v163, vcc
	v_add_co_u32_e32 v154, vcc, s60, v160
	global_load_dword v149, v[152:153], off
	s_nop 0
	global_load_dword v150, v[150:151], off offset:2048
	s_nop 0
	global_load_dword v151, v[152:153], off offset:2048
	v_addc_co_u32_e32 v155, vcc, 0, v161, vcc
	v_add_co_u32_e32 v156, vcc, s60, v162
	global_load_dword v152, v[154:155], off
	s_nop 0
	v_addc_co_u32_e32 v157, vcc, 0, v163, vcc
	v_add_co_u32_e32 v158, vcc, s61, v160
	global_load_dword v153, v[156:157], off
	s_nop 0
	global_load_dword v154, v[154:155], off offset:2048
	s_nop 0
	global_load_dword v155, v[156:157], off offset:2048
	v_addc_co_u32_e32 v159, vcc, 0, v161, vcc
	v_add_co_u32_e32 v164, vcc, s61, v162
	global_load_dword v156, v[158:159], off
	s_nop 0
	v_addc_co_u32_e32 v165, vcc, 0, v163, vcc
	global_load_dword v157, v[164:165], off
	s_nop 0
	global_load_dword v158, v[158:159], off offset:2048
	s_nop 0
	global_load_dword v159, v[164:165], off offset:2048
	v_add_co_u32_e32 v164, vcc, 0x7000, v160
	s_nop 1
	v_addc_co_u32_e32 v165, vcc, 0, v161, vcc
	v_add_co_u32_e32 v166, vcc, 0x7000, v162
	global_load_dword v160, v[164:165], off
	s_nop 0
	v_addc_co_u32_e32 v167, vcc, 0, v163, vcc
	global_load_dword v161, v[166:167], off
	global_load_dword v162, v[164:165], off offset:2048
	global_load_dword v163, v[166:167], off offset:2048
	s_nop 0
	global_load_dword v164, v[36:37], off
	v_add_co_u32_e32 v166, vcc, 0x1000, v36
	s_nop 1
	v_addc_co_u32_e32 v167, vcc, 0, v37, vcc
	global_load_dword v165, v[166:167], off
	v_add_co_u32_e32 v166, vcc, 0x2000, v36
	s_nop 1
	v_addc_co_u32_e32 v167, vcc, 0, v37, vcc
	v_add_co_u32_e32 v168, vcc, 0x3000, v36
	global_load_dword v166, v[166:167], off
	s_nop 0
	v_addc_co_u32_e32 v169, vcc, 0, v37, vcc
	global_load_dword v167, v[168:169], off
	v_add_co_u32_e32 v168, vcc, 0x4000, v36
	s_nop 1
	v_addc_co_u32_e32 v169, vcc, 0, v37, vcc
	v_add_co_u32_e32 v170, vcc, 0x5000, v36
	global_load_dword v168, v[168:169], off
	s_nop 0
	v_addc_co_u32_e32 v171, vcc, 0, v37, vcc
	global_load_dword v169, v[170:171], off
	v_add_co_u32_e32 v170, vcc, 0x6000, v36
	s_nop 1
	v_addc_co_u32_e32 v171, vcc, 0, v37, vcc
	v_add_co_u32_e32 v36, vcc, 0x7000, v36
	global_load_dword v170, v[170:171], off
	s_nop 0
	v_addc_co_u32_e32 v37, vcc, 0, v37, vcc
	global_load_dword v171, v[36:37], off
	s_branch .LBB0_1046

.LBB0_1053:
	v_ashrrev_i32_e32 v0, 31, v92
	v_lshrrev_b32_e32 v1, 30, v0
	v_add_u32_e32 v1, v92, v1
	v_ashrrev_i32_e32 v2, 2, v1
	v_lshrrev_b32_e32 v0, 27, v0
	v_and_b32_e32 v36, 7, v2
	v_add_u32_e32 v0, v92, v0
	v_ashrrev_i32_e32 v32, 5, v0
	v_lshlrev_b32_e32 v0, 2, v36
	global_load_dword v0, v0, s[84:85]
	v_and_b32_e32 v1, 0x3fffffc, v1
	v_sub_u32_e32 v1, v92, v1
	v_lshlrev_b32_e32 v34, 6, v1
	s_mov_b32 s52, 0x3fb8aa3b
	v_readlane_b32 s80, v241, 18
	v_readlane_b32 s88, v241, 26
	v_readlane_b32 s89, v241, 27
	v_ashrrev_i32_e32 v35, 31, v34
	s_waitcnt vmcnt(0)
	v_mov_b32_e32 v69, v65
	v_mov_b32_e32 v71, v65
	v_readlane_b32 s81, v241, 19
	v_readlane_b32 s82, v241, 20
	v_readlane_b32 s83, v241, 21
	v_readlane_b32 s84, v241, 22
	v_readlane_b32 s85, v241, 23
	v_readlane_b32 s86, v241, 24
	v_readlane_b32 s87, v241, 25
	v_readlane_b32 s90, v241, 28
	v_readlane_b32 s91, v241, 29
	v_readlane_b32 s92, v241, 30
	v_readlane_b32 s93, v241, 31
	v_readlane_b32 s94, v241, 32
	v_readlane_b32 s95, v241, 33
	s_waitcnt vmcnt(0)
	v_mul_f32_e32 v1, 0x3fb8aa3b, v0
	v_fma_f32 v2, v0, s52, -v1
	v_rndne_f32_e32 v3, v1
	v_fmac_f32_e32 v2, 0x32a5705f, v0
	v_sub_f32_e32 v1, v1, v3
	v_add_f32_e32 v1, v1, v2
	v_exp_f32_e32 v1, v1
	v_cvt_i32_f32_e32 v2, v3
	s_mov_b32 s52, 0xc2ce8ed0
	v_cmp_ngt_f32_e32 vcc, s52, v0
	s_mov_b32 s52, 0x42b17218
	v_ldexp_f32 v1, v1, v2
	v_cndmask_b32_e32 v1, 0, v1, vcc
	v_cmp_nlt_f32_e32 vcc, s52, v0
	s_mov_b32 s52, 0x3f2aaaab
	s_nop 0
	v_cndmask_b32_e32 v2, v124, v1, vcc
	v_sub_f32_e32 v3, 1.0, v2
	v_add_f32_e32 v0, -1.0, v3
	v_sub_f32_e32 v1, v0, v3
	v_add_f32_e32 v1, 1.0, v1
	v_sub_f32_e64 v0, -v2, v0
	v_add_f32_e32 v4, v0, v1
	v_frexp_mant_f32_e32 v0, v3
	v_cmp_gt_f32_e32 vcc, s52, v0
	v_cvt_f64_f32_e32 v[0:1], v3
	v_frexp_exp_i32_f64_e32 v0, v[0:1]
	v_subbrev_co_u32_e32 v0, vcc, 0, v0, vcc
	v_sub_u32_e32 v1, 0, v0
	v_ldexp_f32 v3, v3, v1
	v_ldexp_f32 v1, v4, v1
	v_add_f32_e32 v4, -1.0, v3
	v_add_f32_e32 v5, 1.0, v4
	v_sub_f32_e32 v5, v3, v5
	v_add_f32_e32 v5, v1, v5
	v_add_f32_e32 v6, v4, v5
	v_sub_f32_e32 v4, v6, v4
	v_sub_f32_e32 v4, v5, v4
	v_add_f32_e32 v5, 1.0, v3
	v_add_f32_e32 v7, -1.0, v5
	v_sub_f32_e32 v3, v3, v7
	v_add_f32_e32 v1, v1, v3
	v_add_f32_e32 v3, v5, v1
	v_sub_f32_e32 v5, v3, v5
	v_sub_f32_e32 v1, v1, v5
	v_rcp_f32_e32 v5, v3
	v_cvt_f32_i32_e32 v0, v0
	s_mov_b32 s52, 0x3f317218
	v_cmp_nlt_f32_e32 vcc, 1.0, v2
	v_mul_f32_e32 v7, v6, v5
	v_mul_f32_e32 v8, v3, v7
	v_fma_f32 v9, v7, v3, -v8
	v_fmac_f32_e32 v9, v7, v1
	v_add_f32_e32 v10, v8, v9
	v_sub_f32_e32 v11, v6, v10
	v_sub_f32_e32 v6, v6, v11
	v_sub_f32_e32 v8, v10, v8
	v_sub_f32_e32 v6, v6, v10
	v_add_f32_e32 v4, v4, v6
	v_sub_f32_e32 v6, v8, v9
	v_add_f32_e32 v4, v6, v4
	v_add_f32_e32 v6, v11, v4
	v_mul_f32_e32 v8, v5, v6
	v_mul_f32_e32 v9, v3, v8
	v_fma_f32 v3, v8, v3, -v9
	v_fmac_f32_e32 v3, v8, v1
	v_sub_f32_e32 v1, v11, v6
	v_add_f32_e32 v1, v4, v1
	v_add_f32_e32 v4, v9, v3
	v_sub_f32_e32 v10, v6, v4
	v_sub_f32_e32 v6, v6, v10
	v_sub_f32_e32 v9, v4, v9
	v_sub_f32_e32 v4, v6, v4
	v_add_f32_e32 v1, v1, v4
	v_sub_f32_e32 v3, v9, v3
	v_add_f32_e32 v1, v3, v1
	v_add_f32_e32 v3, v7, v8
	v_add_f32_e32 v1, v10, v1
	v_sub_f32_e32 v4, v3, v7
	v_mul_f32_e32 v1, v5, v1
	v_sub_f32_e32 v4, v8, v4
	v_add_f32_e32 v1, v4, v1
	v_mul_f32_e32 v7, 0x3f317218, v0
	v_add_f32_e32 v4, v3, v1
	v_fma_f32 v8, v0, s52, -v7
	v_mul_f32_e32 v5, v4, v4
	v_fmac_f32_e32 v8, 0xb102e308, v0
	v_sub_f32_e32 v0, v4, v3
	v_fmamk_f32 v6, v5, 0x3e9b6dac, v99
	v_sub_f32_e32 v0, v1, v0
	v_add_f32_e32 v1, v7, v8
	v_fmaak_f32 v6, v5, v6, 0x3f2aaada
	v_sub_f32_e32 v3, v1, v7
	v_ldexp_f32 v7, v4, 1
	v_mul_f32_e32 v4, v4, v5
	v_mul_f32_e32 v4, v4, v6
	v_add_f32_e32 v5, v7, v4
	v_sub_f32_e32 v6, v5, v7
	v_ldexp_f32 v0, v0, 1
	v_sub_f32_e32 v4, v4, v6
	v_add_f32_e32 v0, v0, v4
	v_add_f32_e32 v4, v5, v0
	v_sub_f32_e32 v5, v4, v5
	v_sub_f32_e32 v0, v0, v5
	v_add_f32_e32 v5, v1, v4
	v_sub_f32_e32 v6, v5, v1
	v_sub_f32_e32 v7, v5, v6
	v_sub_f32_e32 v3, v8, v3
	v_sub_f32_e32 v1, v1, v7
	v_sub_f32_e32 v4, v4, v6
	v_add_f32_e32 v1, v4, v1
	v_add_f32_e32 v4, v3, v0
	v_sub_f32_e32 v6, v4, v3
	v_sub_f32_e32 v7, v4, v6
	v_sub_f32_e32 v3, v3, v7
	v_sub_f32_e32 v0, v0, v6
	v_add_f32_e32 v1, v4, v1
	v_add_f32_e32 v0, v0, v3
	v_add_f32_e32 v3, v5, v1
	v_sub_f32_e32 v4, v3, v5
	v_sub_f32_e32 v1, v1, v4
	v_add_f32_e32 v0, v0, v1
	v_add_f32_e32 v0, v3, v0
	v_cndmask_b32_e32 v0, v125, v0, vcc
	v_cmp_neq_f32_e32 vcc, 1.0, v2
	s_mov_b32 s52, 0x33800000
	v_cmp_lt_f32_e64 s[52:53], |v2|, s52
	v_cndmask_b32_e32 v0, v126, v0, vcc
	s_nop 0
	v_cndmask_b32_e64 v0, v0, -v2, s[52:53]
	v_mul_f32_e32 v33, 0x3fb8aa3b, v0
	v_lshl_or_b32 v0, v32, 4, v36
	v_ashrrev_i32_e32 v1, 31, v0
	v_lshlrev_b64 v[0:1], 17, v[0:1]
	v_lshl_add_u64 v[0:1], s[88:89], 0, v[0:1]
	v_lshl_add_u64 v[0:1], v[34:35], 2, v[0:1]
	v_lshl_add_u64 v[0:1], v[0:1], 0, v[64:65]
	v_lshl_add_u64 v[0:1], v[0:1], 0, v[68:69]
	v_lshl_add_u64 v[28:29], v[0:1], 0, v[70:71]
	s_mov_b32 s52, 0x8000
	v_add_co_u32_e32 v8, vcc, s54, v28
	global_load_dword v4, v[28:29], off
	global_load_dword v5, v[28:29], off offset:1024
	global_load_dword v6, v[28:29], off offset:2048
	global_load_dword v7, v[28:29], off offset:3072
	v_addc_co_u32_e32 v9, vcc, 0, v29, vcc
	v_add_co_u32_e32 v12, vcc, s52, v28
	s_mov_b32 s52, 0xc000
	s_nop 0
	v_addc_co_u32_e32 v13, vcc, 0, v29, vcc
	v_add_co_u32_e32 v16, vcc, s52, v28
	s_mov_b32 s52, 0x10000
	s_nop 0
	v_addc_co_u32_e32 v17, vcc, 0, v29, vcc
	v_add_co_u32_e32 v20, vcc, s52, v28
	s_mov_b32 s52, 0x14000
	s_nop 0
	v_addc_co_u32_e32 v21, vcc, 0, v29, vcc
	v_add_co_u32_e32 v24, vcc, s52, v28
	global_load_dword v0, v[8:9], off
	global_load_dword v1, v[8:9], off offset:1024
	global_load_dword v2, v[8:9], off offset:2048
	global_load_dword v3, v[8:9], off offset:3072
	v_addc_co_u32_e32 v25, vcc, 0, v29, vcc
	v_add_co_u32_e32 v30, vcc, 0x18000, v28
	global_load_dword v8, v[12:13], off
	global_load_dword v9, v[12:13], off offset:1024
	global_load_dword v10, v[12:13], off offset:2048
	global_load_dword v11, v[12:13], off offset:3072
	v_addc_co_u32_e32 v31, vcc, 0, v29, vcc
	v_add_co_u32_e32 v38, vcc, 0x1c000, v28
	global_load_dword v12, v[16:17], off
	global_load_dword v13, v[16:17], off offset:1024
	global_load_dword v14, v[16:17], off offset:2048
	global_load_dword v15, v[16:17], off offset:3072
	v_addc_co_u32_e32 v39, vcc, 0, v29, vcc
	global_load_dword v16, v[20:21], off
	global_load_dword v17, v[20:21], off offset:1024
	global_load_dword v18, v[20:21], off offset:2048
	global_load_dword v19, v[20:21], off offset:3072
	s_nop 0
	global_load_dword v20, v[24:25], off
	global_load_dword v21, v[24:25], off offset:1024
	global_load_dword v22, v[24:25], off offset:2048
	global_load_dword v23, v[24:25], off offset:3072
	s_nop 0
	global_load_dword v24, v[30:31], off
	global_load_dword v25, v[30:31], off offset:1024
	global_load_dword v26, v[30:31], off offset:2048
	global_load_dword v27, v[30:31], off offset:3072
	global_load_dword v28, v[38:39], off
	global_load_dword v29, v[38:39], off offset:1024
	s_nop 0
	global_load_dword v30, v[38:39], off offset:2048
	global_load_dword v31, v[38:39], off offset:3072
	s_and_saveexec_b64 s[52:53], s[38:39]
	s_cbranch_execz .LBB0_1055
	v_mul_f32_e32 v37, v33, v88
	v_exp_f32_e64 v39, -v37
	v_exp_f32_e32 v38, v37
	ds_write_b64 v100, v[38:39]

.LBB0_1057:
	s_or_b64 exec, exec, s[52:53]
	v_ashrrev_i32_e32 v33, 31, v32
	v_lshlrev_b64 v[38:39], 11, v[32:33]
	s_mov_b64 s[52:53], 0x2000
	v_lshl_add_u64 v[38:39], v[38:39], 0, s[52:53]
	v_lshlrev_b64 v[40:41], 11, v[38:39]
	v_lshl_add_u64 v[42:43], s[68:69], 0, v[40:41]
	v_lshlrev_b32_e32 v44, 8, v36
	v_mov_b32_e32 v45, v65
	v_lshl_add_u64 v[40:41], s[42:43], 0, v[40:41]
	v_lshlrev_b64 v[38:39], 12, v[38:39]
	v_lshl_add_u64 v[42:43], v[42:43], 0, v[44:45]
	v_lshl_add_u64 v[40:41], v[40:41], 0, v[44:45]
	v_lshl_add_u64 v[38:39], s[44:45], 0, v[38:39]
	v_lshlrev_b32_e32 v44, 9, v36
	v_lshl_add_u64 v[38:39], v[38:39], 0, v[44:45]
	v_lshlrev_b64 v[34:35], 1, v[34:35]
	v_lshl_add_u64 v[38:39], v[38:39], 0, v[34:35]
	v_mov_b32_e32 v73, v65
	v_mov_b32_e32 v75, v65
	v_lshl_add_u64 v[42:43], v[42:43], 0, v[72:73]
	v_lshl_add_u64 v[40:41], v[40:41], 0, v[72:73]
	v_lshl_add_u64 v[38:39], v[38:39], 0, v[74:75]
	v_mov_b64_e32 v[44:45], v[40:41]
	v_mov_b64_e32 v[46:47], v[42:43]
	v_mov_b64_e32 v[48:49], v[38:39]
	s_waitcnt lgkmcnt(0)
	s_barrier
	global_load_dword v69, v[46:47], off
	global_load_dword v73, v[46:47], off offset:2048
	global_load_dword v71, v[44:45], off
	global_load_dword v75, v[44:45], off offset:2048
	v_add_co_u32_e32 v50, vcc, s55, v46
	v_lshlrev_b64 v[32:33], 23, v[32:33]
	s_nop 0
	v_addc_co_u32_e32 v51, vcc, 0, v47, vcc
	v_add_co_u32_e32 v52, vcc, s55, v44
	v_lshl_or_b32 v32, v36, 9, v32
	s_nop 0
	v_addc_co_u32_e32 v53, vcc, 0, v45, vcc
	global_load_dword v127, v[50:51], off
	global_load_dword v129, v[50:51], off offset:2048
	global_load_dword v128, v[52:53], off
	global_load_dword v130, v[52:53], off offset:2048
	v_add_co_u32_e32 v50, vcc, s56, v46
	v_lshl_add_u64 v[32:33], v[32:33], 0, v[34:35]
	s_nop 0
	v_addc_co_u32_e32 v51, vcc, 0, v47, vcc
	v_add_co_u32_e32 v52, vcc, s56, v44
	v_readlane_b32 s80, v241, 37
	s_nop 0
	v_addc_co_u32_e32 v53, vcc, 0, v45, vcc
	global_load_dword v131, v[50:51], off
	global_load_dword v133, v[50:51], off offset:2048
	global_load_dword v132, v[52:53], off
	global_load_dword v134, v[52:53], off offset:2048
	v_add_co_u32_e32 v50, vcc, s57, v46
	s_mov_b32 s52, 0
	s_nop 0
	v_addc_co_u32_e32 v51, vcc, 0, v47, vcc
	v_add_co_u32_e32 v52, vcc, s57, v44
	v_mov_b32_e32 v77, v76
	s_nop 0
	v_addc_co_u32_e32 v53, vcc, 0, v45, vcc
	global_load_dword v135, v[50:51], off
	global_load_dword v137, v[50:51], off offset:2048
	global_load_dword v136, v[52:53], off
	global_load_dword v138, v[52:53], off offset:2048
	v_add_co_u32_e32 v50, vcc, s54, v46
	v_lshl_add_u64 v[78:79], v[42:43], 0, s[48:49]
	s_nop 0
	v_addc_co_u32_e32 v51, vcc, 0, v47, vcc
	v_add_co_u32_e32 v52, vcc, s54, v44
	v_lshl_add_u64 v[80:81], v[40:41], 0, s[48:49]
	s_nop 0
	v_addc_co_u32_e32 v53, vcc, 0, v45, vcc
	global_load_dword v139, v[50:51], off
	global_load_dword v141, v[50:51], off offset:2048
	global_load_dword v140, v[52:53], off
	global_load_dword v142, v[52:53], off offset:2048
	v_add_co_u32_e32 v50, vcc, s58, v46
	v_lshl_add_u64 v[82:83], v[38:39], 0, s[50:51]
	s_nop 0
	v_addc_co_u32_e32 v51, vcc, 0, v47, vcc
	v_add_co_u32_e32 v52, vcc, s58, v44
	v_lshl_add_u64 v[84:85], v[66:67], 0, v[32:33]
	s_nop 0
	v_addc_co_u32_e32 v53, vcc, 0, v45, vcc
	global_load_dword v143, v[50:51], off
	global_load_dword v145, v[50:51], off offset:2048
	global_load_dword v144, v[52:53], off
	global_load_dword v146, v[52:53], off offset:2048
	v_add_co_u32_e32 v50, vcc, s59, v46
	v_readlane_b32 s84, v241, 41
	s_nop 0
	v_addc_co_u32_e32 v51, vcc, 0, v47, vcc
	v_add_co_u32_e32 v52, vcc, s59, v44
	v_readlane_b32 s85, v241, 42
	s_nop 0
	v_addc_co_u32_e32 v53, vcc, 0, v45, vcc
	v_add_co_u32_e32 v46, vcc, s60, v46
	global_load_dword v147, v[50:51], off
	global_load_dword v149, v[50:51], off offset:2048
	global_load_dword v148, v[52:53], off
	global_load_dword v150, v[52:53], off offset:2048
	v_addc_co_u32_e32 v47, vcc, 0, v47, vcc
	v_add_co_u32_e32 v44, vcc, s60, v44
	v_readlane_b32 s86, v241, 43
	s_nop 0
	v_addc_co_u32_e32 v45, vcc, 0, v45, vcc
	global_load_dword v151, v[46:47], off
	global_load_dword v153, v[46:47], off offset:2048
	global_load_dword v152, v[44:45], off
	global_load_dword v154, v[44:45], off offset:2048
	global_load_dword v155, v[48:49], off
	v_add_co_u32_e32 v44, vcc, s55, v48
	v_readlane_b32 s87, v241, 44
	s_nop 0
	v_addc_co_u32_e32 v45, vcc, 0, v49, vcc
	v_add_co_u32_e32 v46, vcc, s56, v48
	v_readlane_b32 s88, v241, 45
	s_nop 0
	v_addc_co_u32_e32 v47, vcc, 0, v49, vcc
	v_add_co_u32_e32 v50, vcc, s57, v48
	v_readlane_b32 s89, v241, 46
	s_nop 0
	v_addc_co_u32_e32 v51, vcc, 0, v49, vcc
	v_add_co_u32_e32 v52, vcc, s54, v48
	v_readlane_b32 s92, v241, 49
	s_nop 0
	v_addc_co_u32_e32 v53, vcc, 0, v49, vcc
	v_add_co_u32_e32 v54, vcc, s58, v48
	v_readlane_b32 s93, v241, 50
	s_nop 0
	v_addc_co_u32_e32 v55, vcc, 0, v49, vcc
	v_add_co_u32_e32 v56, vcc, s59, v48
	v_readlane_b32 s94, v241, 51
	s_nop 0
	v_addc_co_u32_e32 v57, vcc, 0, v49, vcc
	v_add_co_u32_e32 v48, vcc, 0x7000, v48
	v_readlane_b32 s95, v241, 52
	s_nop 0
	v_addc_co_u32_e32 v49, vcc, 0, v49, vcc
	global_load_dword v156, v[44:45], off
	global_load_dword v157, v[46:47], off
	global_load_dword v158, v[50:51], off
	global_load_dword v159, v[52:53], off
	global_load_dword v160, v[54:55], off
	global_load_dword v161, v[56:57], off
	global_load_dword v162, v[48:49], off
	v_readlane_b32 s81, v241, 38
	v_readlane_b32 s82, v241, 39
	v_readlane_b32 s83, v241, 40
	v_readlane_b32 s90, v241, 47
	v_readlane_b32 s91, v241, 48
	s_waitcnt vmcnt(0)
	s_branch .LBB0_1059

.LBB0_1059:
	ds_read_b64 v[32:33], v98
	s_waitcnt vmcnt(4) lgkmcnt(0)
	v_lshlrev_b32_e32 v34, 16, v69
	v_and_b32_e32 v35, 0xffff0000, v69
	v_lshlrev_b32_e32 v36, 16, v71
	v_and_b32_e32 v37, 0xffff0000, v71
	v_pk_mul_f32 v[34:35], v[32:33], v[34:35] op_sel_hi:[0,1]
	v_cvt_pk_bf16_f32 v34, v34, v35
	v_pk_mul_f32 v[32:33], v[32:33], v[36:37] op_sel:[1,0]
	ds_write_b32 v101, v34
	v_cvt_pk_bf16_f32 v34, v32, v33
	ds_write_b32 v101, v34 offset:17408
	ds_read_b64 v[34:35], v102
	v_lshlrev_b32_e32 v36, 16, v73
	v_and_b32_e32 v37, 0xffff0000, v73
	v_lshlrev_b32_e32 v38, 16, v127
	v_and_b32_e32 v39, 0xffff0000, v127
	s_waitcnt lgkmcnt(0)
	v_pk_mul_f32 v[36:37], v[34:35], v[36:37] op_sel_hi:[0,1]
	v_cvt_pk_bf16_f32 v36, v36, v37
	ds_write_b32 v101, v36 offset:272
	v_lshlrev_b32_e32 v36, 16, v75
	v_and_b32_e32 v37, 0xffff0000, v75
	v_pk_mul_f32 v[34:35], v[34:35], v[36:37] op_sel:[1,0]
	v_lshlrev_b32_e32 v40, 16, v129
	v_cvt_pk_bf16_f32 v36, v34, v35
	ds_write_b32 v101, v36 offset:17680
	ds_read_b64 v[36:37], v103
	v_and_b32_e32 v41, 0xffff0000, v129
	v_lshlrev_b32_e32 v42, 16, v131
	v_and_b32_e32 v43, 0xffff0000, v131
	v_lshlrev_b32_e32 v44, 16, v133
	s_waitcnt lgkmcnt(0)
	v_pk_mul_f32 v[38:39], v[36:37], v[38:39] op_sel_hi:[0,1]
	v_cvt_pk_bf16_f32 v38, v38, v39
	ds_write_b32 v101, v38 offset:544
	v_lshlrev_b32_e32 v38, 16, v128
	v_and_b32_e32 v39, 0xffff0000, v128
	v_pk_mul_f32 v[38:39], v[36:37], v[38:39] op_sel:[1,0]
	v_and_b32_e32 v45, 0xffff0000, v133
	v_cvt_pk_bf16_f32 v36, v38, v39
	ds_write_b32 v101, v36 offset:17952
	ds_read_b64 v[36:37], v104
	v_lshlrev_b32_e32 v46, 16, v135
	v_and_b32_e32 v47, 0xffff0000, v135
	v_lshlrev_b32_e32 v48, 16, v137
	v_and_b32_e32 v49, 0xffff0000, v137
	s_waitcnt lgkmcnt(0)
	v_pk_mul_f32 v[40:41], v[36:37], v[40:41] op_sel_hi:[0,1]
	v_cvt_pk_bf16_f32 v40, v40, v41
	ds_write_b32 v101, v40 offset:816
	v_lshlrev_b32_e32 v40, 16, v130
	v_and_b32_e32 v41, 0xffff0000, v130
	v_pk_mul_f32 v[40:41], v[36:37], v[40:41] op_sel:[1,0]
	v_lshlrev_b32_e32 v50, 16, v139
	v_cvt_pk_bf16_f32 v36, v40, v41
	ds_write_b32 v101, v36 offset:18224
	ds_read_b64 v[36:37], v105
	v_and_b32_e32 v51, 0xffff0000, v139
	v_lshlrev_b32_e32 v52, 16, v141
	v_and_b32_e32 v53, 0xffff0000, v141
	v_lshlrev_b32_e32 v54, 16, v143
	s_waitcnt lgkmcnt(0)
	v_pk_mul_f32 v[42:43], v[36:37], v[42:43] op_sel_hi:[0,1]
	v_cvt_pk_bf16_f32 v42, v42, v43
	ds_write_b32 v101, v42 offset:1088
	v_lshlrev_b32_e32 v42, 16, v132
	v_and_b32_e32 v43, 0xffff0000, v132
	v_pk_mul_f32 v[42:43], v[36:37], v[42:43] op_sel:[1,0]
	v_and_b32_e32 v55, 0xffff0000, v143
	v_cvt_pk_bf16_f32 v36, v42, v43
	ds_write_b32 v101, v36 offset:18496
	ds_read_b64 v[36:37], v106
	v_lshlrev_b32_e32 v56, 16, v145
	v_and_b32_e32 v57, 0xffff0000, v145
	v_lshlrev_b32_e32 v58, 16, v147
	v_and_b32_e32 v59, 0xffff0000, v147
	s_waitcnt lgkmcnt(0)
	v_pk_mul_f32 v[44:45], v[36:37], v[44:45] op_sel_hi:[0,1]
	v_cvt_pk_bf16_f32 v44, v44, v45
	ds_write_b32 v101, v44 offset:1360
	v_lshlrev_b32_e32 v44, 16, v134
	v_and_b32_e32 v45, 0xffff0000, v134
	v_pk_mul_f32 v[44:45], v[36:37], v[44:45] op_sel:[1,0]
	v_lshlrev_b32_e32 v60, 16, v149
	v_cvt_pk_bf16_f32 v36, v44, v45
	ds_write_b32 v101, v36 offset:18768
	ds_read_b64 v[36:37], v107
	v_and_b32_e32 v61, 0xffff0000, v149
	v_lshlrev_b32_e32 v62, 16, v151
	v_and_b32_e32 v63, 0xffff0000, v151
	v_lshlrev_b32_e32 v86, 16, v153
	s_waitcnt lgkmcnt(0)
	v_pk_mul_f32 v[46:47], v[36:37], v[46:47] op_sel_hi:[0,1]
	v_cvt_pk_bf16_f32 v46, v46, v47
	ds_write_b32 v101, v46 offset:1632
	v_lshlrev_b32_e32 v46, 16, v136
	v_and_b32_e32 v47, 0xffff0000, v136
	v_pk_mul_f32 v[46:47], v[36:37], v[46:47] op_sel:[1,0]
	v_and_b32_e32 v87, 0xffff0000, v153
	v_cvt_pk_bf16_f32 v36, v46, v47
	ds_write_b32 v101, v36 offset:19040
	ds_read_b64 v[36:37], v108
	v_lshlrev_b32_e32 v163, 16, v162
	v_lshlrev_b32_e32 v166, 16, v160
	v_or_b32_sdwa v167, v161, v163 dst_sel:DWORD dst_unused:UNUSED_PAD src0_sel:WORD_0 src1_sel:DWORD
	v_or_b32_sdwa v166, v159, v166 dst_sel:DWORD dst_unused:UNUSED_PAD src0_sel:WORD_0 src1_sel:DWORD
	s_waitcnt lgkmcnt(0)
	v_pk_mul_f32 v[48:49], v[36:37], v[48:49] op_sel_hi:[0,1]
	v_cvt_pk_bf16_f32 v48, v48, v49
	ds_write_b32 v101, v48 offset:1904
	v_lshlrev_b32_e32 v48, 16, v138
	v_and_b32_e32 v49, 0xffff0000, v138
	v_pk_mul_f32 v[48:49], v[36:37], v[48:49] op_sel:[1,0]
	s_cmp_gt_u32 s52, 30
	v_cvt_pk_bf16_f32 v36, v48, v49
	ds_write_b32 v101, v36 offset:19312
	ds_read_b64 v[36:37], v109
	s_waitcnt lgkmcnt(0)
	v_pk_mul_f32 v[50:51], v[36:37], v[50:51] op_sel_hi:[0,1]
	v_cvt_pk_bf16_f32 v50, v50, v51
	ds_write_b32 v101, v50 offset:2176
	v_lshlrev_b32_e32 v50, 16, v140
	v_and_b32_e32 v51, 0xffff0000, v140
	v_pk_mul_f32 v[50:51], v[36:37], v[50:51] op_sel:[1,0]
	s_nop 0
	v_cvt_pk_bf16_f32 v36, v50, v51
	ds_write_b32 v101, v36 offset:19584
	ds_read_b64 v[36:37], v110
	s_waitcnt lgkmcnt(0)
	v_pk_mul_f32 v[52:53], v[36:37], v[52:53] op_sel_hi:[0,1]
	v_cvt_pk_bf16_f32 v52, v52, v53
	ds_write_b32 v101, v52 offset:2448
	v_lshlrev_b32_e32 v52, 16, v142
	v_and_b32_e32 v53, 0xffff0000, v142
	v_pk_mul_f32 v[52:53], v[36:37], v[52:53] op_sel:[1,0]
	s_nop 0
	v_cvt_pk_bf16_f32 v36, v52, v53
	ds_write_b32 v101, v36 offset:19856
	ds_read_b64 v[36:37], v111
	s_waitcnt lgkmcnt(0)
	v_pk_mul_f32 v[54:55], v[36:37], v[54:55] op_sel_hi:[0,1]
	v_cvt_pk_bf16_f32 v54, v54, v55
	ds_write_b32 v101, v54 offset:2720
	v_lshlrev_b32_e32 v54, 16, v144
	v_and_b32_e32 v55, 0xffff0000, v144
	v_pk_mul_f32 v[54:55], v[36:37], v[54:55] op_sel:[1,0]
	s_nop 0
	v_cvt_pk_bf16_f32 v36, v54, v55
	ds_write_b32 v101, v36 offset:20128
	ds_read_b64 v[36:37], v112
	s_waitcnt lgkmcnt(0)
	v_pk_mul_f32 v[56:57], v[36:37], v[56:57] op_sel_hi:[0,1]
	v_cvt_pk_bf16_f32 v56, v56, v57
	ds_write_b32 v101, v56 offset:2992
	v_lshlrev_b32_e32 v56, 16, v146
	v_and_b32_e32 v57, 0xffff0000, v146
	v_pk_mul_f32 v[56:57], v[36:37], v[56:57] op_sel:[1,0]
	s_nop 0
	v_cvt_pk_bf16_f32 v36, v56, v57
	ds_write_b32 v101, v36 offset:20400
	ds_read_b64 v[36:37], v113
	s_waitcnt lgkmcnt(0)
	v_pk_mul_f32 v[58:59], v[36:37], v[58:59] op_sel_hi:[0,1]
	v_cvt_pk_bf16_f32 v58, v58, v59
	ds_write_b32 v101, v58 offset:3264
	v_lshlrev_b32_e32 v58, 16, v148
	v_and_b32_e32 v59, 0xffff0000, v148
	v_pk_mul_f32 v[58:59], v[36:37], v[58:59] op_sel:[1,0]
	s_nop 0
	v_cvt_pk_bf16_f32 v36, v58, v59
	ds_write_b32 v101, v36 offset:20672
	ds_read_b64 v[36:37], v114
	s_waitcnt lgkmcnt(0)
	v_pk_mul_f32 v[60:61], v[36:37], v[60:61] op_sel_hi:[0,1]
	v_cvt_pk_bf16_f32 v60, v60, v61
	ds_write_b32 v101, v60 offset:3536
	v_lshlrev_b32_e32 v60, 16, v150
	v_and_b32_e32 v61, 0xffff0000, v150
	v_pk_mul_f32 v[60:61], v[36:37], v[60:61] op_sel:[1,0]
	s_nop 0
	v_cvt_pk_bf16_f32 v36, v60, v61
	ds_write_b32 v101, v36 offset:20944
	ds_read_b64 v[36:37], v115
	s_waitcnt lgkmcnt(0)
	v_pk_mul_f32 v[62:63], v[36:37], v[62:63] op_sel_hi:[0,1]
	v_cvt_pk_bf16_f32 v62, v62, v63
	ds_write_b32 v101, v62 offset:3808
	v_lshlrev_b32_e32 v62, 16, v152
	v_and_b32_e32 v63, 0xffff0000, v152
	v_pk_mul_f32 v[62:63], v[36:37], v[62:63] op_sel:[1,0]
	s_nop 0
	v_cvt_pk_bf16_f32 v36, v62, v63
	ds_write_b32 v101, v36 offset:21216
	ds_read_b64 v[36:37], v116
	s_waitcnt lgkmcnt(0)
	v_pk_mul_f32 v[86:87], v[36:37], v[86:87] op_sel_hi:[0,1]
	v_cvt_pk_bf16_f32 v86, v86, v87
	ds_write_b32 v101, v86 offset:4080
	v_lshlrev_b32_e32 v86, 16, v154
	v_and_b32_e32 v87, 0xffff0000, v154
	v_pk_mul_f32 v[86:87], v[36:37], v[86:87] op_sel:[1,0]
	v_lshlrev_b32_e32 v37, 16, v156
	v_cvt_pk_bf16_f32 v36, v86, v87
	ds_write_b32 v101, v36 offset:21488
	v_lshlrev_b32_e32 v36, 16, v158
	v_or_b32_sdwa v165, v157, v36 dst_sel:DWORD dst_unused:UNUSED_PAD src0_sel:WORD_0 src1_sel:DWORD
	v_or_b32_sdwa v164, v155, v37 dst_sel:DWORD dst_unused:UNUSED_PAD src0_sel:WORD_0 src1_sel:DWORD
	v_and_b32_e32 v36, 0xffff0000, v158
	v_and_b32_e32 v37, 0xffff0000, v156
	ds_write_b128 v117, v[164:167] offset:35840
	v_or_b32_sdwa v165, v157, v36 dst_sel:DWORD dst_unused:UNUSED_PAD src0_sel:WORD_1 src1_sel:DWORD
	v_or_b32_sdwa v164, v155, v37 dst_sel:DWORD dst_unused:UNUSED_PAD src0_sel:WORD_1 src1_sel:DWORD
	v_and_b32_e32 v36, 0xffff0000, v162
	v_and_b32_e32 v37, 0xffff0000, v160
	v_or_b32_sdwa v167, v161, v36 dst_sel:DWORD dst_unused:UNUSED_PAD src0_sel:WORD_1 src1_sel:DWORD
	v_or_b32_sdwa v166, v159, v37 dst_sel:DWORD dst_unused:UNUSED_PAD src0_sel:WORD_1 src1_sel:DWORD
	ds_write_b128 v117, v[164:167] offset:35984
	s_cbranch_scc1 .LBB0_1058
	v_mov_b64_e32 v[152:153], v[78:79]
	v_mov_b64_e32 v[36:37], v[82:83]
	v_mov_b64_e32 v[154:155], v[80:81]
	global_load_dword v69, v[152:153], off
	global_load_dword v71, v[154:155], off
	global_load_dword v73, v[152:153], off offset:2048
	global_load_dword v75, v[154:155], off offset:2048
	v_add_co_u32_e32 v130, vcc, 0x1000, v152
	s_nop 1
	v_addc_co_u32_e32 v131, vcc, 0, v153, vcc
	v_add_co_u32_e32 v132, vcc, 0x1000, v154
	global_load_dword v127, v[130:131], off
	s_nop 0
	v_addc_co_u32_e32 v133, vcc, 0, v155, vcc
	v_add_co_u32_e32 v134, vcc, 0x2000, v152
	global_load_dword v128, v[132:133], off
	global_load_dword v129, v[130:131], off offset:2048
	s_nop 0
	global_load_dword v130, v[132:133], off offset:2048
	v_addc_co_u32_e32 v135, vcc, 0, v153, vcc
	v_add_co_u32_e32 v136, vcc, 0x2000, v154
	global_load_dword v131, v[134:135], off
	s_nop 0
	v_addc_co_u32_e32 v137, vcc, 0, v155, vcc
	v_add_co_u32_e32 v138, vcc, 0x3000, v152
	global_load_dword v132, v[136:137], off
	global_load_dword v133, v[134:135], off offset:2048
	s_nop 0
	global_load_dword v134, v[136:137], off offset:2048
	v_addc_co_u32_e32 v139, vcc, 0, v153, vcc
	v_add_co_u32_e32 v140, vcc, 0x3000, v154
	global_load_dword v135, v[138:139], off
	s_nop 0
	v_addc_co_u32_e32 v141, vcc, 0, v155, vcc
	v_add_co_u32_e32 v142, vcc, s54, v152
	global_load_dword v136, v[140:141], off
	global_load_dword v137, v[138:139], off offset:2048
	s_nop 0
	global_load_dword v138, v[140:141], off offset:2048
	v_addc_co_u32_e32 v143, vcc, 0, v153, vcc
	v_add_co_u32_e32 v144, vcc, s54, v154
	global_load_dword v139, v[142:143], off
	s_nop 0
	v_addc_co_u32_e32 v145, vcc, 0, v155, vcc
	v_add_co_u32_e32 v146, vcc, s58, v152
	global_load_dword v140, v[144:145], off
	global_load_dword v141, v[142:143], off offset:2048
	s_nop 0
	global_load_dword v142, v[144:145], off offset:2048
	v_addc_co_u32_e32 v147, vcc, 0, v153, vcc
	v_add_co_u32_e32 v148, vcc, s58, v154
	global_load_dword v143, v[146:147], off
	s_nop 0
	v_addc_co_u32_e32 v149, vcc, 0, v155, vcc
	v_add_co_u32_e32 v150, vcc, s59, v152
	global_load_dword v144, v[148:149], off
	global_load_dword v145, v[146:147], off offset:2048
	s_nop 0
	global_load_dword v146, v[148:149], off offset:2048
	v_addc_co_u32_e32 v151, vcc, 0, v153, vcc
	v_add_co_u32_e32 v156, vcc, s59, v154
	global_load_dword v147, v[150:151], off
	s_nop 0
	v_addc_co_u32_e32 v157, vcc, 0, v155, vcc
	global_load_dword v148, v[156:157], off
	global_load_dword v149, v[150:151], off offset:2048
	s_nop 0
	global_load_dword v150, v[156:157], off offset:2048
	v_add_co_u32_e32 v156, vcc, 0x7000, v152
	s_nop 1
	v_addc_co_u32_e32 v157, vcc, 0, v153, vcc
	v_add_co_u32_e32 v154, vcc, 0x7000, v154
	global_load_dword v151, v[156:157], off
	s_nop 0
	v_addc_co_u32_e32 v155, vcc, 0, v155, vcc
	global_load_dword v152, v[154:155], off
	global_load_dword v153, v[156:157], off offset:2048
	s_nop 0
	global_load_dword v154, v[154:155], off offset:2048
	s_nop 0
	global_load_dword v155, v[36:37], off
	v_add_co_u32_e32 v156, vcc, 0x1000, v36
	s_nop 1
	v_addc_co_u32_e32 v157, vcc, 0, v37, vcc
	v_add_co_u32_e32 v158, vcc, 0x2000, v36
	global_load_dword v156, v[156:157], off
	s_nop 0
	v_addc_co_u32_e32 v159, vcc, 0, v37, vcc
	global_load_dword v157, v[158:159], off
	v_add_co_u32_e32 v158, vcc, 0x3000, v36
	s_nop 1
	v_addc_co_u32_e32 v159, vcc, 0, v37, vcc
	v_add_co_u32_e32 v160, vcc, 0x4000, v36
	global_load_dword v158, v[158:159], off
	s_nop 0
	v_addc_co_u32_e32 v161, vcc, 0, v37, vcc
	global_load_dword v159, v[160:161], off
	v_add_co_u32_e32 v160, vcc, 0x5000, v36
	s_nop 1
	v_addc_co_u32_e32 v161, vcc, 0, v37, vcc
	v_add_co_u32_e32 v162, vcc, 0x6000, v36
	global_load_dword v160, v[160:161], off
	s_nop 0
	v_addc_co_u32_e32 v163, vcc, 0, v37, vcc
	v_add_co_u32_e32 v36, vcc, 0x7000, v36
	global_load_dword v161, v[162:163], off
	s_nop 0
	v_addc_co_u32_e32 v37, vcc, 0, v37, vcc
	global_load_dword v162, v[36:37], off
	s_branch .LBB0_1058

.LBB0_1077:
	v_add_u32_e32 v0, 0x100, v65
	v_cmp_lt_i32_e64 s[64:65], -1, v65
	v_readlane_b32 s4, v241, 37
	v_readlane_b32 s8, v241, 41
	v_cndmask_b32_e64 v0, v0, v65, s[64:65]
	v_ashrrev_i32_e32 v1, 31, v0
	v_lshrrev_b32_e32 v2, 30, v1
	v_add_u32_e32 v2, v0, v2
	s_waitcnt vmcnt(0)
	v_bfe_u32 v165, v2, 2, 3
	v_lshlrev_b32_e32 v68, 2, v165
	v_readlane_b32 s9, v241, 42
	v_and_b32_e32 v2, 0x3fffffc, v2
	v_lshrrev_b32_e32 v1, 27, v1
	v_sub_u32_e32 v2, v0, v2
	v_add_u32_e32 v0, v0, v1
	v_ashrrev_i32_e32 v94, 5, v0
	global_load_dword v32, v68, s[8:9]
	v_lshlrev_b32_e32 v82, 6, v2
	v_cmp_gt_i32_e64 s[66:67], 0, v65
	v_ashrrev_i32_e32 v83, 31, v82
	v_lshl_or_b32 v98, v94, 4, v165
	v_lshlrev_b32_e32 v84, 2, v66
	v_lshlrev_b32_e32 v80, 2, v64
	v_lshlrev_b32_e32 v78, 2, v70
	v_mov_b32_e32 v12, v69
	v_mov_b32_e32 v13, v69
	v_mov_b32_e32 v14, v69
	v_mov_b32_e32 v15, v69
	v_mov_b32_e32 v0, v69
	v_mov_b32_e32 v1, v69
	v_mov_b32_e32 v2, v69
	v_mov_b32_e32 v3, v69
	v_mov_b32_e32 v8, v69
	v_mov_b32_e32 v9, v69
	v_mov_b32_e32 v10, v69
	v_mov_b32_e32 v11, v69
	v_mov_b32_e32 v4, v69
	v_mov_b32_e32 v5, v69
	v_mov_b32_e32 v6, v69
	v_mov_b32_e32 v7, v69
	v_mov_b32_e32 v20, v69
	v_mov_b32_e32 v21, v69
	v_mov_b32_e32 v22, v69
	v_mov_b32_e32 v23, v69
	v_mov_b32_e32 v16, v69
	v_mov_b32_e32 v17, v69
	v_mov_b32_e32 v18, v69
	v_mov_b32_e32 v19, v69
	v_mov_b32_e32 v24, v69
	v_mov_b32_e32 v25, v69
	v_mov_b32_e32 v26, v69
	v_mov_b32_e32 v27, v69
	v_mov_b32_e32 v28, v69
	v_mov_b32_e32 v29, v69
	v_mov_b32_e32 v30, v69
	v_mov_b32_e32 v31, v69
	v_readlane_b32 s5, v241, 38
	v_readlane_b32 s6, v241, 39
	v_readlane_b32 s7, v241, 40
	v_readlane_b32 s10, v241, 43
	v_readlane_b32 s11, v241, 44
	v_readlane_b32 s12, v241, 45
	v_readlane_b32 s13, v241, 46
	v_readlane_b32 s14, v241, 47
	v_readlane_b32 s15, v241, 48
	v_readlane_b32 s16, v241, 49
	v_readlane_b32 s17, v241, 50
	v_readlane_b32 s18, v241, 51
	v_readlane_b32 s19, v241, 52
	s_and_saveexec_b64 s[82:83], s[66:67]
	s_cbranch_execz .LBB0_1079
	v_ashrrev_i32_e32 v99, 31, v98
	v_readlane_b32 s4, v241, 18
	v_lshlrev_b64 v[0:1], 17, v[98:99]
	v_readlane_b32 s12, v241, 26
	v_readlane_b32 s13, v241, 27
	v_mov_b32_e32 v85, v69
	v_mov_b32_e32 v81, v69
	v_lshl_add_u64 v[0:1], s[12:13], 0, v[0:1]
	v_lshl_add_u64 v[0:1], v[82:83], 2, v[0:1]
	v_lshl_add_u64 v[0:1], v[0:1], 0, v[84:85]
	v_lshl_add_u64 v[0:1], v[0:1], 0, v[80:81]
	v_mov_b32_e32 v79, v69
	v_lshl_add_u64 v[24:25], v[0:1], 0, v[78:79]
	s_mov_b32 s4, 0x8000
	v_add_co_u32_e32 v4, vcc, s33, v24
	v_readlane_b32 s5, v241, 19
	s_nop 0
	v_addc_co_u32_e32 v5, vcc, 0, v25, vcc
	global_load_dword v12, v[24:25], off
	global_load_dword v13, v[24:25], off offset:1024
	global_load_dword v14, v[24:25], off offset:2048
	global_load_dword v15, v[24:25], off offset:3072
	global_load_dword v0, v[4:5], off
	global_load_dword v1, v[4:5], off offset:1024
	global_load_dword v2, v[4:5], off offset:2048
	global_load_dword v3, v[4:5], off offset:3072
	v_add_co_u32_e32 v4, vcc, s4, v24
	s_mov_b32 s4, 0xc000
	s_nop 0
	v_addc_co_u32_e32 v5, vcc, 0, v25, vcc
	v_add_co_u32_e32 v16, vcc, s4, v24
	s_mov_b32 s4, 0x10000
	s_nop 0
	v_addc_co_u32_e32 v17, vcc, 0, v25, vcc
	global_load_dword v8, v[4:5], off
	global_load_dword v9, v[4:5], off offset:1024
	global_load_dword v10, v[4:5], off offset:2048
	global_load_dword v11, v[4:5], off offset:3072
	s_nop 0
	global_load_dword v4, v[16:17], off
	global_load_dword v5, v[16:17], off offset:1024
	global_load_dword v6, v[16:17], off offset:2048
	global_load_dword v7, v[16:17], off offset:3072
	v_add_co_u32_e32 v16, vcc, s4, v24
	s_mov_b32 s4, 0x14000
	s_nop 0
	v_addc_co_u32_e32 v17, vcc, 0, v25, vcc
	v_add_co_u32_e32 v26, vcc, s4, v24
	v_readlane_b32 s6, v241, 20
	s_nop 0
	v_addc_co_u32_e32 v27, vcc, 0, v25, vcc
	v_add_co_u32_e32 v28, vcc, 0x18000, v24
	global_load_dword v20, v[16:17], off
	global_load_dword v21, v[16:17], off offset:1024
	global_load_dword v22, v[16:17], off offset:2048
	global_load_dword v23, v[16:17], off offset:3072
	s_nop 0
	global_load_dword v16, v[26:27], off
	global_load_dword v17, v[26:27], off offset:1024
	global_load_dword v18, v[26:27], off offset:2048
	global_load_dword v19, v[26:27], off offset:3072
	v_addc_co_u32_e32 v29, vcc, 0, v25, vcc
	v_add_co_u32_e32 v34, vcc, 0x1c000, v24
	v_readlane_b32 s7, v241, 21
	s_nop 0
	v_addc_co_u32_e32 v35, vcc, 0, v25, vcc
	global_load_dword v24, v[28:29], off
	global_load_dword v25, v[28:29], off offset:1024
	global_load_dword v26, v[28:29], off offset:2048
	global_load_dword v27, v[28:29], off offset:3072
	s_nop 0
	global_load_dword v28, v[34:35], off
	global_load_dword v29, v[34:35], off offset:1024
	global_load_dword v30, v[34:35], off offset:2048
	global_load_dword v31, v[34:35], off offset:3072
	v_readlane_b32 s8, v241, 22
	v_readlane_b32 s9, v241, 23
	v_readlane_b32 s10, v241, 24
	v_readlane_b32 s11, v241, 25
	v_readlane_b32 s14, v241, 28
	v_readlane_b32 s15, v241, 29
	v_readlane_b32 s16, v241, 30
	v_readlane_b32 s17, v241, 31
	v_readlane_b32 s18, v241, 32
	v_readlane_b32 s19, v241, 33

.LBB0_1083:
	s_or_b64 exec, exec, s[82:83]
	v_ashrrev_i32_e32 v95, 31, v94
	v_readlane_b32 s4, v241, 37
	v_lshlrev_b64 v[32:33], 11, v[94:95]
	s_mov_b64 s[82:83], 0x2000
	v_readlane_b32 s5, v241, 38
	v_readlane_b32 s6, v241, 39
	v_readlane_b32 s7, v241, 40
	v_lshl_add_u64 v[32:33], v[32:33], 0, s[82:83]
	v_lshlrev_b64 v[34:35], 8, v[94:95]
	v_cndmask_b32_e64 v33, v33, v35, s[64:65]
	v_cndmask_b32_e64 v32, v32, v34, s[64:65]
	v_readlane_b32 s4, v241, 53
	v_lshlrev_b64 v[34:35], 11, v[32:33]
	v_readlane_b32 s5, v241, 54
	v_readlane_b32 s8, v241, 41
	v_readlane_b32 s9, v241, 42
	v_lshl_add_u64 v[36:37], s[4:5], 0, v[34:35]
	v_readlane_b32 s4, v241, 63
	v_readlane_b32 s5, v240, 0
	v_lshlrev_b32_e32 v96, 8, v165
	v_mov_b32_e32 v97, v69
	v_lshl_add_u64 v[34:35], s[4:5], 0, v[34:35]
	v_readlane_b32 s4, v240, 1
	v_lshlrev_b64 v[32:33], 12, v[32:33]
	v_readlane_b32 s5, v240, 2
	v_lshl_add_u64 v[108:109], s[8:9], 0, v[68:69]
	v_lshl_add_u64 v[102:103], v[34:35], 0, v[96:97]
	v_lshl_add_u64 v[34:35], s[4:5], 0, v[32:33]
	v_lshlrev_b32_e32 v68, 9, v165
	v_lshl_add_u64 v[100:101], v[36:37], 0, v[96:97]
	v_lshl_add_u64 v[34:35], v[34:35], 0, v[68:69]
	v_lshlrev_b64 v[36:37], 1, v[82:83]
	v_lshl_add_u64 v[104:105], v[34:35], 0, v[36:37]
	v_lshlrev_b32_e32 v106, 2, v72
	v_mov_b32_e32 v107, v69
	v_mov_b32_e32 v75, v69
	v_lshl_add_u64 v[86:87], v[100:101], 0, v[106:107]
	v_lshl_add_u64 v[88:89], v[102:103], 0, v[106:107]
	v_lshl_add_u64 v[90:91], v[104:105], 0, v[74:75]
	v_mov_b64_e32 v[34:35], v[86:87]
	v_mov_b64_e32 v[38:39], v[90:91]
	v_mov_b64_e32 v[40:41], v[88:89]
	s_movk_i32 s4, 0x1000
	s_waitcnt lgkmcnt(0)
	s_barrier
	s_movk_i32 s5, 0x2000
	v_add_co_u32_e32 v42, vcc, s4, v34
	global_load_dword v75, v[34:35], off
	global_load_dword v81, v[34:35], off offset:2048
	global_load_dword v79, v[40:41], off
	global_load_dword v85, v[40:41], off offset:2048
	v_addc_co_u32_e32 v43, vcc, 0, v35, vcc
	v_add_co_u32_e32 v44, vcc, s4, v40
	v_readlane_b32 s6, v241, 55
	s_nop 0
	v_addc_co_u32_e32 v45, vcc, 0, v41, vcc
	global_load_dword v95, v[42:43], off
	global_load_dword v99, v[42:43], off offset:2048
	global_load_dword v97, v[44:45], off
	global_load_dword v107, v[44:45], off offset:2048
	v_add_co_u32_e32 v42, vcc, s5, v34
	s_movk_i32 s6, 0x7000
	s_nop 0
	v_addc_co_u32_e32 v43, vcc, 0, v35, vcc
	v_add_co_u32_e32 v44, vcc, s5, v40
	v_mov_b32_e32 v77, v69
	s_nop 0
	v_addc_co_u32_e32 v45, vcc, 0, v41, vcc
	global_load_dword v166, v[42:43], off
	global_load_dword v168, v[42:43], off offset:2048
	global_load_dword v167, v[44:45], off
	global_load_dword v169, v[44:45], off offset:2048
	v_add_co_u32_e32 v42, vcc, s76, v34
	v_cndmask_b32_e64 v161, 32, 4, s[64:65]
	s_nop 0
	v_addc_co_u32_e32 v43, vcc, 0, v35, vcc
	v_add_co_u32_e32 v44, vcc, s76, v40
	s_mov_b32 s79, 0
	s_nop 0
	v_addc_co_u32_e32 v45, vcc, 0, v41, vcc
	global_load_dword v170, v[42:43], off
	global_load_dword v172, v[42:43], off offset:2048
	global_load_dword v171, v[44:45], off
	global_load_dword v173, v[44:45], off offset:2048
	v_add_co_u32_e32 v42, vcc, s33, v34
	v_mov_b32_e32 v111, v110
	s_nop 0
	v_addc_co_u32_e32 v43, vcc, 0, v35, vcc
	v_add_co_u32_e32 v44, vcc, s33, v40
	v_lshl_add_u64 v[112:113], v[90:91], 0, s[74:75]
	s_nop 0
	v_addc_co_u32_e32 v45, vcc, 0, v41, vcc
	global_load_dword v174, v[42:43], off
	global_load_dword v176, v[42:43], off offset:2048
	global_load_dword v175, v[44:45], off
	global_load_dword v177, v[44:45], off offset:2048
	v_add_co_u32_e32 v42, vcc, s77, v34
	v_lshl_add_u64 v[114:115], v[88:89], 0, s[80:81]
	s_nop 0
	v_addc_co_u32_e32 v43, vcc, 0, v35, vcc
	v_add_co_u32_e32 v44, vcc, s77, v40
	v_lshl_add_u64 v[116:117], v[86:87], 0, s[80:81]
	s_nop 0
	v_addc_co_u32_e32 v45, vcc, 0, v41, vcc
	global_load_dword v187, v[42:43], off
	global_load_dword v189, v[42:43], off offset:2048
	global_load_dword v188, v[44:45], off
	global_load_dword v190, v[44:45], off offset:2048
	v_add_co_u32_e32 v42, vcc, s78, v34
	s_mov_b64 s[82:83], 0
	s_nop 0
	v_addc_co_u32_e32 v43, vcc, 0, v35, vcc
	v_add_co_u32_e32 v44, vcc, s78, v40
	v_readlane_b32 s10, v241, 43
	s_nop 0
	v_addc_co_u32_e32 v45, vcc, 0, v41, vcc
	v_add_co_u32_e32 v34, vcc, s6, v34
	global_load_dword v191, v[42:43], off
	global_load_dword v193, v[42:43], off offset:2048
	global_load_dword v192, v[44:45], off
	global_load_dword v194, v[44:45], off offset:2048
	v_addc_co_u32_e32 v35, vcc, 0, v35, vcc
	v_add_co_u32_e32 v40, vcc, s6, v40
	v_readlane_b32 s11, v241, 44
	s_nop 0
	v_addc_co_u32_e32 v41, vcc, 0, v41, vcc
	global_load_dword v195, v[34:35], off
	global_load_dword v197, v[34:35], off offset:2048
	global_load_dword v196, v[40:41], off
	global_load_dword v198, v[40:41], off offset:2048
	global_load_dword v199, v[38:39], off
	v_add_co_u32_e32 v34, vcc, s4, v38
	v_readlane_b32 s12, v241, 45
	s_nop 0
	v_addc_co_u32_e32 v35, vcc, 0, v39, vcc
	v_add_co_u32_e32 v40, vcc, s5, v38
	v_readlane_b32 s4, v240, 3
	s_nop 0
	v_addc_co_u32_e32 v41, vcc, 0, v39, vcc
	v_add_co_u32_e32 v42, vcc, s76, v38
	v_readlane_b32 s5, v240, 4
	s_nop 0
	v_addc_co_u32_e32 v43, vcc, 0, v39, vcc
	v_add_co_u32_e32 v44, vcc, s33, v38
	v_lshl_add_u64 v[32:33], s[4:5], 0, v[32:33]
	s_nop 0
	v_addc_co_u32_e32 v45, vcc, 0, v39, vcc
	v_add_co_u32_e32 v46, vcc, s77, v38
	v_lshl_add_u64 v[32:33], v[32:33], 0, v[68:69]
	s_nop 0
	v_addc_co_u32_e32 v47, vcc, 0, v39, vcc
	v_add_co_u32_e32 v48, vcc, s78, v38
	v_lshl_add_u64 v[32:33], v[32:33], 0, v[36:37]
	s_nop 0
	v_addc_co_u32_e32 v49, vcc, 0, v39, vcc
	v_add_co_u32_e32 v38, vcc, 0x7000, v38
	v_lshl_add_u64 v[92:93], v[32:33], 0, v[76:77]
	s_nop 0
	v_addc_co_u32_e32 v39, vcc, 0, v39, vcc
	global_load_dword v200, v[34:35], off
	global_load_dword v201, v[40:41], off
	global_load_dword v202, v[42:43], off
	global_load_dword v203, v[44:45], off
	global_load_dword v204, v[46:47], off
	global_load_dword v205, v[48:49], off
	global_load_dword v206, v[38:39], off
	v_mov_b32_e32 v68, v122
	v_readlane_b32 s13, v241, 46
	v_readlane_b32 s14, v241, 47
	v_readlane_b32 s15, v241, 48
	v_readlane_b32 s16, v241, 49
	v_readlane_b32 s17, v241, 50
	v_readlane_b32 s18, v241, 51
	v_readlane_b32 s19, v241, 52
	v_readlane_b32 s7, v241, 56
	s_waitcnt vmcnt(0)
	s_branch .LBB0_1085

.LBB0_1085:
	ds_read_b64 v[32:33], v127
	s_waitcnt vmcnt(4) lgkmcnt(0)
	v_lshlrev_b32_e32 v34, 16, v75
	v_and_b32_e32 v35, 0xffff0000, v75
	v_lshlrev_b32_e32 v36, 16, v79
	v_and_b32_e32 v37, 0xffff0000, v79
	v_pk_mul_f32 v[34:35], v[32:33], v[34:35] op_sel_hi:[0,1]
	v_cvt_pk_bf16_f32 v34, v34, v35
	v_pk_mul_f32 v[32:33], v[32:33], v[36:37] op_sel:[1,0]
	ds_write_b32 v135, v34
	v_cvt_pk_bf16_f32 v34, v32, v33
	ds_write_b32 v135, v34 offset:17408
	ds_read_b64 v[34:35], v136
	v_lshlrev_b32_e32 v36, 16, v81
	v_and_b32_e32 v37, 0xffff0000, v81
	v_lshlrev_b32_e32 v38, 16, v95
	v_and_b32_e32 v39, 0xffff0000, v95
	s_waitcnt lgkmcnt(0)
	v_pk_mul_f32 v[36:37], v[34:35], v[36:37] op_sel_hi:[0,1]
	v_cvt_pk_bf16_f32 v36, v36, v37
	ds_write_b32 v135, v36 offset:272
	v_lshlrev_b32_e32 v36, 16, v85
	v_and_b32_e32 v37, 0xffff0000, v85
	v_pk_mul_f32 v[34:35], v[34:35], v[36:37] op_sel:[1,0]
	v_lshlrev_b32_e32 v40, 16, v99
	v_cvt_pk_bf16_f32 v36, v34, v35
	ds_write_b32 v135, v36 offset:17680
	ds_read_b64 v[36:37], v137
	v_and_b32_e32 v41, 0xffff0000, v99
	v_lshlrev_b32_e32 v42, 16, v166
	v_and_b32_e32 v43, 0xffff0000, v166
	v_lshlrev_b32_e32 v44, 16, v168
	s_waitcnt lgkmcnt(0)
	v_pk_mul_f32 v[38:39], v[36:37], v[38:39] op_sel_hi:[0,1]
	v_cvt_pk_bf16_f32 v38, v38, v39
	ds_write_b32 v135, v38 offset:544
	v_lshlrev_b32_e32 v38, 16, v97
	v_and_b32_e32 v39, 0xffff0000, v97
	v_pk_mul_f32 v[38:39], v[36:37], v[38:39] op_sel:[1,0]
	v_and_b32_e32 v45, 0xffff0000, v168
	v_cvt_pk_bf16_f32 v36, v38, v39
	ds_write_b32 v135, v36 offset:17952
	ds_read_b64 v[36:37], v138
	v_lshlrev_b32_e32 v46, 16, v170
	v_and_b32_e32 v47, 0xffff0000, v170
	v_lshlrev_b32_e32 v48, 16, v172
	v_and_b32_e32 v49, 0xffff0000, v172
	s_waitcnt lgkmcnt(0)
	v_pk_mul_f32 v[40:41], v[36:37], v[40:41] op_sel_hi:[0,1]
	v_cvt_pk_bf16_f32 v40, v40, v41
	ds_write_b32 v135, v40 offset:816
	v_lshlrev_b32_e32 v40, 16, v107
	v_and_b32_e32 v41, 0xffff0000, v107
	v_pk_mul_f32 v[40:41], v[36:37], v[40:41] op_sel:[1,0]
	v_lshlrev_b32_e32 v50, 16, v174
	v_cvt_pk_bf16_f32 v36, v40, v41
	ds_write_b32 v135, v36 offset:18224
	ds_read_b64 v[36:37], v139
	v_and_b32_e32 v51, 0xffff0000, v174
	v_lshlrev_b32_e32 v52, 16, v176
	v_and_b32_e32 v53, 0xffff0000, v176
	v_lshlrev_b32_e32 v54, 16, v187
	s_waitcnt lgkmcnt(0)
	v_pk_mul_f32 v[42:43], v[36:37], v[42:43] op_sel_hi:[0,1]
	v_cvt_pk_bf16_f32 v42, v42, v43
	ds_write_b32 v135, v42 offset:1088
	v_lshlrev_b32_e32 v42, 16, v167
	v_and_b32_e32 v43, 0xffff0000, v167
	v_pk_mul_f32 v[42:43], v[36:37], v[42:43] op_sel:[1,0]
	v_and_b32_e32 v55, 0xffff0000, v187
	v_cvt_pk_bf16_f32 v36, v42, v43
	ds_write_b32 v135, v36 offset:18496
	ds_read_b64 v[36:37], v140
	v_lshlrev_b32_e32 v56, 16, v189
	v_and_b32_e32 v57, 0xffff0000, v189
	v_lshlrev_b32_e32 v58, 16, v191
	v_and_b32_e32 v59, 0xffff0000, v191
	s_waitcnt lgkmcnt(0)
	v_pk_mul_f32 v[44:45], v[36:37], v[44:45] op_sel_hi:[0,1]
	v_cvt_pk_bf16_f32 v44, v44, v45
	ds_write_b32 v135, v44 offset:1360
	v_lshlrev_b32_e32 v44, 16, v169
	v_and_b32_e32 v45, 0xffff0000, v169
	v_pk_mul_f32 v[44:45], v[36:37], v[44:45] op_sel:[1,0]
	v_lshlrev_b32_e32 v60, 16, v193
	v_cvt_pk_bf16_f32 v36, v44, v45
	ds_write_b32 v141, v36 offset:17408
	ds_read_b64 v[36:37], v142
	v_and_b32_e32 v61, 0xffff0000, v193
	v_lshlrev_b32_e32 v62, 16, v195
	v_and_b32_e32 v63, 0xffff0000, v195
	v_lshlrev_b32_e32 v118, 16, v197
	s_waitcnt lgkmcnt(0)
	v_pk_mul_f32 v[46:47], v[36:37], v[46:47] op_sel_hi:[0,1]
	v_cvt_pk_bf16_f32 v46, v46, v47
	ds_write_b32 v141, v46 offset:272
	v_lshlrev_b32_e32 v46, 16, v171
	v_and_b32_e32 v47, 0xffff0000, v171
	v_pk_mul_f32 v[46:47], v[36:37], v[46:47] op_sel:[1,0]
	v_and_b32_e32 v119, 0xffff0000, v197
	v_cvt_pk_bf16_f32 v36, v46, v47
	ds_write_b32 v141, v36 offset:17680
	ds_read_b64 v[36:37], v143
	v_lshlrev_b32_e32 v162, 16, v204
	v_or_b32_sdwa v210, v203, v162 dst_sel:DWORD dst_unused:UNUSED_PAD src0_sel:WORD_0 src1_sel:DWORD
	s_add_i32 s79, s79, 1
	v_cmp_lt_u32_e32 vcc, s79, v161
	s_waitcnt lgkmcnt(0)
	v_pk_mul_f32 v[48:49], v[36:37], v[48:49] op_sel_hi:[0,1]
	v_cvt_pk_bf16_f32 v48, v48, v49
	ds_write_b32 v141, v48 offset:544
	v_lshlrev_b32_e32 v48, 16, v173
	v_and_b32_e32 v49, 0xffff0000, v173
	v_pk_mul_f32 v[48:49], v[36:37], v[48:49] op_sel:[1,0]
	s_nop 0
	v_cvt_pk_bf16_f32 v36, v48, v49
	ds_write_b32 v141, v36 offset:17952
	ds_read_b64 v[36:37], v144
	s_waitcnt lgkmcnt(0)
	v_pk_mul_f32 v[50:51], v[36:37], v[50:51] op_sel_hi:[0,1]
	v_cvt_pk_bf16_f32 v50, v50, v51
	ds_write_b32 v141, v50 offset:816
	v_lshlrev_b32_e32 v50, 16, v175
	v_and_b32_e32 v51, 0xffff0000, v175
	v_pk_mul_f32 v[50:51], v[36:37], v[50:51] op_sel:[1,0]
	s_nop 0
	v_cvt_pk_bf16_f32 v36, v50, v51
	ds_write_b32 v141, v36 offset:18224
	ds_read_b64 v[36:37], v145
	s_waitcnt lgkmcnt(0)
	v_pk_mul_f32 v[52:53], v[36:37], v[52:53] op_sel_hi:[0,1]
	v_cvt_pk_bf16_f32 v52, v52, v53
	ds_write_b32 v141, v52 offset:1088
	v_lshlrev_b32_e32 v52, 16, v177
	v_and_b32_e32 v53, 0xffff0000, v177
	v_pk_mul_f32 v[52:53], v[36:37], v[52:53] op_sel:[1,0]
	s_nop 0
	v_cvt_pk_bf16_f32 v36, v52, v53
	ds_write_b32 v141, v36 offset:18496
	ds_read_b64 v[36:37], v146
	s_waitcnt lgkmcnt(0)
	v_pk_mul_f32 v[54:55], v[36:37], v[54:55] op_sel_hi:[0,1]
	v_cvt_pk_bf16_f32 v54, v54, v55
	ds_write_b32 v141, v54 offset:1360
	v_lshlrev_b32_e32 v54, 16, v188
	v_and_b32_e32 v55, 0xffff0000, v188
	v_pk_mul_f32 v[54:55], v[36:37], v[54:55] op_sel:[1,0]
	s_nop 0
	v_cvt_pk_bf16_f32 v36, v54, v55
	ds_write_b32 v141, v36 offset:18768
	ds_read_b64 v[36:37], v147
	s_waitcnt lgkmcnt(0)
	v_pk_mul_f32 v[56:57], v[36:37], v[56:57] op_sel_hi:[0,1]
	v_cvt_pk_bf16_f32 v56, v56, v57
	ds_write_b32 v141, v56 offset:1632
	v_lshlrev_b32_e32 v56, 16, v190
	v_and_b32_e32 v57, 0xffff0000, v190
	v_pk_mul_f32 v[56:57], v[36:37], v[56:57] op_sel:[1,0]
	s_nop 0
	v_cvt_pk_bf16_f32 v36, v56, v57
	ds_write_b32 v141, v36 offset:19040
	ds_read_b64 v[36:37], v148
	s_waitcnt lgkmcnt(0)
	v_pk_mul_f32 v[58:59], v[36:37], v[58:59] op_sel_hi:[0,1]
	v_cvt_pk_bf16_f32 v58, v58, v59
	ds_write_b32 v141, v58 offset:1904
	v_lshlrev_b32_e32 v58, 16, v192
	v_and_b32_e32 v59, 0xffff0000, v192
	v_pk_mul_f32 v[58:59], v[36:37], v[58:59] op_sel:[1,0]
	s_nop 0
	v_cvt_pk_bf16_f32 v36, v58, v59
	ds_write_b32 v141, v36 offset:19312
	ds_read_b64 v[36:37], v149
	s_waitcnt lgkmcnt(0)
	v_pk_mul_f32 v[60:61], v[36:37], v[60:61] op_sel_hi:[0,1]
	v_cvt_pk_bf16_f32 v60, v60, v61
	ds_write_b32 v141, v60 offset:2176
	v_lshlrev_b32_e32 v60, 16, v194
	v_and_b32_e32 v61, 0xffff0000, v194
	v_pk_mul_f32 v[60:61], v[36:37], v[60:61] op_sel:[1,0]
	s_nop 0
	v_cvt_pk_bf16_f32 v36, v60, v61
	ds_write_b32 v141, v36 offset:19584
	ds_read_b64 v[36:37], v150
	s_waitcnt lgkmcnt(0)
	v_pk_mul_f32 v[62:63], v[36:37], v[62:63] op_sel_hi:[0,1]
	v_cvt_pk_bf16_f32 v62, v62, v63
	ds_write_b32 v141, v62 offset:2448
	v_lshlrev_b32_e32 v62, 16, v196
	v_and_b32_e32 v63, 0xffff0000, v196
	v_pk_mul_f32 v[62:63], v[36:37], v[62:63] op_sel:[1,0]
	s_nop 0
	v_cvt_pk_bf16_f32 v36, v62, v63
	ds_write_b32 v141, v36 offset:19856
	ds_read_b64 v[36:37], v151
	s_waitcnt lgkmcnt(0)
	v_pk_mul_f32 v[118:119], v[36:37], v[118:119] op_sel_hi:[0,1]
	v_cvt_pk_bf16_f32 v77, v118, v119
	v_lshlrev_b32_e32 v118, 16, v198
	v_and_b32_e32 v119, 0xffff0000, v198
	v_pk_mul_f32 v[118:119], v[36:37], v[118:119] op_sel:[1,0]
	ds_write_b32 v141, v77 offset:2720
	v_cvt_pk_bf16_f32 v36, v118, v119
	ds_write_b32 v141, v36 offset:20128
	v_lshlrev_b32_e32 v36, 16, v202
	v_lshlrev_b32_e32 v37, 16, v200
	v_lshlrev_b32_e32 v77, 16, v206
	v_or_b32_sdwa v209, v201, v36 dst_sel:DWORD dst_unused:UNUSED_PAD src0_sel:WORD_0 src1_sel:DWORD
	v_or_b32_sdwa v208, v199, v37 dst_sel:DWORD dst_unused:UNUSED_PAD src0_sel:WORD_0 src1_sel:DWORD
	v_or_b32_sdwa v211, v205, v77 dst_sel:DWORD dst_unused:UNUSED_PAD src0_sel:WORD_0 src1_sel:DWORD
	v_and_b32_e32 v36, 0xffff0000, v202
	v_and_b32_e32 v37, 0xffff0000, v200
	ds_write_b128 v152, v[208:211] offset:35840
	v_or_b32_sdwa v209, v201, v36 dst_sel:DWORD dst_unused:UNUSED_PAD src0_sel:WORD_1 src1_sel:DWORD
	v_or_b32_sdwa v208, v199, v37 dst_sel:DWORD dst_unused:UNUSED_PAD src0_sel:WORD_1 src1_sel:DWORD
	v_and_b32_e32 v36, 0xffff0000, v206
	v_and_b32_e32 v37, 0xffff0000, v204
	v_or_b32_sdwa v211, v205, v36 dst_sel:DWORD dst_unused:UNUSED_PAD src0_sel:WORD_1 src1_sel:DWORD
	v_or_b32_sdwa v210, v203, v37 dst_sel:DWORD dst_unused:UNUSED_PAD src0_sel:WORD_1 src1_sel:DWORD
	ds_write_b128 v152, v[208:211] offset:35984
	s_and_saveexec_b64 s[90:91], vcc
	s_cbranch_execz .LBB0_1084
	v_mov_b64_e32 v[162:163], v[114:115]
	v_mov_b64_e32 v[196:197], v[116:117]
	v_mov_b64_e32 v[36:37], v[112:113]
	global_load_dword v75, v[196:197], off
	global_load_dword v79, v[162:163], off
	global_load_dword v81, v[196:197], off offset:2048
	global_load_dword v85, v[162:163], off offset:2048
	v_add_co_u32_e32 v166, vcc, 0x1000, v196
	s_nop 1
	v_addc_co_u32_e32 v167, vcc, 0, v197, vcc
	v_add_co_u32_e32 v168, vcc, 0x1000, v162
	global_load_dword v95, v[166:167], off
	s_nop 0
	v_addc_co_u32_e32 v169, vcc, 0, v163, vcc
	global_load_dword v97, v[168:169], off
	global_load_dword v99, v[166:167], off offset:2048
	global_load_dword v107, v[168:169], off offset:2048
	v_add_co_u32_e32 v168, vcc, 0x2000, v196
	s_nop 1
	v_addc_co_u32_e32 v169, vcc, 0, v197, vcc
	v_add_co_u32_e32 v170, vcc, 0x2000, v162
	global_load_dword v166, v[168:169], off
	s_nop 0
	v_addc_co_u32_e32 v171, vcc, 0, v163, vcc
	v_add_co_u32_e32 v172, vcc, 0x3000, v196
	global_load_dword v167, v[170:171], off
	s_nop 0
	global_load_dword v168, v[168:169], off offset:2048
	s_nop 0
	global_load_dword v169, v[170:171], off offset:2048
	v_addc_co_u32_e32 v173, vcc, 0, v197, vcc
	v_add_co_u32_e32 v174, vcc, 0x3000, v162
	global_load_dword v170, v[172:173], off
	s_nop 0
	v_addc_co_u32_e32 v175, vcc, 0, v163, vcc
	v_add_co_u32_e32 v176, vcc, s33, v196
	global_load_dword v171, v[174:175], off
	s_nop 0
	global_load_dword v172, v[172:173], off offset:2048
	s_nop 0
	global_load_dword v173, v[174:175], off offset:2048
	v_addc_co_u32_e32 v177, vcc, 0, v197, vcc
	v_add_co_u32_e32 v188, vcc, s33, v162
	global_load_dword v174, v[176:177], off
	s_nop 0
	v_addc_co_u32_e32 v189, vcc, 0, v163, vcc
	v_add_co_u32_e32 v190, vcc, s77, v196
	global_load_dword v175, v[188:189], off
	s_nop 0
	global_load_dword v176, v[176:177], off offset:2048
	s_nop 0
	global_load_dword v177, v[188:189], off offset:2048
	v_addc_co_u32_e32 v191, vcc, 0, v197, vcc
	v_add_co_u32_e32 v192, vcc, s77, v162
	global_load_dword v187, v[190:191], off
	s_nop 0
	v_addc_co_u32_e32 v193, vcc, 0, v163, vcc
	v_add_co_u32_e32 v194, vcc, s78, v196
	global_load_dword v188, v[192:193], off
	global_load_dword v189, v[190:191], off offset:2048
	s_nop 0
	global_load_dword v190, v[192:193], off offset:2048
	v_addc_co_u32_e32 v195, vcc, 0, v197, vcc
	v_add_co_u32_e32 v198, vcc, s78, v162
	global_load_dword v191, v[194:195], off
	s_nop 0
	v_addc_co_u32_e32 v199, vcc, 0, v163, vcc
	global_load_dword v192, v[198:199], off
	global_load_dword v193, v[194:195], off offset:2048
	s_nop 0
	global_load_dword v194, v[198:199], off offset:2048
	v_add_co_u32_e32 v198, vcc, 0x7000, v196
	s_nop 1
	v_addc_co_u32_e32 v199, vcc, 0, v197, vcc
	v_add_co_u32_e32 v162, vcc, 0x7000, v162
	global_load_dword v195, v[198:199], off
	s_nop 0
	v_addc_co_u32_e32 v163, vcc, 0, v163, vcc
	global_load_dword v196, v[162:163], off
	global_load_dword v197, v[198:199], off offset:2048
	s_nop 0
	global_load_dword v198, v[162:163], off offset:2048
	global_load_dword v199, v[36:37], off
	v_add_co_u32_e32 v162, vcc, 0x1000, v36
	s_nop 1
	v_addc_co_u32_e32 v163, vcc, 0, v37, vcc
	global_load_dword v200, v[162:163], off
	v_add_co_u32_e32 v162, vcc, 0x2000, v36
	s_nop 1
	v_addc_co_u32_e32 v163, vcc, 0, v37, vcc
	global_load_dword v201, v[162:163], off
	v_add_co_u32_e32 v162, vcc, 0x3000, v36
	s_nop 1
	v_addc_co_u32_e32 v163, vcc, 0, v37, vcc
	global_load_dword v202, v[162:163], off
	v_add_co_u32_e32 v162, vcc, 0x4000, v36
	s_nop 1
	v_addc_co_u32_e32 v163, vcc, 0, v37, vcc
	global_load_dword v203, v[162:163], off
	v_add_co_u32_e32 v162, vcc, 0x5000, v36
	s_nop 1
	v_addc_co_u32_e32 v163, vcc, 0, v37, vcc
	global_load_dword v204, v[162:163], off
	v_add_co_u32_e32 v162, vcc, 0x6000, v36
	s_nop 1
	v_addc_co_u32_e32 v163, vcc, 0, v37, vcc
	v_add_co_u32_e32 v36, vcc, 0x7000, v36
	global_load_dword v205, v[162:163], off
	s_nop 0
	v_addc_co_u32_e32 v37, vcc, 0, v37, vcc
	global_load_dword v206, v[36:37], off
	s_branch .LBB0_1084
.LBB0_1087:
	s_or_b64 exec, exec, s[82:83]
	s_and_saveexec_b64 s[82:83], s[64:65]
	s_cbranch_execz .LBB0_1089
	s_waitcnt vmcnt(0)
	v_mov_b32_e32 v99, v69
	v_readlane_b32 s4, v240, 5
	v_lshlrev_b64 v[32:33], 17, v[98:99]
	v_readlane_b32 s5, v240, 6
	v_mov_b32_e32 v85, v69
	v_mov_b32_e32 v81, v69
	v_lshl_add_u64 v[32:33], s[4:5], 0, v[32:33]
	v_lshl_add_u64 v[32:33], v[82:83], 2, v[32:33]
	v_lshl_add_u64 v[32:33], v[32:33], 0, v[84:85]
	v_lshl_add_u64 v[32:33], v[32:33], 0, v[80:81]
	v_mov_b32_e32 v79, v69
	v_lshl_add_u64 v[32:33], v[32:33], 0, v[78:79]
	global_store_dword v[32:33], v12, off
	global_store_dword v[32:33], v13, off offset:1024
	global_store_dword v[32:33], v14, off offset:2048
	global_store_dword v[32:33], v15, off offset:3072
	v_add_co_u32_e32 v12, vcc, s33, v32
	s_mov_b32 s4, 0x8000
	s_nop 0
	v_addc_co_u32_e32 v13, vcc, 0, v33, vcc
	global_store_dword v[12:13], v0, off
	global_store_dword v[12:13], v1, off offset:1024
	global_store_dword v[12:13], v2, off offset:2048
	global_store_dword v[12:13], v3, off offset:3072
	v_add_co_u32_e32 v0, vcc, s4, v32
	s_mov_b32 s4, 0xc000
	s_nop 0
	v_addc_co_u32_e32 v1, vcc, 0, v33, vcc
	global_store_dword v[0:1], v8, off
	global_store_dword v[0:1], v9, off offset:1024
	global_store_dword v[0:1], v10, off offset:2048
	global_store_dword v[0:1], v11, off offset:3072
	v_add_co_u32_e32 v0, vcc, s4, v32
	s_mov_b32 s4, 0x10000
	s_nop 0
	v_addc_co_u32_e32 v1, vcc, 0, v33, vcc
	global_store_dword v[0:1], v4, off
	global_store_dword v[0:1], v5, off offset:1024
	global_store_dword v[0:1], v6, off offset:2048
	global_store_dword v[0:1], v7, off offset:3072
	v_add_co_u32_e32 v0, vcc, s4, v32
	s_mov_b32 s4, 0x14000
	s_nop 0
	v_addc_co_u32_e32 v1, vcc, 0, v33, vcc
	global_store_dword v[0:1], v20, off
	global_store_dword v[0:1], v21, off offset:1024
	global_store_dword v[0:1], v22, off offset:2048
	global_store_dword v[0:1], v23, off offset:3072
	v_add_co_u32_e32 v0, vcc, s4, v32
	s_nop 1
	v_addc_co_u32_e32 v1, vcc, 0, v33, vcc
	global_store_dword v[0:1], v16, off
	global_store_dword v[0:1], v17, off offset:1024
	global_store_dword v[0:1], v18, off offset:2048
	global_store_dword v[0:1], v19, off offset:3072
	v_add_co_u32_e32 v0, vcc, 0x18000, v32
	s_nop 1
	v_addc_co_u32_e32 v1, vcc, 0, v33, vcc
	global_store_dword v[0:1], v24, off
	global_store_dword v[0:1], v25, off offset:1024
	global_store_dword v[0:1], v26, off offset:2048
	global_store_dword v[0:1], v27, off offset:3072
	v_add_co_u32_e32 v0, vcc, 0x1c000, v32
	s_nop 1
	v_addc_co_u32_e32 v1, vcc, 0, v33, vcc
	global_store_dword v[0:1], v28, off
	global_store_dword v[0:1], v29, off offset:1024
	global_store_dword v[0:1], v30, off offset:2048
	global_store_dword v[0:1], v31, off offset:3072
.LBB0_1089:
	s_or_b64 exec, exec, s[82:83]
	global_load_dword v32, v[108:109], off offset:32
	v_mov_b32_e32 v8, 0
	v_lshlrev_b32_e32 v0, 4, v94
	v_or3_b32 v98, v0, v165, 8
	v_mov_b32_e32 v9, v8
	v_mov_b32_e32 v10, v8
	v_mov_b32_e32 v11, v8
	v_mov_b32_e32 v0, v8
	v_mov_b32_e32 v1, v8
	v_mov_b32_e32 v2, v8
	v_mov_b32_e32 v3, v8
	v_mov_b32_e32 v12, v8
	v_mov_b32_e32 v13, v8
	v_mov_b32_e32 v14, v8
	v_mov_b32_e32 v15, v8
	v_mov_b32_e32 v4, v8
	v_mov_b32_e32 v5, v8
	v_mov_b32_e32 v6, v8
	v_mov_b32_e32 v7, v8
	v_mov_b32_e32 v20, v8
	v_mov_b32_e32 v21, v8
	v_mov_b32_e32 v22, v8
	v_mov_b32_e32 v23, v8
	v_mov_b32_e32 v16, v8
	v_mov_b32_e32 v17, v8
	v_mov_b32_e32 v18, v8
	v_mov_b32_e32 v19, v8
	v_mov_b32_e32 v28, v8
	v_mov_b32_e32 v29, v8
	v_mov_b32_e32 v30, v8
	v_mov_b32_e32 v31, v8
	v_mov_b32_e32 v24, v8
	v_mov_b32_e32 v25, v8
	v_mov_b32_e32 v26, v8
	v_mov_b32_e32 v27, v8
	s_and_saveexec_b64 s[82:83], s[66:67]
	s_cbranch_execz .LBB0_1091
	s_waitcnt vmcnt(0)
	v_ashrrev_i32_e32 v99, 31, v98
	v_readlane_b32 s4, v241, 18
	v_lshlrev_b64 v[0:1], 17, v[98:99]
	v_readlane_b32 s12, v241, 26
	v_readlane_b32 s13, v241, 27
	v_mov_b32_e32 v85, v69
	v_mov_b32_e32 v81, v69
	v_lshl_add_u64 v[0:1], s[12:13], 0, v[0:1]
	v_lshl_add_u64 v[0:1], v[82:83], 2, v[0:1]
	v_lshl_add_u64 v[0:1], v[0:1], 0, v[84:85]
	v_lshl_add_u64 v[0:1], v[0:1], 0, v[80:81]
	v_mov_b32_e32 v79, v69
	v_lshl_add_u64 v[24:25], v[0:1], 0, v[78:79]
	s_mov_b32 s4, 0x8000
	v_add_co_u32_e32 v4, vcc, s33, v24
	v_readlane_b32 s5, v241, 19
	s_nop 0
	v_addc_co_u32_e32 v5, vcc, 0, v25, vcc
	global_load_dword v8, v[24:25], off
	global_load_dword v9, v[24:25], off offset:1024
	global_load_dword v10, v[24:25], off offset:2048
	global_load_dword v11, v[24:25], off offset:3072
	global_load_dword v0, v[4:5], off
	global_load_dword v1, v[4:5], off offset:1024
	global_load_dword v2, v[4:5], off offset:2048
	global_load_dword v3, v[4:5], off offset:3072
	v_add_co_u32_e32 v4, vcc, s4, v24
	s_mov_b32 s4, 0xc000
	s_nop 0
	v_addc_co_u32_e32 v5, vcc, 0, v25, vcc
	v_add_co_u32_e32 v16, vcc, s4, v24
	s_mov_b32 s4, 0x10000
	s_nop 0
	v_addc_co_u32_e32 v17, vcc, 0, v25, vcc
	global_load_dword v12, v[4:5], off
	global_load_dword v13, v[4:5], off offset:1024
	global_load_dword v14, v[4:5], off offset:2048
	global_load_dword v15, v[4:5], off offset:3072
	s_nop 0
	global_load_dword v4, v[16:17], off
	global_load_dword v5, v[16:17], off offset:1024
	global_load_dword v6, v[16:17], off offset:2048
	global_load_dword v7, v[16:17], off offset:3072
	v_add_co_u32_e32 v16, vcc, s4, v24
	s_mov_b32 s4, 0x14000
	s_nop 0
	v_addc_co_u32_e32 v17, vcc, 0, v25, vcc
	v_add_co_u32_e32 v26, vcc, s4, v24
	v_readlane_b32 s6, v241, 20
	s_nop 0
	v_addc_co_u32_e32 v27, vcc, 0, v25, vcc
	global_load_dword v20, v[16:17], off
	global_load_dword v21, v[16:17], off offset:1024
	global_load_dword v22, v[16:17], off offset:2048
	global_load_dword v23, v[16:17], off offset:3072
	s_nop 0
	global_load_dword v16, v[26:27], off
	global_load_dword v17, v[26:27], off offset:1024
	global_load_dword v18, v[26:27], off offset:2048
	global_load_dword v19, v[26:27], off offset:3072
	v_add_co_u32_e32 v26, vcc, 0x18000, v24
	v_readlane_b32 s7, v241, 21
	s_nop 0
	v_addc_co_u32_e32 v27, vcc, 0, v25, vcc
	v_add_co_u32_e32 v34, vcc, 0x1c000, v24
	v_readlane_b32 s8, v241, 22
	s_nop 0
	v_addc_co_u32_e32 v35, vcc, 0, v25, vcc
	global_load_dword v28, v[26:27], off
	global_load_dword v29, v[26:27], off offset:1024
	global_load_dword v30, v[26:27], off offset:2048
	global_load_dword v31, v[26:27], off offset:3072
	global_load_dword v24, v[34:35], off
	global_load_dword v25, v[34:35], off offset:1024
	s_nop 0
	global_load_dword v26, v[34:35], off offset:2048
	global_load_dword v27, v[34:35], off offset:3072
	v_readlane_b32 s9, v241, 23
	v_readlane_b32 s10, v241, 24
	v_readlane_b32 s11, v241, 25
	v_readlane_b32 s14, v241, 28
	v_readlane_b32 s15, v241, 29
	v_readlane_b32 s16, v241, 30
	v_readlane_b32 s17, v241, 31
	v_readlane_b32 s18, v241, 32
	v_readlane_b32 s19, v241, 33

.LBB0_1095:
	s_or_b64 exec, exec, s[82:83]
	v_add_u32_e32 v68, -1, v161
	v_lshlrev_b64 v[32:33], 17, v[68:69]
	v_lshl_add_u64 v[34:35], v[100:101], 0, v[32:33]
	v_mov_b32_e32 v107, v69
	v_lshl_add_u64 v[32:33], v[102:103], 0, v[32:33]
	v_lshl_add_u64 v[36:37], v[32:33], 0, v[106:107]
	v_lshlrev_b64 v[32:33], 18, v[68:69]
	v_lshl_add_u64 v[32:33], v[104:105], 0, v[32:33]
	v_mov_b32_e32 v75, v69
	v_lshl_add_u64 v[34:35], v[34:35], 0, v[106:107]
	v_lshl_add_u64 v[32:33], v[32:33], 0, v[74:75]
	s_movk_i32 s4, 0x1000
	s_waitcnt lgkmcnt(0)
	s_barrier
	s_movk_i32 s5, 0x2000
	v_add_co_u32_e32 v38, vcc, s4, v34
	global_load_dword v75, v[34:35], off
	global_load_dword v79, v[36:37], off
	global_load_dword v81, v[34:35], off offset:2048
	global_load_dword v85, v[36:37], off offset:2048
	v_addc_co_u32_e32 v39, vcc, 0, v35, vcc
	v_add_co_u32_e32 v40, vcc, s4, v36
	global_load_dword v95, v[38:39], off
	s_nop 0
	v_addc_co_u32_e32 v41, vcc, 0, v37, vcc
	global_load_dword v99, v[40:41], off
	global_load_dword v104, v[38:39], off offset:2048
	global_load_dword v105, v[40:41], off offset:2048
	v_add_co_u32_e32 v38, vcc, s5, v34
	s_movk_i32 s6, 0x7000
	s_nop 0
	v_addc_co_u32_e32 v39, vcc, 0, v35, vcc
	v_add_co_u32_e32 v40, vcc, s5, v36
	global_load_dword v106, v[38:39], off
	s_nop 0
	v_addc_co_u32_e32 v41, vcc, 0, v37, vcc
	global_load_dword v107, v[40:41], off
	global_load_dword v110, v[38:39], off offset:2048
	global_load_dword v111, v[40:41], off offset:2048
	v_add_co_u32_e32 v38, vcc, s76, v34
	s_movk_i32 s79, 0xffc0
	s_nop 0
	v_addc_co_u32_e32 v39, vcc, 0, v35, vcc
	v_add_co_u32_e32 v40, vcc, s76, v36
	global_load_dword v112, v[38:39], off
	s_nop 0
	v_addc_co_u32_e32 v41, vcc, 0, v37, vcc
	global_load_dword v113, v[40:41], off
	global_load_dword v114, v[38:39], off offset:2048
	global_load_dword v115, v[40:41], off offset:2048
	v_add_co_u32_e32 v38, vcc, s33, v34
	v_mov_b32_e32 v109, v108
	s_nop 0
	v_addc_co_u32_e32 v39, vcc, 0, v35, vcc
	v_add_co_u32_e32 v40, vcc, s33, v36
	global_load_dword v116, v[38:39], off
	s_nop 0
	v_addc_co_u32_e32 v41, vcc, 0, v37, vcc
	global_load_dword v117, v[40:41], off
	global_load_dword v119, v[38:39], off offset:2048
	global_load_dword v165, v[40:41], off offset:2048
	v_add_co_u32_e32 v38, vcc, s77, v34
	s_mov_b64 s[82:83], 0
	s_nop 0
	v_addc_co_u32_e32 v39, vcc, 0, v35, vcc
	v_add_co_u32_e32 v40, vcc, s77, v36
	global_load_dword v166, v[38:39], off
	s_nop 0
	v_addc_co_u32_e32 v41, vcc, 0, v37, vcc
	global_load_dword v167, v[40:41], off
	global_load_dword v170, v[38:39], off offset:2048
	global_load_dword v171, v[40:41], off offset:2048
	v_add_co_u32_e32 v38, vcc, s78, v34
	v_lshlrev_b32_e32 v96, 1, v96
	s_nop 0
	v_addc_co_u32_e32 v39, vcc, 0, v35, vcc
	v_add_co_u32_e32 v40, vcc, s78, v36
	global_load_dword v172, v[38:39], off
	s_nop 0
	v_addc_co_u32_e32 v41, vcc, 0, v37, vcc
	v_add_co_u32_e32 v34, vcc, s6, v34
	global_load_dword v173, v[40:41], off
	global_load_dword v174, v[38:39], off offset:2048
	global_load_dword v175, v[40:41], off offset:2048
	v_addc_co_u32_e32 v35, vcc, 0, v35, vcc
	v_add_co_u32_e32 v36, vcc, s6, v36
	global_load_dword v176, v[34:35], off
	s_nop 0
	v_addc_co_u32_e32 v37, vcc, 0, v37, vcc
	global_load_dword v177, v[36:37], off
	global_load_dword v187, v[34:35], off offset:2048
	global_load_dword v188, v[36:37], off offset:2048
	global_load_dword v189, v[32:33], off
	v_add_co_u32_e32 v34, vcc, s4, v32
	s_nop 1
	v_addc_co_u32_e32 v35, vcc, 0, v33, vcc
	global_load_dword v190, v[34:35], off
	v_add_co_u32_e32 v34, vcc, s5, v32
	s_nop 1
	v_addc_co_u32_e32 v35, vcc, 0, v33, vcc
	global_load_dword v191, v[34:35], off
	v_add_co_u32_e32 v34, vcc, s76, v32
	s_nop 1
	v_addc_co_u32_e32 v35, vcc, 0, v33, vcc
	global_load_dword v192, v[34:35], off
	v_add_co_u32_e32 v34, vcc, s33, v32
	s_nop 1
	v_addc_co_u32_e32 v35, vcc, 0, v33, vcc
	global_load_dword v193, v[34:35], off
	v_add_co_u32_e32 v34, vcc, s77, v32
	s_nop 1
	v_addc_co_u32_e32 v35, vcc, 0, v33, vcc
	global_load_dword v194, v[34:35], off
	v_add_co_u32_e32 v34, vcc, s78, v32
	s_nop 1
	v_addc_co_u32_e32 v35, vcc, 0, v33, vcc
	v_add_co_u32_e32 v32, vcc, 0x7000, v32
	global_load_dword v195, v[34:35], off
	s_nop 0
	v_addc_co_u32_e32 v33, vcc, 0, v33, vcc
	global_load_dword v196, v[32:33], off
	v_lshlrev_b32_e32 v33, 6, v161
	v_lshlrev_b32_e32 v32, 11, v94
	v_add_u32_e32 v100, v129, v33
	v_add_u32_e32 v94, -2, v161
	v_lshlrev_b32_e32 v168, 11, v100
	v_add3_u32 v169, v32, v33, s79
	s_mov_b32 s79, 1
	s_waitcnt vmcnt(0)
	s_branch .LBB0_1097

.LBB0_1097:
	ds_read_b64 v[32:33], v127
	s_waitcnt vmcnt(1) lgkmcnt(0)
	v_lshlrev_b32_e32 v34, 16, v75
	v_and_b32_e32 v35, 0xffff0000, v75
	v_lshlrev_b32_e32 v36, 16, v79
	v_and_b32_e32 v37, 0xffff0000, v79
	v_pk_mul_f32 v[34:35], v[32:33], v[34:35] op_sel_hi:[0,1]
	v_cvt_pk_bf16_f32 v34, v34, v35
	v_pk_mul_f32 v[32:33], v[32:33], v[36:37] op_sel:[1,0]
	ds_write_b32 v135, v34
	v_cvt_pk_bf16_f32 v34, v32, v33
	ds_write_b32 v135, v34 offset:17408
	ds_read_b64 v[34:35], v136
	v_lshlrev_b32_e32 v36, 16, v81
	v_and_b32_e32 v37, 0xffff0000, v81
	v_lshlrev_b32_e32 v38, 16, v95
	v_and_b32_e32 v39, 0xffff0000, v95
	s_waitcnt lgkmcnt(0)
	v_pk_mul_f32 v[36:37], v[34:35], v[36:37] op_sel_hi:[0,1]
	v_cvt_pk_bf16_f32 v36, v36, v37
	ds_write_b32 v135, v36 offset:272
	v_lshlrev_b32_e32 v36, 16, v85
	v_and_b32_e32 v37, 0xffff0000, v85
	v_pk_mul_f32 v[34:35], v[34:35], v[36:37] op_sel:[1,0]
	v_lshlrev_b32_e32 v40, 16, v104
	v_cvt_pk_bf16_f32 v36, v34, v35
	ds_write_b32 v135, v36 offset:17680
	ds_read_b64 v[36:37], v137
	v_and_b32_e32 v41, 0xffff0000, v104
	v_lshlrev_b32_e32 v42, 16, v106
	v_and_b32_e32 v43, 0xffff0000, v106
	v_lshlrev_b32_e32 v44, 16, v110
	s_waitcnt lgkmcnt(0)
	v_pk_mul_f32 v[38:39], v[36:37], v[38:39] op_sel_hi:[0,1]
	v_cvt_pk_bf16_f32 v38, v38, v39
	ds_write_b32 v135, v38 offset:544
	v_lshlrev_b32_e32 v38, 16, v99
	v_and_b32_e32 v39, 0xffff0000, v99
	v_pk_mul_f32 v[38:39], v[36:37], v[38:39] op_sel:[1,0]
	v_and_b32_e32 v45, 0xffff0000, v110
	v_cvt_pk_bf16_f32 v36, v38, v39
	ds_write_b32 v135, v36 offset:17952
	ds_read_b64 v[36:37], v138
	v_lshlrev_b32_e32 v46, 16, v112
	v_and_b32_e32 v47, 0xffff0000, v112
	v_lshlrev_b32_e32 v48, 16, v114
	v_and_b32_e32 v49, 0xffff0000, v114
	s_waitcnt lgkmcnt(0)
	v_pk_mul_f32 v[40:41], v[36:37], v[40:41] op_sel_hi:[0,1]
	v_cvt_pk_bf16_f32 v40, v40, v41
	ds_write_b32 v135, v40 offset:816
	v_lshlrev_b32_e32 v40, 16, v105
	v_and_b32_e32 v41, 0xffff0000, v105
	v_pk_mul_f32 v[40:41], v[36:37], v[40:41] op_sel:[1,0]
	v_lshlrev_b32_e32 v50, 16, v116
	v_cvt_pk_bf16_f32 v36, v40, v41
	ds_write_b32 v135, v36 offset:18224
	ds_read_b64 v[36:37], v139
	v_and_b32_e32 v51, 0xffff0000, v116
	v_lshlrev_b32_e32 v52, 16, v119
	v_and_b32_e32 v53, 0xffff0000, v119
	v_lshlrev_b32_e32 v54, 16, v166
	s_waitcnt lgkmcnt(0)
	v_pk_mul_f32 v[42:43], v[36:37], v[42:43] op_sel_hi:[0,1]
	v_cvt_pk_bf16_f32 v42, v42, v43
	ds_write_b32 v135, v42 offset:1088
	v_lshlrev_b32_e32 v42, 16, v107
	v_and_b32_e32 v43, 0xffff0000, v107
	v_pk_mul_f32 v[42:43], v[36:37], v[42:43] op_sel:[1,0]
	v_and_b32_e32 v55, 0xffff0000, v166
	v_cvt_pk_bf16_f32 v36, v42, v43
	ds_write_b32 v135, v36 offset:18496
	ds_read_b64 v[36:37], v140
	v_lshlrev_b32_e32 v56, 16, v170
	v_and_b32_e32 v57, 0xffff0000, v170
	v_lshlrev_b32_e32 v58, 16, v172
	v_and_b32_e32 v59, 0xffff0000, v172
	s_waitcnt lgkmcnt(0)
	v_pk_mul_f32 v[44:45], v[36:37], v[44:45] op_sel_hi:[0,1]
	v_cvt_pk_bf16_f32 v44, v44, v45
	ds_write_b32 v135, v44 offset:1360
	v_lshlrev_b32_e32 v44, 16, v111
	v_and_b32_e32 v45, 0xffff0000, v111
	v_pk_mul_f32 v[44:45], v[36:37], v[44:45] op_sel:[1,0]
	v_lshlrev_b32_e32 v60, 16, v174
	v_cvt_pk_bf16_f32 v36, v44, v45
	ds_write_b32 v141, v36 offset:17408
	ds_read_b64 v[36:37], v142
	v_and_b32_e32 v61, 0xffff0000, v174
	v_lshlrev_b32_e32 v62, 16, v176
	v_and_b32_e32 v63, 0xffff0000, v176
	v_lshlrev_b32_e32 v102, 16, v187
	s_waitcnt lgkmcnt(0)
	v_pk_mul_f32 v[46:47], v[36:37], v[46:47] op_sel_hi:[0,1]
	v_cvt_pk_bf16_f32 v46, v46, v47
	ds_write_b32 v141, v46 offset:272
	v_lshlrev_b32_e32 v46, 16, v113
	v_and_b32_e32 v47, 0xffff0000, v113
	v_pk_mul_f32 v[46:47], v[36:37], v[46:47] op_sel:[1,0]
	v_and_b32_e32 v103, 0xffff0000, v187
	v_cvt_pk_bf16_f32 v36, v46, v47
	ds_write_b32 v141, v36 offset:17680
	ds_read_b64 v[36:37], v143
	v_lshlrev_b32_e32 v77, 16, v194
	v_or_b32_sdwa v200, v193, v77 dst_sel:DWORD dst_unused:UNUSED_PAD src0_sel:WORD_0 src1_sel:DWORD
	v_cmp_lt_u32_e32 vcc, s79, v161
	s_waitcnt lgkmcnt(0)
	v_pk_mul_f32 v[48:49], v[36:37], v[48:49] op_sel_hi:[0,1]
	v_cvt_pk_bf16_f32 v48, v48, v49
	ds_write_b32 v141, v48 offset:544
	v_lshlrev_b32_e32 v48, 16, v115
	v_and_b32_e32 v49, 0xffff0000, v115
	v_pk_mul_f32 v[48:49], v[36:37], v[48:49] op_sel:[1,0]
	s_nop 0
	v_cvt_pk_bf16_f32 v36, v48, v49
	ds_write_b32 v141, v36 offset:17952
	ds_read_b64 v[36:37], v144
	s_waitcnt lgkmcnt(0)
	v_pk_mul_f32 v[50:51], v[36:37], v[50:51] op_sel_hi:[0,1]
	v_cvt_pk_bf16_f32 v50, v50, v51
	ds_write_b32 v141, v50 offset:816
	v_lshlrev_b32_e32 v50, 16, v117
	v_and_b32_e32 v51, 0xffff0000, v117
	v_pk_mul_f32 v[50:51], v[36:37], v[50:51] op_sel:[1,0]
	s_nop 0
	v_cvt_pk_bf16_f32 v36, v50, v51
	ds_write_b32 v141, v36 offset:18224
	ds_read_b64 v[36:37], v145
	s_waitcnt lgkmcnt(0)
	v_pk_mul_f32 v[52:53], v[36:37], v[52:53] op_sel_hi:[0,1]
	v_cvt_pk_bf16_f32 v52, v52, v53
	ds_write_b32 v141, v52 offset:1088
	v_lshlrev_b32_e32 v52, 16, v165
	v_and_b32_e32 v53, 0xffff0000, v165
	v_pk_mul_f32 v[52:53], v[36:37], v[52:53] op_sel:[1,0]
	s_nop 0
	v_cvt_pk_bf16_f32 v36, v52, v53
	ds_write_b32 v141, v36 offset:18496
	ds_read_b64 v[36:37], v146
	s_waitcnt lgkmcnt(0)
	v_pk_mul_f32 v[54:55], v[36:37], v[54:55] op_sel_hi:[0,1]
	v_cvt_pk_bf16_f32 v54, v54, v55
	ds_write_b32 v141, v54 offset:1360
	v_lshlrev_b32_e32 v54, 16, v167
	v_and_b32_e32 v55, 0xffff0000, v167
	v_pk_mul_f32 v[54:55], v[36:37], v[54:55] op_sel:[1,0]
	s_nop 0
	v_cvt_pk_bf16_f32 v36, v54, v55
	ds_write_b32 v141, v36 offset:18768
	ds_read_b64 v[36:37], v147
	s_waitcnt lgkmcnt(0)
	v_pk_mul_f32 v[56:57], v[36:37], v[56:57] op_sel_hi:[0,1]
	v_cvt_pk_bf16_f32 v56, v56, v57
	ds_write_b32 v141, v56 offset:1632
	v_lshlrev_b32_e32 v56, 16, v171
	v_and_b32_e32 v57, 0xffff0000, v171
	v_pk_mul_f32 v[56:57], v[36:37], v[56:57] op_sel:[1,0]
	s_nop 0
	v_cvt_pk_bf16_f32 v36, v56, v57
	ds_write_b32 v141, v36 offset:19040
	ds_read_b64 v[36:37], v148
	s_waitcnt lgkmcnt(0)
	v_pk_mul_f32 v[58:59], v[36:37], v[58:59] op_sel_hi:[0,1]
	v_cvt_pk_bf16_f32 v58, v58, v59
	ds_write_b32 v141, v58 offset:1904
	v_lshlrev_b32_e32 v58, 16, v173
	v_and_b32_e32 v59, 0xffff0000, v173
	v_pk_mul_f32 v[58:59], v[36:37], v[58:59] op_sel:[1,0]
	s_nop 0
	v_cvt_pk_bf16_f32 v36, v58, v59
	ds_write_b32 v141, v36 offset:19312
	ds_read_b64 v[36:37], v149
	s_waitcnt lgkmcnt(0)
	v_pk_mul_f32 v[60:61], v[36:37], v[60:61] op_sel_hi:[0,1]
	v_cvt_pk_bf16_f32 v60, v60, v61
	ds_write_b32 v141, v60 offset:2176
	v_lshlrev_b32_e32 v60, 16, v175
	v_and_b32_e32 v61, 0xffff0000, v175
	v_pk_mul_f32 v[60:61], v[36:37], v[60:61] op_sel:[1,0]
	s_nop 0
	v_cvt_pk_bf16_f32 v36, v60, v61
	ds_write_b32 v141, v36 offset:19584
	ds_read_b64 v[36:37], v150
	s_waitcnt lgkmcnt(0)
	v_pk_mul_f32 v[62:63], v[36:37], v[62:63] op_sel_hi:[0,1]
	v_cvt_pk_bf16_f32 v62, v62, v63
	ds_write_b32 v141, v62 offset:2448
	v_lshlrev_b32_e32 v62, 16, v177
	v_and_b32_e32 v63, 0xffff0000, v177
	v_pk_mul_f32 v[62:63], v[36:37], v[62:63] op_sel:[1,0]
	s_nop 0
	v_cvt_pk_bf16_f32 v36, v62, v63
	ds_write_b32 v141, v36 offset:19856
	ds_read_b64 v[36:37], v151
	s_waitcnt lgkmcnt(0)
	v_pk_mul_f32 v[102:103], v[36:37], v[102:103] op_sel_hi:[0,1]
	v_cvt_pk_bf16_f32 v68, v102, v103
	v_lshlrev_b32_e32 v102, 16, v188
	v_and_b32_e32 v103, 0xffff0000, v188
	v_pk_mul_f32 v[102:103], v[36:37], v[102:103] op_sel:[1,0]
	ds_write_b32 v141, v68 offset:2720
	v_cvt_pk_bf16_f32 v36, v102, v103
	ds_write_b32 v141, v36 offset:20128
	v_lshlrev_b32_e32 v36, 16, v192
	v_lshlrev_b32_e32 v37, 16, v190
	v_lshlrev_b32_e32 v68, 16, v196
	v_or_b32_sdwa v199, v191, v36 dst_sel:DWORD dst_unused:UNUSED_PAD src0_sel:WORD_0 src1_sel:DWORD
	v_or_b32_sdwa v198, v189, v37 dst_sel:DWORD dst_unused:UNUSED_PAD src0_sel:WORD_0 src1_sel:DWORD
	v_or_b32_sdwa v201, v195, v68 dst_sel:DWORD dst_unused:UNUSED_PAD src0_sel:WORD_0 src1_sel:DWORD
	v_and_b32_e32 v36, 0xffff0000, v192
	v_and_b32_e32 v37, 0xffff0000, v190
	ds_write_b128 v152, v[198:201] offset:35840
	v_or_b32_sdwa v199, v191, v36 dst_sel:DWORD dst_unused:UNUSED_PAD src0_sel:WORD_1 src1_sel:DWORD
	v_or_b32_sdwa v198, v189, v37 dst_sel:DWORD dst_unused:UNUSED_PAD src0_sel:WORD_1 src1_sel:DWORD
	v_and_b32_e32 v36, 0xffff0000, v196
	v_and_b32_e32 v37, 0xffff0000, v194
	v_or_b32_sdwa v201, v195, v36 dst_sel:DWORD dst_unused:UNUSED_PAD src0_sel:WORD_1 src1_sel:DWORD
	v_or_b32_sdwa v200, v193, v37 dst_sel:DWORD dst_unused:UNUSED_PAD src0_sel:WORD_1 src1_sel:DWORD
	ds_write_b128 v152, v[198:201] offset:35984
	s_and_saveexec_b64 s[90:91], vcc
	s_cbranch_execz .LBB0_1099
	v_ashrrev_i32_e32 v95, 31, v94
	v_lshlrev_b64 v[36:37], 17, v[94:95]
	v_lshl_add_u64 v[176:177], v[86:87], 0, v[36:37]
	v_lshl_add_u64 v[188:189], v[88:89], 0, v[36:37]
	v_lshlrev_b64 v[36:37], 18, v[94:95]
	v_lshl_add_u64 v[36:37], v[90:91], 0, v[36:37]
	global_load_dword v75, v[176:177], off
	global_load_dword v79, v[188:189], off
	global_load_dword v81, v[176:177], off offset:2048
	global_load_dword v85, v[188:189], off offset:2048
	v_add_co_u32_e32 v104, vcc, 0x1000, v176
	s_nop 1
	v_addc_co_u32_e32 v105, vcc, 0, v177, vcc
	v_add_co_u32_e32 v106, vcc, 0x1000, v188
	global_load_dword v95, v[104:105], off
	s_nop 0
	v_addc_co_u32_e32 v107, vcc, 0, v189, vcc
	v_add_co_u32_e32 v110, vcc, 0x2000, v176
	global_load_dword v99, v[106:107], off
	s_nop 0
	global_load_dword v104, v[104:105], off offset:2048
	s_nop 0
	global_load_dword v105, v[106:107], off offset:2048
	v_addc_co_u32_e32 v111, vcc, 0, v177, vcc
	v_add_co_u32_e32 v112, vcc, 0x2000, v188
	global_load_dword v106, v[110:111], off
	s_nop 0
	v_addc_co_u32_e32 v113, vcc, 0, v189, vcc
	v_add_co_u32_e32 v114, vcc, 0x3000, v176
	global_load_dword v107, v[112:113], off
	s_nop 0
	global_load_dword v110, v[110:111], off offset:2048
	s_nop 0
	global_load_dword v111, v[112:113], off offset:2048
	v_addc_co_u32_e32 v115, vcc, 0, v177, vcc
	v_add_co_u32_e32 v116, vcc, 0x3000, v188
	global_load_dword v112, v[114:115], off
	s_nop 0
	v_addc_co_u32_e32 v117, vcc, 0, v189, vcc
	v_add_co_u32_e32 v166, vcc, s33, v176
	global_load_dword v113, v[116:117], off
	s_nop 0
	global_load_dword v114, v[114:115], off offset:2048
	s_nop 0
	global_load_dword v115, v[116:117], off offset:2048
	v_addc_co_u32_e32 v167, vcc, 0, v177, vcc
	v_add_co_u32_e32 v170, vcc, s33, v188
	global_load_dword v116, v[166:167], off
	s_nop 0
	v_addc_co_u32_e32 v171, vcc, 0, v189, vcc
	global_load_dword v117, v[170:171], off
	global_load_dword v119, v[166:167], off offset:2048
	global_load_dword v165, v[170:171], off offset:2048
	v_add_co_u32_e32 v170, vcc, s77, v176
	s_nop 1
	v_addc_co_u32_e32 v171, vcc, 0, v177, vcc
	v_add_co_u32_e32 v172, vcc, s77, v188
	global_load_dword v166, v[170:171], off
	s_nop 0
	v_addc_co_u32_e32 v173, vcc, 0, v189, vcc
	v_add_co_u32_e32 v174, vcc, s78, v176
	global_load_dword v167, v[172:173], off
	s_nop 0
	global_load_dword v170, v[170:171], off offset:2048
	s_nop 0
	global_load_dword v171, v[172:173], off offset:2048
	v_addc_co_u32_e32 v175, vcc, 0, v177, vcc
	v_add_co_u32_e32 v190, vcc, s78, v188
	global_load_dword v172, v[174:175], off
	s_nop 0
	v_addc_co_u32_e32 v191, vcc, 0, v189, vcc
	global_load_dword v173, v[190:191], off
	s_nop 0
	global_load_dword v174, v[174:175], off offset:2048
	s_nop 0
	global_load_dword v175, v[190:191], off offset:2048
	v_add_co_u32_e32 v190, vcc, 0x7000, v176
	s_nop 1
	v_addc_co_u32_e32 v191, vcc, 0, v177, vcc
	v_add_co_u32_e32 v188, vcc, 0x7000, v188
	global_load_dword v176, v[190:191], off
	s_nop 0
	v_addc_co_u32_e32 v189, vcc, 0, v189, vcc
	global_load_dword v177, v[188:189], off
	global_load_dword v187, v[190:191], off offset:2048
	s_nop 0
	global_load_dword v188, v[188:189], off offset:2048
	s_nop 0
	global_load_dword v189, v[36:37], off
	v_add_co_u32_e32 v190, vcc, 0x1000, v36
	s_nop 1
	v_addc_co_u32_e32 v191, vcc, 0, v37, vcc
	v_add_co_u32_e32 v192, vcc, 0x2000, v36
	global_load_dword v190, v[190:191], off
	s_nop 0
	v_addc_co_u32_e32 v193, vcc, 0, v37, vcc
	global_load_dword v191, v[192:193], off
	v_add_co_u32_e32 v192, vcc, 0x3000, v36
	s_nop 1
	v_addc_co_u32_e32 v193, vcc, 0, v37, vcc
	v_add_co_u32_e32 v194, vcc, 0x4000, v36
	global_load_dword v192, v[192:193], off
	s_nop 0
	v_addc_co_u32_e32 v195, vcc, 0, v37, vcc
	global_load_dword v193, v[194:195], off
	v_add_co_u32_e32 v194, vcc, 0x5000, v36
	s_nop 1
	v_addc_co_u32_e32 v195, vcc, 0, v37, vcc
	v_add_co_u32_e32 v196, vcc, 0x6000, v36
	global_load_dword v194, v[194:195], off
	s_nop 0
	v_addc_co_u32_e32 v197, vcc, 0, v37, vcc
	v_add_co_u32_e32 v36, vcc, 0x7000, v36
	global_load_dword v195, v[196:197], off
	s_nop 0
	v_addc_co_u32_e32 v37, vcc, 0, v37, vcc
	global_load_dword v196, v[36:37], off

.LBB0_1111:
	s_or_b64 exec, exec, s[82:83]
	s_and_saveexec_b64 s[66:67], s[64:65]
	s_cbranch_execz .LBB0_1076
	s_waitcnt vmcnt(0)
	v_mov_b32_e32 v99, v69
	v_readlane_b32 s4, v240, 5
	v_lshlrev_b64 v[32:33], 17, v[98:99]
	v_readlane_b32 s5, v240, 6
	v_mov_b32_e32 v85, v69
	v_mov_b32_e32 v81, v69
	v_lshl_add_u64 v[32:33], s[4:5], 0, v[32:33]
	v_lshl_add_u64 v[32:33], v[82:83], 2, v[32:33]
	v_lshl_add_u64 v[32:33], v[32:33], 0, v[84:85]
	v_lshl_add_u64 v[32:33], v[32:33], 0, v[80:81]
	v_mov_b32_e32 v79, v69
	v_lshl_add_u64 v[32:33], v[32:33], 0, v[78:79]
	global_store_dword v[32:33], v8, off
	global_store_dword v[32:33], v9, off offset:1024
	global_store_dword v[32:33], v10, off offset:2048
	global_store_dword v[32:33], v11, off offset:3072
	v_add_co_u32_e32 v8, vcc, s33, v32
	s_mov_b32 s4, 0x8000
	s_nop 0
	v_addc_co_u32_e32 v9, vcc, 0, v33, vcc
	global_store_dword v[8:9], v0, off
	global_store_dword v[8:9], v1, off offset:1024
	global_store_dword v[8:9], v2, off offset:2048
	global_store_dword v[8:9], v3, off offset:3072
	v_add_co_u32_e32 v0, vcc, s4, v32
	s_mov_b32 s4, 0xc000
	s_nop 0
	v_addc_co_u32_e32 v1, vcc, 0, v33, vcc
	global_store_dword v[0:1], v12, off
	global_store_dword v[0:1], v13, off offset:1024
	global_store_dword v[0:1], v14, off offset:2048
	global_store_dword v[0:1], v15, off offset:3072
	v_add_co_u32_e32 v0, vcc, s4, v32
	s_mov_b32 s4, 0x10000
	s_nop 0
	v_addc_co_u32_e32 v1, vcc, 0, v33, vcc
	global_store_dword v[0:1], v4, off
	global_store_dword v[0:1], v5, off offset:1024
	global_store_dword v[0:1], v6, off offset:2048
	global_store_dword v[0:1], v7, off offset:3072
	v_add_co_u32_e32 v0, vcc, s4, v32
	s_mov_b32 s4, 0x14000
	s_nop 0
	v_addc_co_u32_e32 v1, vcc, 0, v33, vcc
	global_store_dword v[0:1], v20, off
	global_store_dword v[0:1], v21, off offset:1024
	global_store_dword v[0:1], v22, off offset:2048
	global_store_dword v[0:1], v23, off offset:3072
	v_add_co_u32_e32 v0, vcc, s4, v32
	s_nop 1
	v_addc_co_u32_e32 v1, vcc, 0, v33, vcc
	global_store_dword v[0:1], v16, off
	global_store_dword v[0:1], v17, off offset:1024
	global_store_dword v[0:1], v18, off offset:2048
	global_store_dword v[0:1], v19, off offset:3072
	v_add_co_u32_e32 v0, vcc, 0x18000, v32
	s_nop 1
	v_addc_co_u32_e32 v1, vcc, 0, v33, vcc
	global_store_dword v[0:1], v28, off
	global_store_dword v[0:1], v29, off offset:1024
	global_store_dword v[0:1], v30, off offset:2048
	global_store_dword v[0:1], v31, off offset:3072
	v_add_co_u32_e32 v0, vcc, 0x1c000, v32
	s_nop 1
	v_addc_co_u32_e32 v1, vcc, 0, v33, vcc
	global_store_dword v[0:1], v24, off
	global_store_dword v[0:1], v25, off offset:1024
	global_store_dword v[0:1], v26, off offset:2048
	global_store_dword v[0:1], v27, off offset:3072
	s_branch .LBB0_1076

.LBB0_1458:
	s_movk_i32 s42, 0x7f
	v_add_u32_e32 v0, 0xffffff80, v100
	v_cmp_lt_i32_e64 s[42:43], s42, v100
	v_cmp_gt_i32_e32 vcc, s33, v100
	v_lshlrev_b32_e32 v82, 2, v64
	v_cndmask_b32_e64 v0, v100, v0, s[42:43]
	v_lshrrev_b32_e32 v1, 31, v0
	v_add_u32_e32 v1, v0, v1
	v_and_b32_e32 v2, 0x3fffffe, v1
	v_bfe_u32 v34, v1, 1, 3
	v_ashrrev_i32_e32 v1, 31, v0
	v_lshrrev_b32_e32 v1, 28, v1
	v_sub_u32_e32 v2, v0, v2
	v_add_u32_e32 v0, v0, v1
	v_ashrrev_i32_e32 v32, 4, v0
	v_lshlrev_b32_e32 v80, 6, v2
	v_lshlrev_b32_e32 v0, 4, v32
	v_ashrrev_i32_e32 v81, 31, v80
	v_or3_b32 v84, v0, v34, 8
	v_lshlrev_b32_e32 v78, 2, v68
	v_mov_b32_e32 v16, v67
	v_mov_b32_e32 v17, v67
	v_mov_b32_e32 v18, v67
	v_mov_b32_e32 v19, v67
	v_mov_b32_e32 v0, v67
	v_mov_b32_e32 v1, v67
	v_mov_b32_e32 v2, v67
	v_mov_b32_e32 v3, v67
	v_mov_b32_e32 v8, v67
	v_mov_b32_e32 v9, v67
	v_mov_b32_e32 v10, v67
	v_mov_b32_e32 v11, v67
	v_mov_b32_e32 v4, v67
	v_mov_b32_e32 v5, v67
	v_mov_b32_e32 v6, v67
	v_mov_b32_e32 v7, v67
	v_mov_b32_e32 v20, v67
	v_mov_b32_e32 v21, v67
	v_mov_b32_e32 v22, v67
	v_mov_b32_e32 v23, v67
	v_mov_b32_e32 v12, v67
	v_mov_b32_e32 v13, v67
	v_mov_b32_e32 v14, v67
	v_mov_b32_e32 v15, v67
	v_mov_b32_e32 v24, v67
	v_mov_b32_e32 v25, v67
	v_mov_b32_e32 v26, v67
	v_mov_b32_e32 v27, v67
	v_mov_b32_e32 v28, v67
	v_mov_b32_e32 v29, v67
	v_mov_b32_e32 v30, v67
	v_mov_b32_e32 v31, v67
	s_and_saveexec_b64 s[56:57], vcc
	s_cbranch_execz .LBB0_1460
	s_waitcnt vmcnt(0)
	v_ashrrev_i32_e32 v85, 31, v84
	v_readlane_b32 s80, v241, 18
	v_lshlrev_b64 v[0:1], 16, v[84:85]
	v_readlane_b32 s90, v241, 28
	v_readlane_b32 s91, v241, 29
	v_mov_b32_e32 v77, v67
	v_mov_b32_e32 v83, v67
	v_lshl_add_u64 v[0:1], s[90:91], 0, v[0:1]
	v_lshl_add_u64 v[0:1], v[80:81], 2, v[0:1]
	v_lshl_add_u64 v[0:1], v[0:1], 0, v[76:77]
	v_lshl_add_u64 v[0:1], v[0:1], 0, v[82:83]
	v_mov_b32_e32 v79, v67
	v_lshl_add_u64 v[24:25], v[0:1], 0, v[78:79]
	v_readlane_b32 s81, v241, 19
	v_add_co_u32_e32 v4, vcc, s60, v24
	v_readlane_b32 s82, v241, 20
	s_nop 0
	v_addc_co_u32_e32 v5, vcc, 0, v25, vcc
	global_load_dword v16, v[24:25], off
	global_load_dword v17, v[24:25], off offset:512
	global_load_dword v18, v[24:25], off offset:1024
	global_load_dword v19, v[24:25], off offset:1536
	global_load_dword v0, v[4:5], off
	global_load_dword v1, v[4:5], off offset:512
	global_load_dword v2, v[4:5], off offset:1024
	global_load_dword v3, v[4:5], off offset:1536
	v_add_co_u32_e32 v4, vcc, s61, v24
	v_readlane_b32 s83, v241, 21
	s_nop 0
	v_addc_co_u32_e32 v5, vcc, 0, v25, vcc
	v_add_co_u32_e32 v12, vcc, s62, v24
	v_readlane_b32 s84, v241, 22
	s_nop 0
	v_addc_co_u32_e32 v13, vcc, 0, v25, vcc
	global_load_dword v8, v[4:5], off
	global_load_dword v9, v[4:5], off offset:512
	global_load_dword v10, v[4:5], off offset:1024
	global_load_dword v11, v[4:5], off offset:1536
	s_nop 0
	global_load_dword v4, v[12:13], off
	global_load_dword v5, v[12:13], off offset:512
	global_load_dword v6, v[12:13], off offset:1024
	global_load_dword v7, v[12:13], off offset:1536
	v_add_co_u32_e32 v12, vcc, s63, v24
	v_readlane_b32 s85, v241, 23
	s_nop 0
	v_addc_co_u32_e32 v13, vcc, 0, v25, vcc
	v_add_co_u32_e32 v26, vcc, s64, v24
	v_readlane_b32 s86, v241, 24
	s_nop 0
	v_addc_co_u32_e32 v27, vcc, 0, v25, vcc
	v_add_co_u32_e32 v28, vcc, 0xc000, v24
	global_load_dword v20, v[12:13], off
	global_load_dword v21, v[12:13], off offset:512
	global_load_dword v22, v[12:13], off offset:1024
	global_load_dword v23, v[12:13], off offset:1536
	s_nop 0
	global_load_dword v12, v[26:27], off
	global_load_dword v13, v[26:27], off offset:512
	global_load_dword v14, v[26:27], off offset:1024
	global_load_dword v15, v[26:27], off offset:1536
	v_addc_co_u32_e32 v29, vcc, 0, v25, vcc
	v_add_co_u32_e32 v36, vcc, 0xe000, v24
	v_readlane_b32 s87, v241, 25
	s_nop 0
	v_addc_co_u32_e32 v37, vcc, 0, v25, vcc
	global_load_dword v24, v[28:29], off
	global_load_dword v25, v[28:29], off offset:512
	global_load_dword v26, v[28:29], off offset:1024
	global_load_dword v27, v[28:29], off offset:1536
	s_nop 0
	global_load_dword v28, v[36:37], off
	global_load_dword v29, v[36:37], off offset:512
	global_load_dword v30, v[36:37], off offset:1024
	global_load_dword v31, v[36:37], off offset:1536
	v_readlane_b32 s88, v241, 26
	v_readlane_b32 s89, v241, 27
	v_readlane_b32 s92, v241, 30
	v_readlane_b32 s93, v241, 31
	v_readlane_b32 s94, v241, 32
	v_readlane_b32 s95, v241, 33
	v_readlane_b32 s80, v241, 37
	v_readlane_b32 s92, v241, 49
	v_readlane_b32 s93, v241, 50
	v_readlane_b32 s94, v241, 51
	v_readlane_b32 s95, v241, 52
	v_readlane_b32 s81, v241, 38
	v_readlane_b32 s82, v241, 39
	v_readlane_b32 s83, v241, 40
	v_readlane_b32 s84, v241, 41
	v_readlane_b32 s85, v241, 42
	v_readlane_b32 s86, v241, 43
	v_readlane_b32 s87, v241, 44
	v_readlane_b32 s88, v241, 45
	v_readlane_b32 s89, v241, 46
	v_readlane_b32 s90, v241, 47
	v_readlane_b32 s91, v241, 48
.LBB0_1460:
	s_or_b64 exec, exec, s[56:57]
	v_ashrrev_i32_e32 v33, 31, v32
	v_lshlrev_b64 v[36:37], 11, v[32:33]
	s_mov_b64 s[56:57], 0x2000
	v_lshl_add_u64 v[36:37], v[36:37], 0, s[56:57]
	v_lshlrev_b64 v[32:33], 8, v[32:33]
	v_cndmask_b32_e64 v33, v37, v33, s[42:43]
	v_cndmask_b32_e64 v32, v36, v32, s[42:43]
	v_lshlrev_b64 v[36:37], 11, v[32:33]
	v_cndmask_b32_e64 v77, 32, 4, s[42:43]
	v_lshl_add_u64 v[38:39], s[68:69], 0, v[36:37]
	v_lshlrev_b32_e32 v66, 8, v34
	v_lshl_add_u64 v[40:41], s[48:49], 0, v[36:37]
	v_lshl_add_u64 v[36:37], s[50:51], 0, v[36:37]
	v_lshl_add_u64 v[38:39], v[38:39], 0, v[66:67]
	v_lshl_add_u64 v[40:41], v[40:41], 0, v[66:67]
	v_lshl_add_u64 v[36:37], v[36:37], 0, v[66:67]
	v_add_u32_e32 v66, -1, v77
	v_lshl_add_u64 v[36:37], v[80:81], 1, v[36:37]
	v_lshlrev_b64 v[42:43], 17, v[66:67]
	v_lshl_add_u64 v[44:45], v[38:39], 0, v[42:43]
	v_mov_b32_e32 v71, v67
	v_lshl_add_u64 v[46:47], v[40:41], 0, v[42:43]
	v_lshl_add_u64 v[42:43], v[36:37], 0, v[42:43]
	v_mov_b32_e32 v73, v67
	v_lshl_add_u64 v[44:45], v[44:45], 0, v[70:71]
	v_lshl_add_u64 v[46:47], v[46:47], 0, v[70:71]
	v_lshl_add_u64 v[42:43], v[42:43], 0, v[72:73]
	s_waitcnt vmcnt(0)
	global_load_dword v79, v[44:45], off
	global_load_dword v83, v[44:45], off offset:2048
	global_load_dword v85, v[46:47], off
	global_load_dword v93, v[46:47], off offset:2048
	v_add_co_u32_e32 v48, vcc, s65, v44
	v_lshlrev_b32_e32 v33, 6, v77
	s_nop 0
	v_addc_co_u32_e32 v49, vcc, 0, v45, vcc
	v_add_co_u32_e32 v50, vcc, s65, v46
	v_lshlrev_b32_e32 v34, 7, v34
	s_nop 0
	v_addc_co_u32_e32 v51, vcc, 0, v47, vcc
	global_load_dword v124, v[48:49], off
	global_load_dword v125, v[48:49], off offset:2048
	global_load_dword v126, v[50:51], off
	global_load_dword v127, v[50:51], off offset:2048
	v_add_co_u32_e32 v48, vcc, s60, v44
	v_lshl_add_u64 v[86:87], v[38:39], 0, v[70:71]
	s_nop 0
	v_addc_co_u32_e32 v49, vcc, 0, v45, vcc
	v_add_co_u32_e32 v50, vcc, s60, v46
	v_lshl_add_u64 v[88:89], v[40:41], 0, v[70:71]
	s_nop 0
	v_addc_co_u32_e32 v51, vcc, 0, v47, vcc
	global_load_dword v128, v[48:49], off
	global_load_dword v129, v[48:49], off offset:2048
	global_load_dword v130, v[50:51], off
	global_load_dword v131, v[50:51], off offset:2048
	v_add_co_u32_e32 v48, vcc, s66, v44
	v_add3_u32 v71, v113, v33, v32
	s_nop 0
	v_addc_co_u32_e32 v49, vcc, 0, v45, vcc
	v_add_co_u32_e32 v50, vcc, s66, v46
	s_mov_b32 s73, 1
	s_nop 0
	v_addc_co_u32_e32 v51, vcc, 0, v47, vcc
	global_load_dword v132, v[48:49], off
	global_load_dword v133, v[48:49], off offset:2048
	global_load_dword v134, v[50:51], off
	global_load_dword v135, v[50:51], off offset:2048
	v_add_co_u32_e32 v48, vcc, s61, v44
	v_lshl_add_u64 v[90:91], v[36:37], 0, v[72:73]
	s_nop 0
	v_addc_co_u32_e32 v49, vcc, 0, v45, vcc
	v_add_co_u32_e32 v50, vcc, s61, v46
	v_add_u32_e32 v92, -2, v77
	s_nop 0
	v_addc_co_u32_e32 v51, vcc, 0, v47, vcc
	global_load_dword v136, v[48:49], off
	global_load_dword v137, v[48:49], off offset:2048
	global_load_dword v138, v[50:51], off
	global_load_dword v139, v[50:51], off offset:2048
	v_add_co_u32_e32 v48, vcc, s67, v44
	v_lshlrev_b32_e32 v73, 10, v71
	s_nop 0
	v_addc_co_u32_e32 v49, vcc, 0, v45, vcc
	v_add_co_u32_e32 v50, vcc, s67, v46
	s_mov_b64 s[56:57], 0
	s_nop 0
	v_addc_co_u32_e32 v51, vcc, 0, v47, vcc
	global_load_dword v140, v[48:49], off
	global_load_dword v141, v[48:49], off offset:2048
	global_load_dword v142, v[50:51], off
	global_load_dword v143, v[50:51], off offset:2048
	v_add_co_u32_e32 v48, vcc, s62, v44
	v_lshlrev_b32_e32 v94, 1, v34
	s_nop 0
	v_addc_co_u32_e32 v49, vcc, 0, v45, vcc
	v_add_co_u32_e32 v50, vcc, s62, v46
	s_nop 1
	v_addc_co_u32_e32 v51, vcc, 0, v47, vcc
	v_add_co_u32_e32 v44, vcc, s72, v44
	global_load_dword v144, v[48:49], off
	global_load_dword v145, v[48:49], off offset:2048
	global_load_dword v146, v[50:51], off
	global_load_dword v147, v[50:51], off offset:2048
	v_addc_co_u32_e32 v45, vcc, 0, v45, vcc
	v_add_co_u32_e32 v46, vcc, s72, v46
	s_nop 1
	v_addc_co_u32_e32 v47, vcc, 0, v47, vcc
	global_load_dword v148, v[44:45], off
	global_load_dword v149, v[44:45], off offset:2048
	global_load_dword v150, v[46:47], off
	global_load_dword v151, v[46:47], off offset:2048
	global_load_dword v152, v[42:43], off
	global_load_dword v153, v[42:43], off offset:2048
	v_add_co_u32_e32 v44, vcc, s65, v42
	s_nop 1
	v_addc_co_u32_e32 v45, vcc, 0, v43, vcc
	v_add_co_u32_e32 v46, vcc, s60, v42
	s_nop 1
	v_addc_co_u32_e32 v47, vcc, 0, v43, vcc
	v_add_co_u32_e32 v42, vcc, 0x3000, v42
	s_nop 1
	v_addc_co_u32_e32 v43, vcc, 0, v43, vcc
	global_load_dword v154, v[44:45], off
	global_load_dword v155, v[44:45], off offset:2048
	global_load_dword v156, v[46:47], off
	global_load_dword v157, v[46:47], off offset:2048
	global_load_dword v158, v[42:43], off
	global_load_dword v159, v[42:43], off offset:2048
	s_waitcnt vmcnt(0)
	s_branch .LBB0_1462

.LBB0_1462:
	s_waitcnt vmcnt(4) lgkmcnt(0)
	v_lshlrev_b32_e32 v54, 16, v85
	v_and_b32_e32 v55, 0xffff0000, v85
	v_lshlrev_b32_e32 v58, 16, v93
	v_and_b32_e32 v59, 0xffff0000, v93
	v_pk_add_f32 v[32:33], v[54:55], 0 op_sel_hi:[1,0]
	v_lshlrev_b32_e32 v62, 16, v126
	v_and_b32_e32 v63, 0xffff0000, v126
	v_pk_add_f32 v[32:33], v[32:33], v[58:59]
	v_lshlrev_b32_e32 v98, 16, v127
	v_and_b32_e32 v99, 0xffff0000, v127
	v_pk_add_f32 v[32:33], v[32:33], v[62:63]
	v_lshlrev_b32_e32 v96, 16, v130
	v_and_b32_e32 v97, 0xffff0000, v130
	v_pk_add_f32 v[32:33], v[32:33], v[98:99]
	v_lshlrev_b32_e32 v60, 16, v131
	v_pk_add_f32 v[32:33], v[32:33], v[96:97]
	v_and_b32_e32 v61, 0xffff0000, v131
	v_lshlrev_b32_e32 v56, 16, v134
	v_and_b32_e32 v57, 0xffff0000, v134
	v_pk_add_f32 v[32:33], v[32:33], v[60:61]
	v_lshlrev_b32_e32 v52, 16, v135
	v_and_b32_e32 v53, 0xffff0000, v135
	v_pk_add_f32 v[32:33], v[32:33], v[56:57]
	v_lshlrev_b32_e32 v50, 16, v138
	v_and_b32_e32 v51, 0xffff0000, v138
	v_pk_add_f32 v[32:33], v[32:33], v[52:53]
	v_lshlrev_b32_e32 v48, 16, v139
	v_and_b32_e32 v49, 0xffff0000, v139
	v_pk_add_f32 v[32:33], v[32:33], v[50:51]
	v_lshlrev_b32_e32 v46, 16, v142
	v_and_b32_e32 v47, 0xffff0000, v142
	v_pk_add_f32 v[32:33], v[32:33], v[48:49]
	v_lshlrev_b32_e32 v44, 16, v143
	v_and_b32_e32 v45, 0xffff0000, v143
	v_pk_add_f32 v[32:33], v[32:33], v[46:47]
	v_lshlrev_b32_e32 v42, 16, v146
	v_and_b32_e32 v43, 0xffff0000, v146
	v_pk_add_f32 v[32:33], v[32:33], v[44:45]
	v_lshlrev_b32_e32 v40, 16, v147
	v_and_b32_e32 v41, 0xffff0000, v147
	v_pk_add_f32 v[32:33], v[32:33], v[42:43]
	v_lshlrev_b32_e32 v38, 16, v150
	v_and_b32_e32 v39, 0xffff0000, v150
	v_pk_add_f32 v[32:33], v[32:33], v[40:41]
	v_lshlrev_b32_e32 v34, 16, v151
	v_and_b32_e32 v35, 0xffff0000, v151
	v_pk_add_f32 v[32:33], v[32:33], v[38:39]
	v_mov_b32_e32 v166, v34
	v_pk_add_f32 v[32:33], v[32:33], v[34:35]
	ds_write_b64 v69, v[32:33]
	s_waitcnt lgkmcnt(0)
	s_barrier
	ds_read_b64 v[32:33], v65
	ds_read_b64 v[36:37], v102
	ds_read_b64 v[160:161], v104
	ds_read_b64 v[162:163], v103
	v_exp_f32_e32 v164, v34
	v_exp_f32_e32 v165, v35
	s_waitcnt lgkmcnt(2)
	v_add_f32_e32 v66, v32, v36
	v_add_f32_e32 v75, v33, v37
	s_waitcnt lgkmcnt(1)
	v_cndmask_b32_e64 v32, v160, 0, s[2:3]
	s_waitcnt lgkmcnt(0)
	v_cndmask_b32_e64 v33, 0, v162, s[4:5]
	v_add_f32_e32 v32, v33, v32
	v_cndmask_b32_e64 v33, 0, v36, s[6:7]
	v_add_f32_e32 v32, v33, v32
	v_cndmask_b32_e64 v33, v161, 0, s[2:3]
	v_cndmask_b32_e64 v36, 0, v163, s[4:5]
	v_add_f32_e32 v33, v36, v33
	v_cndmask_b32_e64 v36, 0, v37, s[6:7]
	v_add_f32_e32 v36, v36, v33
	v_mov_b32_e32 v33, v162
	v_mov_b32_e32 v167, v160
	v_pk_add_f32 v[32:33], v[32:33], v[166:167]
	v_mov_b32_e32 v37, v163
	v_mov_b32_e32 v160, v35
	v_pk_add_f32 v[34:35], v[36:37], v[160:161]
	v_sub_f32_e32 v95, v32, v33
	v_exp_f32_e32 v160, v95
	v_sub_f32_e32 v95, v34, v35
	v_exp_f32_e32 v161, v95
	v_sub_f32_e32 v95, v33, v32
	v_exp_f32_e32 v162, v95
	v_sub_f32_e32 v95, v35, v34
	v_exp_f32_e32 v163, v95
	v_lshlrev_b32_e32 v36, 16, v149
	v_and_b32_e32 v37, 0xffff0000, v149
	v_pk_mul_f32 v[36:37], v[160:161], v[36:37]
	v_add_f32_e32 v32, v32, v38
	v_cvt_pk_bf16_f32 v95, v36, v37
	v_pk_add_f32 v[36:37], v[164:165], 1.0 op_sel_hi:[1,0] neg_lo:[1,0] neg_hi:[1,0]
	v_exp_f32_e32 v160, v38
	v_sub_f32_e32 v38, v32, v33
	v_add_f32_e32 v34, v34, v39
	v_pk_mul_f32 v[36:37], v[36:37], v[162:163]
	v_exp_f32_e32 v162, v38
	v_sub_f32_e32 v38, v34, v35
	v_exp_f32_e32 v163, v38
	v_exp_f32_e32 v161, v39
	v_lshlrev_b32_e32 v38, 16, v148
	v_and_b32_e32 v39, 0xffff0000, v148
	v_pk_mul_f32 v[38:39], v[162:163], v[38:39]
	v_pk_add_f32 v[160:161], v[160:161], 1.0 op_sel_hi:[1,0] neg_lo:[1,0] neg_hi:[1,0]
	v_cvt_pk_bf16_f32 v162, v38, v39
	v_sub_f32_e32 v38, v33, v32
	v_sub_f32_e32 v39, v35, v34
	v_exp_f32_e32 v38, v38
	v_exp_f32_e32 v39, v39
	v_add_f32_e32 v32, v32, v40
	v_add_f32_e32 v34, v34, v41
	v_add_u32_e32 v166, 0xc00, v114
	v_pk_mul_f32 v[38:39], v[160:161], v[38:39]
	v_exp_f32_e32 v160, v40
	v_exp_f32_e32 v161, v41
	v_sub_f32_e32 v40, v32, v33
	v_sub_f32_e32 v41, v34, v35
	v_exp_f32_e32 v40, v40
	v_exp_f32_e32 v41, v41
	v_cvt_pk_bf16_f32 v164, v36, v37
	ds_write2_b32 v166, v162, v95 offset0:184 offset1:252
	v_cvt_pk_bf16_f32 v95, v38, v39
	v_add_u32_e32 v167, 0x5000, v114
	ds_write2_b32 v167, v95, v164 offset0:184 offset1:252
	v_lshlrev_b32_e32 v162, 16, v145
	v_and_b32_e32 v163, 0xffff0000, v145
	v_sub_f32_e32 v95, v33, v32
	v_exp_f32_e32 v164, v95
	v_sub_f32_e32 v95, v35, v34
	v_pk_mul_f32 v[40:41], v[40:41], v[162:163]
	v_add_f32_e32 v32, v32, v42
	v_exp_f32_e32 v165, v95
	v_cvt_pk_bf16_f32 v95, v40, v41
	v_pk_add_f32 v[40:41], v[160:161], 1.0 op_sel_hi:[1,0] neg_lo:[1,0] neg_hi:[1,0]
	v_exp_f32_e32 v160, v42
	v_sub_f32_e32 v42, v32, v33
	v_add_f32_e32 v34, v34, v43
	v_exp_f32_e32 v162, v42
	v_sub_f32_e32 v42, v34, v35
	v_exp_f32_e32 v163, v42
	v_exp_f32_e32 v161, v43
	v_lshlrev_b32_e32 v42, 16, v144
	v_and_b32_e32 v43, 0xffff0000, v144
	v_pk_mul_f32 v[42:43], v[162:163], v[42:43]
	v_sub_f32_e32 v162, v33, v32
	v_sub_f32_e32 v163, v35, v34
	v_exp_f32_e32 v162, v162
	v_exp_f32_e32 v163, v163
	v_cvt_pk_bf16_f32 v42, v42, v43
	v_add_f32_e32 v32, v32, v44
	v_add_f32_e32 v34, v34, v45
	ds_write2_b32 v166, v42, v95 offset0:48 offset1:116
	v_pk_add_f32 v[42:43], v[160:161], 1.0 op_sel_hi:[1,0] neg_lo:[1,0] neg_hi:[1,0]
	v_exp_f32_e32 v160, v44
	v_exp_f32_e32 v161, v45
	v_sub_f32_e32 v44, v32, v33
	v_sub_f32_e32 v45, v34, v35
	v_exp_f32_e32 v44, v44
	v_exp_f32_e32 v45, v45
	v_pk_mul_f32 v[40:41], v[40:41], v[164:165]
	v_pk_mul_f32 v[42:43], v[42:43], v[162:163]
	v_cvt_pk_bf16_f32 v164, v40, v41
	v_cvt_pk_bf16_f32 v95, v42, v43
	ds_write2_b32 v167, v95, v164 offset0:48 offset1:116
	v_lshlrev_b32_e32 v162, 16, v141
	v_and_b32_e32 v163, 0xffff0000, v141
	v_sub_f32_e32 v95, v33, v32
	v_exp_f32_e32 v164, v95
	v_sub_f32_e32 v95, v35, v34
	v_pk_mul_f32 v[44:45], v[44:45], v[162:163]
	v_add_f32_e32 v32, v32, v46
	v_exp_f32_e32 v165, v95
	v_cvt_pk_bf16_f32 v95, v44, v45
	v_pk_add_f32 v[44:45], v[160:161], 1.0 op_sel_hi:[1,0] neg_lo:[1,0] neg_hi:[1,0]
	v_exp_f32_e32 v160, v46
	v_sub_f32_e32 v46, v32, v33
	v_add_f32_e32 v34, v34, v47
	v_exp_f32_e32 v162, v46
	v_sub_f32_e32 v46, v34, v35
	v_exp_f32_e32 v163, v46
	v_exp_f32_e32 v161, v47
	v_lshlrev_b32_e32 v46, 16, v140
	v_and_b32_e32 v47, 0xffff0000, v140
	v_pk_mul_f32 v[46:47], v[162:163], v[46:47]
	v_pk_add_f32 v[160:161], v[160:161], 1.0 op_sel_hi:[1,0] neg_lo:[1,0] neg_hi:[1,0]
	v_cvt_pk_bf16_f32 v162, v46, v47
	v_sub_f32_e32 v46, v33, v32
	v_sub_f32_e32 v47, v35, v34
	v_exp_f32_e32 v46, v46
	v_exp_f32_e32 v47, v47
	v_add_f32_e32 v32, v32, v48
	v_add_f32_e32 v34, v34, v49
	v_pk_mul_f32 v[44:45], v[44:45], v[164:165]
	v_pk_mul_f32 v[46:47], v[160:161], v[46:47]
	v_exp_f32_e32 v160, v48
	v_exp_f32_e32 v161, v49
	v_sub_f32_e32 v48, v32, v33
	v_sub_f32_e32 v49, v34, v35
	v_exp_f32_e32 v48, v48
	v_exp_f32_e32 v49, v49
	v_add_u32_e32 v166, 0x800, v114
	v_cvt_pk_bf16_f32 v164, v44, v45
	ds_write2_b32 v166, v162, v95 offset0:168 offset1:236
	v_cvt_pk_bf16_f32 v95, v46, v47
	v_add_u32_e32 v167, 0x4c00, v114
	ds_write2_b32 v167, v95, v164 offset0:168 offset1:236
	v_lshlrev_b32_e32 v162, 16, v137
	v_and_b32_e32 v163, 0xffff0000, v137
	v_sub_f32_e32 v95, v33, v32
	v_exp_f32_e32 v164, v95
	v_sub_f32_e32 v95, v35, v34
	v_pk_mul_f32 v[48:49], v[48:49], v[162:163]
	v_add_f32_e32 v32, v32, v50
	v_exp_f32_e32 v165, v95
	v_cvt_pk_bf16_f32 v95, v48, v49
	v_pk_add_f32 v[48:49], v[160:161], 1.0 op_sel_hi:[1,0] neg_lo:[1,0] neg_hi:[1,0]
	v_exp_f32_e32 v160, v50
	v_sub_f32_e32 v50, v32, v33
	v_add_f32_e32 v34, v34, v51
	v_exp_f32_e32 v162, v50
	v_sub_f32_e32 v50, v34, v35
	v_exp_f32_e32 v163, v50
	v_exp_f32_e32 v161, v51
	v_lshlrev_b32_e32 v50, 16, v136
	v_and_b32_e32 v51, 0xffff0000, v136
	v_pk_mul_f32 v[50:51], v[162:163], v[50:51]
	v_sub_f32_e32 v162, v33, v32
	v_sub_f32_e32 v163, v35, v34
	v_exp_f32_e32 v162, v162
	v_exp_f32_e32 v163, v163
	v_cvt_pk_bf16_f32 v50, v50, v51
	v_add_f32_e32 v32, v32, v52
	v_add_f32_e32 v34, v34, v53
	ds_write2_b32 v166, v50, v95 offset0:32 offset1:100
	v_pk_add_f32 v[50:51], v[160:161], 1.0 op_sel_hi:[1,0] neg_lo:[1,0] neg_hi:[1,0]
	v_exp_f32_e32 v160, v52
	v_exp_f32_e32 v161, v53
	v_sub_f32_e32 v52, v32, v33
	v_sub_f32_e32 v53, v34, v35
	v_exp_f32_e32 v52, v52
	v_exp_f32_e32 v53, v53
	v_pk_mul_f32 v[48:49], v[48:49], v[164:165]
	v_pk_mul_f32 v[50:51], v[50:51], v[162:163]
	v_cvt_pk_bf16_f32 v164, v48, v49
	v_cvt_pk_bf16_f32 v95, v50, v51
	ds_write2_b32 v167, v95, v164 offset0:32 offset1:100
	v_lshlrev_b32_e32 v162, 16, v133
	v_and_b32_e32 v163, 0xffff0000, v133
	v_sub_f32_e32 v95, v33, v32
	v_exp_f32_e32 v164, v95
	v_sub_f32_e32 v95, v35, v34
	v_pk_mul_f32 v[52:53], v[52:53], v[162:163]
	v_add_f32_e32 v32, v32, v56
	v_exp_f32_e32 v165, v95
	v_cvt_pk_bf16_f32 v95, v52, v53
	v_pk_add_f32 v[52:53], v[160:161], 1.0 op_sel_hi:[1,0] neg_lo:[1,0] neg_hi:[1,0]
	v_exp_f32_e32 v160, v56
	v_add_f32_e32 v34, v34, v57
	v_sub_f32_e32 v56, v32, v33
	v_exp_f32_e32 v162, v56
	v_sub_f32_e32 v56, v34, v35
	v_exp_f32_e32 v163, v56
	v_exp_f32_e32 v161, v57
	v_lshlrev_b32_e32 v56, 16, v132
	v_and_b32_e32 v57, 0xffff0000, v132
	v_pk_mul_f32 v[56:57], v[162:163], v[56:57]
	v_pk_add_f32 v[160:161], v[160:161], 1.0 op_sel_hi:[1,0] neg_lo:[1,0] neg_hi:[1,0]
	v_cvt_pk_bf16_f32 v162, v56, v57
	v_sub_f32_e32 v56, v33, v32
	v_sub_f32_e32 v57, v35, v34
	v_exp_f32_e32 v56, v56
	v_exp_f32_e32 v57, v57
	v_pk_mul_f32 v[52:53], v[52:53], v[164:165]
	v_add_u32_e32 v166, 0x400, v114
	v_cvt_pk_bf16_f32 v164, v52, v53
	v_pk_mul_f32 v[56:57], v[160:161], v[56:57]
	ds_write2_b32 v166, v162, v95 offset0:152 offset1:220
	v_cvt_pk_bf16_f32 v95, v56, v57
	v_add_u32_e32 v167, 0x4800, v114
	v_add_f32_e32 v32, v32, v60
	ds_write2_b32 v167, v95, v164 offset0:152 offset1:220
	v_add_f32_e32 v34, v34, v61
	v_sub_f32_e32 v95, v32, v33
	v_exp_f32_e32 v162, v95
	v_sub_f32_e32 v95, v34, v35
	v_exp_f32_e32 v163, v95
	v_exp_f32_e32 v160, v60
	v_exp_f32_e32 v161, v61
	v_lshlrev_b32_e32 v60, 16, v129
	v_and_b32_e32 v61, 0xffff0000, v129
	v_sub_f32_e32 v95, v33, v32
	v_exp_f32_e32 v164, v95
	v_sub_f32_e32 v95, v35, v34
	v_pk_mul_f32 v[60:61], v[162:163], v[60:61]
	v_add_f32_e32 v32, v32, v96
	v_exp_f32_e32 v165, v95
	v_cvt_pk_bf16_f32 v95, v60, v61
	v_pk_add_f32 v[60:61], v[160:161], 1.0 op_sel_hi:[1,0] neg_lo:[1,0] neg_hi:[1,0]
	v_exp_f32_e32 v160, v96
	v_add_f32_e32 v34, v34, v97
	v_sub_f32_e32 v96, v32, v33
	v_exp_f32_e32 v162, v96
	v_sub_f32_e32 v96, v34, v35
	v_exp_f32_e32 v163, v96
	v_exp_f32_e32 v161, v97
	v_lshlrev_b32_e32 v96, 16, v128
	v_and_b32_e32 v97, 0xffff0000, v128
	v_pk_mul_f32 v[96:97], v[162:163], v[96:97]
	v_sub_f32_e32 v162, v33, v32
	v_sub_f32_e32 v163, v35, v34
	v_exp_f32_e32 v162, v162
	v_exp_f32_e32 v163, v163
	v_cvt_pk_bf16_f32 v96, v96, v97
	ds_write2_b32 v166, v96, v95 offset0:16 offset1:84
	v_pk_add_f32 v[96:97], v[160:161], 1.0 op_sel_hi:[1,0] neg_lo:[1,0] neg_hi:[1,0]
	v_pk_mul_f32 v[60:61], v[60:61], v[164:165]
	v_pk_mul_f32 v[96:97], v[96:97], v[162:163]
	v_cvt_pk_bf16_f32 v164, v60, v61
	v_cvt_pk_bf16_f32 v95, v96, v97
	v_add_f32_e32 v32, v32, v98
	ds_write2_b32 v167, v95, v164 offset0:16 offset1:84
	v_add_f32_e32 v34, v34, v99
	v_sub_f32_e32 v95, v32, v33
	v_exp_f32_e32 v162, v95
	v_sub_f32_e32 v95, v34, v35
	v_exp_f32_e32 v163, v95
	v_exp_f32_e32 v160, v98
	v_exp_f32_e32 v161, v99
	v_lshlrev_b32_e32 v98, 16, v125
	v_and_b32_e32 v99, 0xffff0000, v125
	v_sub_f32_e32 v95, v33, v32
	v_exp_f32_e32 v164, v95
	v_sub_f32_e32 v95, v35, v34
	v_pk_mul_f32 v[98:99], v[162:163], v[98:99]
	v_add_f32_e32 v32, v32, v62
	v_exp_f32_e32 v165, v95
	v_cvt_pk_bf16_f32 v95, v98, v99
	v_pk_add_f32 v[98:99], v[160:161], 1.0 op_sel_hi:[1,0] neg_lo:[1,0] neg_hi:[1,0]
	v_exp_f32_e32 v160, v62
	v_add_f32_e32 v34, v34, v63
	v_sub_f32_e32 v62, v32, v33
	v_exp_f32_e32 v162, v62
	v_sub_f32_e32 v62, v34, v35
	v_exp_f32_e32 v163, v62
	v_exp_f32_e32 v161, v63
	v_lshlrev_b32_e32 v62, 16, v124
	v_and_b32_e32 v63, 0xffff0000, v124
	v_pk_mul_f32 v[62:63], v[162:163], v[62:63]
	v_sub_f32_e32 v162, v33, v32
	v_sub_f32_e32 v163, v35, v34
	v_exp_f32_e32 v162, v162
	v_exp_f32_e32 v163, v163
	v_cvt_pk_bf16_f32 v62, v62, v63
	ds_write2_b32 v114, v62, v95 offset0:136 offset1:204
	v_pk_add_f32 v[62:63], v[160:161], 1.0 op_sel_hi:[1,0] neg_lo:[1,0] neg_hi:[1,0]
	v_pk_mul_f32 v[98:99], v[98:99], v[164:165]
	v_pk_mul_f32 v[62:63], v[62:63], v[162:163]
	v_cvt_pk_bf16_f32 v164, v98, v99
	v_cvt_pk_bf16_f32 v95, v62, v63
	v_add_u32_e32 v166, 0x4400, v114
	v_add_f32_e32 v32, v32, v58
	ds_write2_b32 v166, v95, v164 offset0:136 offset1:204
	v_add_f32_e32 v34, v34, v59
	v_sub_f32_e32 v95, v32, v33
	v_exp_f32_e32 v162, v95
	v_sub_f32_e32 v95, v34, v35
	v_exp_f32_e32 v163, v95
	v_exp_f32_e32 v160, v58
	v_exp_f32_e32 v161, v59
	v_lshlrev_b32_e32 v58, 16, v83
	v_and_b32_e32 v59, 0xffff0000, v83
	v_sub_f32_e32 v95, v33, v32
	v_exp_f32_e32 v164, v95
	v_sub_f32_e32 v95, v35, v34
	v_pk_mul_f32 v[58:59], v[162:163], v[58:59]
	v_add_f32_e32 v32, v32, v54
	v_exp_f32_e32 v165, v95
	v_cvt_pk_bf16_f32 v95, v58, v59
	v_pk_add_f32 v[58:59], v[160:161], 1.0 op_sel_hi:[1,0] neg_lo:[1,0] neg_hi:[1,0]
	v_exp_f32_e32 v160, v54
	v_add_f32_e32 v34, v34, v55
	v_sub_f32_e32 v54, v32, v33
	v_exp_f32_e32 v162, v54
	v_sub_f32_e32 v54, v34, v35
	v_exp_f32_e32 v163, v54
	v_exp_f32_e32 v161, v55
	v_lshlrev_b32_e32 v54, 16, v79
	v_and_b32_e32 v55, 0xffff0000, v79
	v_sub_f32_e32 v32, v33, v32
	v_pk_mul_f32 v[54:55], v[162:163], v[54:55]
	v_exp_f32_e32 v162, v32
	v_sub_f32_e32 v32, v35, v34
	v_exp_f32_e32 v163, v32
	v_cvt_pk_bf16_f32 v32, v54, v55
	v_pk_add_f32 v[54:55], v[160:161], 1.0 op_sel_hi:[1,0] neg_lo:[1,0] neg_hi:[1,0]
	v_pk_mul_f32 v[58:59], v[58:59], v[164:165]
	v_pk_mul_f32 v[54:55], v[54:55], v[162:163]
	v_add_f32_e32 v66, v66, v33
	v_add_f32_e32 v75, v75, v35
	v_cvt_pk_bf16_f32 v164, v58, v59
	ds_write2_b32 v114, v32, v95 offset1:68
	v_cvt_pk_bf16_f32 v32, v54, v55
	ds_write2_b32 v166, v32, v164 offset1:68
	s_and_saveexec_b64 s[58:59], s[6:7]
	s_cbranch_execz .LBB0_1464
	v_exp_f32_e32 v163, v75
	v_exp_f32_e32 v162, v66
	v_exp_f32_e32 v161, v35
	v_exp_f32_e32 v160, v33
	ds_write_b64 v105, v[162:163]
	ds_write_b64 v106, v[160:161]
.LBB0_1464:
	s_or_b64 exec, exec, s[58:59]
	v_lshlrev_b32_e32 v32, 16, v155
	v_lshlrev_b32_e32 v34, 16, v153
	v_lshlrev_b32_e32 v95, 16, v159
	v_lshlrev_b32_e32 v162, 16, v157
	v_or_b32_sdwa v161, v154, v32 dst_sel:DWORD dst_unused:UNUSED_PAD src0_sel:WORD_0 src1_sel:DWORD
	v_or_b32_sdwa v160, v152, v34 dst_sel:DWORD dst_unused:UNUSED_PAD src0_sel:WORD_0 src1_sel:DWORD
	v_or_b32_sdwa v163, v158, v95 dst_sel:DWORD dst_unused:UNUSED_PAD src0_sel:WORD_0 src1_sel:DWORD
	v_or_b32_sdwa v162, v156, v162 dst_sel:DWORD dst_unused:UNUSED_PAD src0_sel:WORD_0 src1_sel:DWORD
	v_and_b32_e32 v32, 0xffff0000, v155
	v_and_b32_e32 v34, 0xffff0000, v153
	ds_write_b128 v115, v[160:163] offset:35840
	v_or_b32_sdwa v161, v154, v32 dst_sel:DWORD dst_unused:UNUSED_PAD src0_sel:WORD_1 src1_sel:DWORD
	v_or_b32_sdwa v160, v152, v34 dst_sel:DWORD dst_unused:UNUSED_PAD src0_sel:WORD_1 src1_sel:DWORD
	v_and_b32_e32 v32, 0xffff0000, v159
	v_and_b32_e32 v34, 0xffff0000, v157
	v_or_b32_sdwa v163, v158, v32 dst_sel:DWORD dst_unused:UNUSED_PAD src0_sel:WORD_1 src1_sel:DWORD
	v_or_b32_sdwa v162, v156, v34 dst_sel:DWORD dst_unused:UNUSED_PAD src0_sel:WORD_1 src1_sel:DWORD
	v_cmp_lt_u32_e32 vcc, s73, v77
	ds_write_b128 v115, v[160:163] offset:35984
	s_and_saveexec_b64 s[58:59], vcc
	s_cbranch_execz .LBB0_1461
	v_ashrrev_i32_e32 v93, 31, v92
	v_lshlrev_b64 v[124:125], 17, v[92:93]
	v_lshl_add_u64 v[148:149], v[86:87], 0, v[124:125]
	v_lshl_add_u64 v[150:151], v[88:89], 0, v[124:125]
	v_lshl_add_u64 v[154:155], v[90:91], 0, v[124:125]
	global_load_dword v79, v[148:149], off
	global_load_dword v83, v[148:149], off offset:2048
	global_load_dword v85, v[150:151], off
	global_load_dword v93, v[150:151], off offset:2048
	v_add_co_u32_e32 v126, vcc, 0x1000, v148
	s_nop 1
	v_addc_co_u32_e32 v127, vcc, 0, v149, vcc
	v_add_co_u32_e32 v128, vcc, 0x1000, v150
	s_nop 1
	v_addc_co_u32_e32 v129, vcc, 0, v151, vcc
	v_add_co_u32_e32 v130, vcc, s60, v148
	global_load_dword v124, v[126:127], off
	global_load_dword v125, v[126:127], off offset:2048
	s_nop 0
	global_load_dword v126, v[128:129], off
	global_load_dword v127, v[128:129], off offset:2048
	v_addc_co_u32_e32 v131, vcc, 0, v149, vcc
	v_add_co_u32_e32 v132, vcc, s60, v150
	s_nop 1
	v_addc_co_u32_e32 v133, vcc, 0, v151, vcc
	v_add_co_u32_e32 v134, vcc, s66, v148
	global_load_dword v128, v[130:131], off
	global_load_dword v129, v[130:131], off offset:2048
	s_nop 0
	global_load_dword v130, v[132:133], off
	global_load_dword v131, v[132:133], off offset:2048
	v_addc_co_u32_e32 v135, vcc, 0, v149, vcc
	v_add_co_u32_e32 v136, vcc, s66, v150
	s_nop 1
	v_addc_co_u32_e32 v137, vcc, 0, v151, vcc
	v_add_co_u32_e32 v138, vcc, s61, v148
	global_load_dword v132, v[134:135], off
	global_load_dword v133, v[134:135], off offset:2048
	s_nop 0
	global_load_dword v134, v[136:137], off
	global_load_dword v135, v[136:137], off offset:2048
	v_addc_co_u32_e32 v139, vcc, 0, v149, vcc
	v_add_co_u32_e32 v140, vcc, s61, v150
	s_nop 1
	v_addc_co_u32_e32 v141, vcc, 0, v151, vcc
	v_add_co_u32_e32 v142, vcc, s67, v148
	global_load_dword v136, v[138:139], off
	global_load_dword v137, v[138:139], off offset:2048
	s_nop 0
	global_load_dword v138, v[140:141], off
	global_load_dword v139, v[140:141], off offset:2048
	v_addc_co_u32_e32 v143, vcc, 0, v149, vcc
	v_add_co_u32_e32 v144, vcc, s67, v150
	s_nop 1
	v_addc_co_u32_e32 v145, vcc, 0, v151, vcc
	v_add_co_u32_e32 v146, vcc, s62, v148
	global_load_dword v140, v[142:143], off
	global_load_dword v141, v[142:143], off offset:2048
	s_nop 0
	global_load_dword v142, v[144:145], off
	global_load_dword v143, v[144:145], off offset:2048
	v_addc_co_u32_e32 v147, vcc, 0, v149, vcc
	v_add_co_u32_e32 v152, vcc, s62, v150
	s_nop 1
	v_addc_co_u32_e32 v153, vcc, 0, v151, vcc
	global_load_dword v144, v[146:147], off
	global_load_dword v145, v[146:147], off offset:2048
	s_nop 0
	global_load_dword v146, v[152:153], off
	global_load_dword v147, v[152:153], off offset:2048
	v_add_co_u32_e32 v152, vcc, 0x7000, v148
	s_nop 1
	v_addc_co_u32_e32 v153, vcc, 0, v149, vcc
	v_add_co_u32_e32 v156, vcc, 0x7000, v150
	s_nop 1
	v_addc_co_u32_e32 v157, vcc, 0, v151, vcc
	global_load_dword v148, v[152:153], off
	global_load_dword v149, v[152:153], off offset:2048
	global_load_dword v150, v[156:157], off
	global_load_dword v151, v[156:157], off offset:2048
	s_nop 0
	global_load_dword v152, v[154:155], off
	global_load_dword v153, v[154:155], off offset:2048
	v_add_co_u32_e32 v156, vcc, 0x1000, v154
	s_nop 1
	v_addc_co_u32_e32 v157, vcc, 0, v155, vcc
	v_add_co_u32_e32 v158, vcc, 0x2000, v154
	s_nop 1
	v_addc_co_u32_e32 v159, vcc, 0, v155, vcc
	v_add_co_u32_e32 v160, vcc, 0x3000, v154
	s_nop 1
	v_addc_co_u32_e32 v161, vcc, 0, v155, vcc
	global_load_dword v154, v[156:157], off
	global_load_dword v155, v[156:157], off offset:2048
	s_nop 0
	global_load_dword v156, v[158:159], off
	global_load_dword v157, v[158:159], off offset:2048
	s_nop 0
	global_load_dword v158, v[160:161], off
	global_load_dword v159, v[160:161], off offset:2048
	s_branch .LBB0_1461
.LBB0_1466:
	s_or_b64 exec, exec, s[56:57]
	s_and_saveexec_b64 s[56:57], s[42:43]
	s_cbranch_execz .LBB0_1457
	s_waitcnt vmcnt(0)
	v_ashrrev_i32_e32 v85, 31, v84
	v_lshlrev_b64 v[32:33], 16, v[84:85]
	v_lshl_add_u64 v[32:33], s[52:53], 0, v[32:33]
	v_lshl_add_u64 v[32:33], v[80:81], 2, v[32:33]
	v_mov_b32_e32 v77, v67
	v_lshl_add_u64 v[32:33], v[32:33], 0, v[76:77]
	v_mov_b32_e32 v83, v67
	v_lshl_add_u64 v[32:33], v[32:33], 0, v[82:83]
	v_mov_b32_e32 v79, v67
	v_lshl_add_u64 v[32:33], v[32:33], 0, v[78:79]
	global_store_dword v[32:33], v16, off
	global_store_dword v[32:33], v17, off offset:512
	global_store_dword v[32:33], v18, off offset:1024
	global_store_dword v[32:33], v19, off offset:1536
	v_add_co_u32_e32 v16, vcc, s60, v32
	s_nop 1
	v_addc_co_u32_e32 v17, vcc, 0, v33, vcc
	global_store_dword v[16:17], v0, off
	global_store_dword v[16:17], v1, off offset:512
	global_store_dword v[16:17], v2, off offset:1024
	global_store_dword v[16:17], v3, off offset:1536
	v_add_co_u32_e32 v0, vcc, s61, v32
	s_nop 1
	v_addc_co_u32_e32 v1, vcc, 0, v33, vcc
	global_store_dword v[0:1], v8, off
	global_store_dword v[0:1], v9, off offset:512
	global_store_dword v[0:1], v10, off offset:1024
	global_store_dword v[0:1], v11, off offset:1536
	v_add_co_u32_e32 v0, vcc, s62, v32
	s_nop 1
	v_addc_co_u32_e32 v1, vcc, 0, v33, vcc
	global_store_dword v[0:1], v4, off
	global_store_dword v[0:1], v5, off offset:512
	global_store_dword v[0:1], v6, off offset:1024
	global_store_dword v[0:1], v7, off offset:1536
	v_add_co_u32_e32 v0, vcc, s63, v32
	s_nop 1
	v_addc_co_u32_e32 v1, vcc, 0, v33, vcc
	global_store_dword v[0:1], v20, off
	global_store_dword v[0:1], v21, off offset:512
	global_store_dword v[0:1], v22, off offset:1024
	global_store_dword v[0:1], v23, off offset:1536
	v_add_co_u32_e32 v0, vcc, s64, v32
	s_nop 1
	v_addc_co_u32_e32 v1, vcc, 0, v33, vcc
	global_store_dword v[0:1], v12, off
	global_store_dword v[0:1], v13, off offset:512
	global_store_dword v[0:1], v14, off offset:1024
	global_store_dword v[0:1], v15, off offset:1536
	v_add_co_u32_e32 v0, vcc, 0xc000, v32
	s_nop 1
	v_addc_co_u32_e32 v1, vcc, 0, v33, vcc
	global_store_dword v[0:1], v24, off
	global_store_dword v[0:1], v25, off offset:512
	global_store_dword v[0:1], v26, off offset:1024
	global_store_dword v[0:1], v27, off offset:1536
	v_add_co_u32_e32 v0, vcc, 0xe000, v32
	s_nop 1
	v_addc_co_u32_e32 v1, vcc, 0, v33, vcc
	global_store_dword v[0:1], v28, off
	global_store_dword v[0:1], v29, off offset:512
	global_store_dword v[0:1], v30, off offset:1024
	global_store_dword v[0:1], v31, off offset:1536
	s_branch .LBB0_1457

.LBB0_1473:
	s_movk_i32 s38, 0x80
	v_cmp_gt_i32_e32 vcc, s38, v100
	v_add_u32_e32 v0, 0xffffff80, v100
	v_cmp_lt_i32_e64 s[38:39], s33, v100
	v_lshlrev_b32_e32 v78, 2, v66
	v_mov_b32_e32 v12, v65
	v_cndmask_b32_e64 v0, v100, v0, s[38:39]
	v_lshrrev_b32_e32 v1, 31, v0
	v_add_u32_e32 v1, v0, v1
	v_and_b32_e32 v2, 0x3fffffe, v1
	v_bfe_u32 v34, v1, 1, 3
	v_ashrrev_i32_e32 v1, 31, v0
	v_lshrrev_b32_e32 v1, 28, v1
	v_sub_u32_e32 v2, v0, v2
	v_add_u32_e32 v0, v0, v1
	v_ashrrev_i32_e32 v32, 4, v0
	v_lshlrev_b32_e32 v80, 6, v2
	v_lshl_or_b32 v82, v32, 4, v34
	v_ashrrev_i32_e32 v81, 31, v80
	v_ashrrev_i32_e32 v83, 31, v82
	v_mov_b32_e32 v13, v65
	v_mov_b32_e32 v14, v65
	v_mov_b32_e32 v15, v65
	v_mov_b32_e32 v0, v65
	v_mov_b32_e32 v1, v65
	v_mov_b32_e32 v2, v65
	v_mov_b32_e32 v3, v65
	v_mov_b32_e32 v8, v65
	v_mov_b32_e32 v9, v65
	v_mov_b32_e32 v10, v65
	v_mov_b32_e32 v11, v65
	v_mov_b32_e32 v4, v65
	v_mov_b32_e32 v5, v65
	v_mov_b32_e32 v6, v65
	v_mov_b32_e32 v7, v65
	v_mov_b32_e32 v20, v65
	v_mov_b32_e32 v21, v65
	v_mov_b32_e32 v22, v65
	v_mov_b32_e32 v23, v65
	v_mov_b32_e32 v16, v65
	v_mov_b32_e32 v17, v65
	v_mov_b32_e32 v18, v65
	v_mov_b32_e32 v19, v65
	v_mov_b32_e32 v24, v65
	v_mov_b32_e32 v25, v65
	v_mov_b32_e32 v26, v65
	v_mov_b32_e32 v27, v65
	v_mov_b32_e32 v28, v65
	v_mov_b32_e32 v29, v65
	v_mov_b32_e32 v30, v65
	v_mov_b32_e32 v31, v65
	s_and_saveexec_b64 s[58:59], vcc
	s_cbranch_execz .LBB0_1475
	v_readlane_b32 s80, v241, 18
	v_lshlrev_b64 v[0:1], 16, v[82:83]
	v_readlane_b32 s90, v241, 28
	v_readlane_b32 s91, v241, 29
	s_waitcnt vmcnt(0)
	v_mov_b32_e32 v75, v65
	v_mov_b32_e32 v77, v65
	v_lshl_add_u64 v[0:1], s[90:91], 0, v[0:1]
	v_lshl_add_u64 v[0:1], v[80:81], 2, v[0:1]
	v_lshl_add_u64 v[0:1], v[0:1], 0, v[74:75]
	v_lshl_add_u64 v[0:1], v[0:1], 0, v[76:77]
	v_mov_b32_e32 v79, v65
	v_lshl_add_u64 v[24:25], v[0:1], 0, v[78:79]
	v_readlane_b32 s81, v241, 19
	v_add_co_u32_e32 v4, vcc, s62, v24
	v_readlane_b32 s82, v241, 20
	s_nop 0
	v_addc_co_u32_e32 v5, vcc, 0, v25, vcc
	global_load_dword v12, v[24:25], off
	global_load_dword v13, v[24:25], off offset:512
	global_load_dword v14, v[24:25], off offset:1024
	global_load_dword v15, v[24:25], off offset:1536
	global_load_dword v0, v[4:5], off
	global_load_dword v1, v[4:5], off offset:512
	global_load_dword v2, v[4:5], off offset:1024
	global_load_dword v3, v[4:5], off offset:1536
	v_add_co_u32_e32 v4, vcc, s63, v24
	v_readlane_b32 s83, v241, 21
	s_nop 0
	v_addc_co_u32_e32 v5, vcc, 0, v25, vcc
	v_add_co_u32_e32 v16, vcc, s64, v24
	v_readlane_b32 s84, v241, 22
	s_nop 0
	v_addc_co_u32_e32 v17, vcc, 0, v25, vcc
	global_load_dword v8, v[4:5], off
	global_load_dword v9, v[4:5], off offset:512
	global_load_dword v10, v[4:5], off offset:1024
	global_load_dword v11, v[4:5], off offset:1536
	s_nop 0
	global_load_dword v4, v[16:17], off
	global_load_dword v5, v[16:17], off offset:512
	global_load_dword v6, v[16:17], off offset:1024
	global_load_dword v7, v[16:17], off offset:1536
	v_add_co_u32_e32 v16, vcc, s65, v24
	v_readlane_b32 s85, v241, 23
	s_nop 0
	v_addc_co_u32_e32 v17, vcc, 0, v25, vcc
	v_add_co_u32_e32 v26, vcc, s66, v24
	v_readlane_b32 s86, v241, 24
	s_nop 0
	v_addc_co_u32_e32 v27, vcc, 0, v25, vcc
	v_add_co_u32_e32 v28, vcc, 0xc000, v24
	global_load_dword v20, v[16:17], off
	global_load_dword v21, v[16:17], off offset:512
	global_load_dword v22, v[16:17], off offset:1024
	global_load_dword v23, v[16:17], off offset:1536
	s_nop 0
	global_load_dword v16, v[26:27], off
	global_load_dword v17, v[26:27], off offset:512
	global_load_dword v18, v[26:27], off offset:1024
	global_load_dword v19, v[26:27], off offset:1536
	v_addc_co_u32_e32 v29, vcc, 0, v25, vcc
	v_add_co_u32_e32 v36, vcc, 0xe000, v24
	v_readlane_b32 s87, v241, 25
	s_nop 0
	v_addc_co_u32_e32 v37, vcc, 0, v25, vcc
	global_load_dword v24, v[28:29], off
	global_load_dword v25, v[28:29], off offset:512
	global_load_dword v26, v[28:29], off offset:1024
	global_load_dword v27, v[28:29], off offset:1536
	s_nop 0
	global_load_dword v28, v[36:37], off
	global_load_dword v29, v[36:37], off offset:512
	global_load_dword v30, v[36:37], off offset:1024
	global_load_dword v31, v[36:37], off offset:1536
	v_readlane_b32 s88, v241, 26
	v_readlane_b32 s89, v241, 27
	v_readlane_b32 s92, v241, 30
	v_readlane_b32 s93, v241, 31
	v_readlane_b32 s94, v241, 32
	v_readlane_b32 s95, v241, 33
	v_readlane_b32 s80, v241, 37
	v_readlane_b32 s92, v241, 49
	v_readlane_b32 s93, v241, 50
	v_readlane_b32 s94, v241, 51
	v_readlane_b32 s95, v241, 52
	v_readlane_b32 s81, v241, 38
	v_readlane_b32 s82, v241, 39
	v_readlane_b32 s83, v241, 40
	v_readlane_b32 s84, v241, 41
	v_readlane_b32 s85, v241, 42
	v_readlane_b32 s86, v241, 43
	v_readlane_b32 s87, v241, 44
	v_readlane_b32 s88, v241, 45
	v_readlane_b32 s89, v241, 46
	v_readlane_b32 s90, v241, 47
	v_readlane_b32 s91, v241, 48
.LBB0_1475:
	s_or_b64 exec, exec, s[58:59]
	v_ashrrev_i32_e32 v33, 31, v32
	v_lshlrev_b64 v[36:37], 11, v[32:33]
	s_mov_b64 s[58:59], 0x2000
	v_lshl_add_u64 v[36:37], v[36:37], 0, s[58:59]
	v_lshlrev_b64 v[32:33], 8, v[32:33]
	v_cndmask_b32_e64 v33, v37, v33, s[38:39]
	v_cndmask_b32_e64 v32, v36, v32, s[38:39]
	v_lshlrev_b64 v[32:33], 11, v[32:33]
	v_lshl_add_u64 v[36:37], s[68:69], 0, v[32:33]
	v_lshlrev_b32_e32 v64, 8, v34
	v_lshl_add_u64 v[38:39], s[48:49], 0, v[32:33]
	v_lshl_add_u64 v[34:35], v[36:37], 0, v[64:65]
	v_lshl_add_u64 v[36:37], s[46:47], 0, v[32:33]
	v_lshl_add_u64 v[38:39], v[38:39], 0, v[64:65]
	v_lshlrev_b64 v[40:41], 1, v[80:81]
	v_lshl_add_u64 v[36:37], v[36:37], 0, v[64:65]
	v_lshl_add_u64 v[38:39], v[38:39], 0, v[40:41]
	s_waitcnt vmcnt(0)
	v_mov_b32_e32 v69, v65
	v_mov_b32_e32 v71, v65
	v_lshl_add_u64 v[34:35], v[34:35], 0, v[68:69]
	v_lshl_add_u64 v[36:37], v[36:37], 0, v[68:69]
	v_lshl_add_u64 v[38:39], v[38:39], 0, v[70:71]
	v_mov_b64_e32 v[42:43], v[34:35]
	v_mov_b64_e32 v[44:45], v[38:39]
	v_mov_b64_e32 v[46:47], v[36:37]
	global_load_dword v69, v[42:43], off
	global_load_dword v71, v[42:43], off offset:2048
	global_load_dword v75, v[46:47], off
	global_load_dword v77, v[46:47], off offset:2048
	v_add_co_u32_e32 v48, vcc, s67, v42
	v_lshl_add_u64 v[32:33], s[50:51], 0, v[32:33]
	s_nop 0
	v_addc_co_u32_e32 v49, vcc, 0, v43, vcc
	v_add_co_u32_e32 v50, vcc, s67, v46
	v_lshl_add_u64 v[32:33], v[32:33], 0, v[64:65]
	s_nop 0
	v_addc_co_u32_e32 v51, vcc, 0, v47, vcc
	global_load_dword v79, v[48:49], off
	global_load_dword v119, v[48:49], off offset:2048
	global_load_dword v120, v[50:51], off
	global_load_dword v121, v[50:51], off offset:2048
	v_add_co_u32_e32 v48, vcc, s62, v42
	v_lshl_add_u64 v[32:33], v[32:33], 0, v[40:41]
	s_nop 0
	v_addc_co_u32_e32 v49, vcc, 0, v43, vcc
	v_add_co_u32_e32 v50, vcc, s62, v46
	v_mov_b32_e32 v73, v65
	s_nop 0
	v_addc_co_u32_e32 v51, vcc, 0, v47, vcc
	global_load_dword v122, v[48:49], off
	global_load_dword v123, v[48:49], off offset:2048
	global_load_dword v124, v[50:51], off
	global_load_dword v125, v[50:51], off offset:2048
	v_add_co_u32_e32 v48, vcc, s72, v42
	v_cndmask_b32_e64 v132, 32, 4, s[38:39]
	s_nop 0
	v_addc_co_u32_e32 v49, vcc, 0, v43, vcc
	v_add_co_u32_e32 v50, vcc, s72, v46
	s_mov_b32 s75, 0
	s_nop 0
	v_addc_co_u32_e32 v51, vcc, 0, v47, vcc
	global_load_dword v126, v[48:49], off
	global_load_dword v127, v[48:49], off offset:2048
	global_load_dword v128, v[50:51], off
	global_load_dword v129, v[50:51], off offset:2048
	v_add_co_u32_e32 v48, vcc, s63, v42
	v_lshl_add_u64 v[84:85], v[32:33], 0, v[72:73]
	s_nop 0
	v_addc_co_u32_e32 v49, vcc, 0, v43, vcc
	v_add_co_u32_e32 v50, vcc, s63, v46
	v_lshl_add_u64 v[86:87], v[38:39], 0, s[56:57]
	s_nop 0
	v_addc_co_u32_e32 v51, vcc, 0, v47, vcc
	global_load_dword v130, v[48:49], off
	global_load_dword v131, v[48:49], off offset:2048
	global_load_dword v133, v[50:51], off
	global_load_dword v134, v[50:51], off offset:2048
	v_add_co_u32_e32 v48, vcc, s73, v42
	v_lshl_add_u64 v[88:89], v[36:37], 0, s[56:57]
	s_nop 0
	v_addc_co_u32_e32 v49, vcc, 0, v43, vcc
	v_add_co_u32_e32 v50, vcc, s73, v46
	v_lshl_add_u64 v[90:91], v[34:35], 0, s[56:57]
	s_nop 0
	v_addc_co_u32_e32 v51, vcc, 0, v47, vcc
	global_load_dword v135, v[48:49], off
	global_load_dword v136, v[48:49], off offset:2048
	global_load_dword v137, v[50:51], off
	global_load_dword v138, v[50:51], off offset:2048
	v_add_co_u32_e32 v48, vcc, s64, v42
	s_mov_b64 s[58:59], 0
	s_nop 0
	v_addc_co_u32_e32 v49, vcc, 0, v43, vcc
	v_add_co_u32_e32 v50, vcc, s64, v46
	v_mov_b32_e32 v64, v106
	s_nop 0
	v_addc_co_u32_e32 v51, vcc, 0, v47, vcc
	v_add_co_u32_e32 v42, vcc, s74, v42
	global_load_dword v139, v[48:49], off
	global_load_dword v140, v[48:49], off offset:2048
	global_load_dword v141, v[50:51], off
	global_load_dword v142, v[50:51], off offset:2048
	v_addc_co_u32_e32 v43, vcc, 0, v43, vcc
	v_add_co_u32_e32 v46, vcc, s74, v46
	s_nop 1
	v_addc_co_u32_e32 v47, vcc, 0, v47, vcc
	global_load_dword v143, v[42:43], off
	global_load_dword v144, v[42:43], off offset:2048
	global_load_dword v145, v[46:47], off
	global_load_dword v146, v[46:47], off offset:2048
	global_load_dword v147, v[44:45], off
	global_load_dword v148, v[44:45], off offset:2048
	v_add_co_u32_e32 v42, vcc, s67, v44
	s_nop 1
	v_addc_co_u32_e32 v43, vcc, 0, v45, vcc
	v_add_co_u32_e32 v46, vcc, s62, v44
	s_nop 1
	v_addc_co_u32_e32 v47, vcc, 0, v45, vcc
	v_add_co_u32_e32 v44, vcc, 0x3000, v44
	s_nop 1
	v_addc_co_u32_e32 v45, vcc, 0, v45, vcc
	global_load_dword v149, v[42:43], off
	global_load_dword v150, v[42:43], off offset:2048
	global_load_dword v151, v[46:47], off
	global_load_dword v152, v[46:47], off offset:2048
	global_load_dword v153, v[44:45], off
	global_load_dword v154, v[44:45], off offset:2048
	s_waitcnt vmcnt(0)
	s_branch .LBB0_1477

.LBB0_1477:
	s_waitcnt vmcnt(4) lgkmcnt(0)
	v_lshlrev_b32_e32 v34, 16, v75
	v_and_b32_e32 v35, 0xffff0000, v75
	v_lshlrev_b32_e32 v38, 16, v77
	v_and_b32_e32 v39, 0xffff0000, v77
	v_pk_add_f32 v[32:33], v[34:35], 0 op_sel_hi:[1,0]
	v_lshlrev_b32_e32 v40, 16, v120
	v_and_b32_e32 v41, 0xffff0000, v120
	v_pk_add_f32 v[32:33], v[32:33], v[38:39]
	v_lshlrev_b32_e32 v42, 16, v121
	v_and_b32_e32 v43, 0xffff0000, v121
	v_pk_add_f32 v[32:33], v[32:33], v[40:41]
	v_lshlrev_b32_e32 v44, 16, v124
	v_and_b32_e32 v45, 0xffff0000, v124
	v_pk_add_f32 v[32:33], v[32:33], v[42:43]
	v_lshlrev_b32_e32 v46, 16, v125
	v_pk_add_f32 v[32:33], v[32:33], v[44:45]
	v_and_b32_e32 v47, 0xffff0000, v125
	v_lshlrev_b32_e32 v48, 16, v128
	v_and_b32_e32 v49, 0xffff0000, v128
	v_pk_add_f32 v[32:33], v[32:33], v[46:47]
	v_lshlrev_b32_e32 v50, 16, v129
	v_and_b32_e32 v51, 0xffff0000, v129
	v_pk_add_f32 v[32:33], v[32:33], v[48:49]
	v_lshlrev_b32_e32 v52, 16, v133
	v_and_b32_e32 v53, 0xffff0000, v133
	v_pk_add_f32 v[32:33], v[32:33], v[50:51]
	v_lshlrev_b32_e32 v54, 16, v134
	v_and_b32_e32 v55, 0xffff0000, v134
	v_pk_add_f32 v[32:33], v[32:33], v[52:53]
	v_lshlrev_b32_e32 v56, 16, v137
	v_and_b32_e32 v57, 0xffff0000, v137
	v_pk_add_f32 v[32:33], v[32:33], v[54:55]
	v_lshlrev_b32_e32 v60, 16, v138
	v_and_b32_e32 v61, 0xffff0000, v138
	v_pk_add_f32 v[32:33], v[32:33], v[56:57]
	v_lshlrev_b32_e32 v92, 16, v141
	v_and_b32_e32 v93, 0xffff0000, v141
	v_pk_add_f32 v[32:33], v[32:33], v[60:61]
	v_lshlrev_b32_e32 v94, 16, v142
	v_and_b32_e32 v95, 0xffff0000, v142
	v_pk_add_f32 v[32:33], v[32:33], v[92:93]
	v_lshlrev_b32_e32 v62, 16, v145
	v_and_b32_e32 v63, 0xffff0000, v145
	v_pk_add_f32 v[32:33], v[32:33], v[94:95]
	v_lshlrev_b32_e32 v58, 16, v146
	v_and_b32_e32 v59, 0xffff0000, v146
	v_pk_add_f32 v[32:33], v[32:33], v[62:63]
	v_mov_b32_e32 v162, v34
	v_pk_add_f32 v[32:33], v[32:33], v[58:59]
	ds_write_b64 v96, v[32:33]
	s_waitcnt lgkmcnt(0)
	s_barrier
	ds_read_b64 v[32:33], v98
	ds_read_b64 v[36:37], v99
	ds_read_b64 v[156:157], v67
	ds_read_b64 v[158:159], v97
	v_exp_f32_e32 v160, v34
	v_exp_f32_e32 v161, v35
	s_waitcnt lgkmcnt(2)
	v_add_f32_e32 v73, v32, v36
	v_add_f32_e32 v155, v33, v37
	s_waitcnt lgkmcnt(1)
	v_cndmask_b32_e64 v36, v156, 0, s[44:45]
	s_waitcnt lgkmcnt(0)
	v_cndmask_b32_e64 v37, 0, v158, s[0:1]
	v_add_f32_e32 v36, v36, v37
	v_cndmask_b32_e64 v32, 0, v32, s[2:3]
	v_add_f32_e32 v32, v36, v32
	v_cndmask_b32_e64 v36, v157, 0, s[44:45]
	v_cndmask_b32_e64 v37, 0, v159, s[0:1]
	v_add_f32_e32 v36, v36, v37
	v_cndmask_b32_e64 v33, 0, v33, s[2:3]
	v_add_f32_e32 v36, v36, v33
	v_mov_b32_e32 v33, v156
	v_mov_b32_e32 v163, v158
	v_mov_b32_e32 v37, v157
	v_mov_b32_e32 v158, v35
	v_pk_add_f32 v[32:33], v[32:33], v[162:163]
	v_pk_add_f32 v[34:35], v[36:37], v[158:159]
	v_sub_f32_e32 v156, v32, v33
	v_sub_f32_e32 v157, v34, v35
	v_exp_f32_e32 v156, v156
	v_exp_f32_e32 v157, v157
	v_sub_f32_e32 v158, v33, v32
	v_sub_f32_e32 v159, v35, v34
	v_exp_f32_e32 v158, v158
	v_exp_f32_e32 v159, v159
	v_lshlrev_b32_e32 v36, 16, v69
	v_and_b32_e32 v37, 0xffff0000, v69
	v_pk_mul_f32 v[36:37], v[156:157], v[36:37]
	v_add_f32_e32 v32, v32, v38
	v_cvt_pk_bf16_f32 v162, v36, v37
	v_pk_add_f32 v[36:37], v[160:161], 1.0 op_sel_hi:[1,0] neg_lo:[1,0] neg_hi:[1,0]
	v_exp_f32_e32 v156, v38
	v_sub_f32_e32 v38, v32, v33
	v_add_f32_e32 v34, v34, v39
	v_pk_mul_f32 v[36:37], v[36:37], v[158:159]
	v_exp_f32_e32 v158, v38
	v_sub_f32_e32 v38, v34, v35
	v_exp_f32_e32 v159, v38
	v_exp_f32_e32 v157, v39
	v_lshlrev_b32_e32 v38, 16, v71
	v_and_b32_e32 v39, 0xffff0000, v71
	v_pk_mul_f32 v[38:39], v[158:159], v[38:39]
	v_sub_f32_e32 v158, v33, v32
	v_sub_f32_e32 v159, v35, v34
	v_exp_f32_e32 v158, v158
	v_exp_f32_e32 v159, v159
	v_cvt_pk_bf16_f32 v38, v38, v39
	ds_write2_b32 v111, v162, v38 offset1:68
	v_pk_add_f32 v[38:39], v[156:157], 1.0 op_sel_hi:[1,0] neg_lo:[1,0] neg_hi:[1,0]
	v_cvt_pk_bf16_f32 v160, v36, v37
	v_pk_mul_f32 v[38:39], v[38:39], v[158:159]
	v_add_u32_e32 v162, 0x4400, v111
	v_cvt_pk_bf16_f32 v156, v38, v39
	v_add_f32_e32 v32, v32, v40
	v_add_f32_e32 v34, v34, v41
	ds_write2_b32 v162, v160, v156 offset1:68
	v_exp_f32_e32 v156, v40
	v_exp_f32_e32 v157, v41
	v_sub_f32_e32 v40, v32, v33
	v_sub_f32_e32 v41, v34, v35
	v_exp_f32_e32 v40, v40
	v_exp_f32_e32 v41, v41
	v_lshlrev_b32_e32 v158, 16, v79
	v_and_b32_e32 v159, 0xffff0000, v79
	v_sub_f32_e32 v160, v33, v32
	v_pk_mul_f32 v[40:41], v[40:41], v[158:159]
	v_add_f32_e32 v32, v32, v42
	v_sub_f32_e32 v161, v35, v34
	v_cvt_pk_bf16_f32 v163, v40, v41
	v_pk_add_f32 v[40:41], v[156:157], 1.0 op_sel_hi:[1,0] neg_lo:[1,0] neg_hi:[1,0]
	v_exp_f32_e32 v156, v42
	v_sub_f32_e32 v42, v32, v33
	v_add_f32_e32 v34, v34, v43
	v_exp_f32_e32 v158, v42
	v_sub_f32_e32 v42, v34, v35
	v_exp_f32_e32 v159, v42
	v_exp_f32_e32 v157, v43
	v_lshlrev_b32_e32 v42, 16, v119
	v_and_b32_e32 v43, 0xffff0000, v119
	v_pk_mul_f32 v[42:43], v[158:159], v[42:43]
	v_sub_f32_e32 v158, v33, v32
	v_sub_f32_e32 v159, v35, v34
	v_exp_f32_e32 v160, v160
	v_exp_f32_e32 v161, v161
	v_exp_f32_e32 v158, v158
	v_exp_f32_e32 v159, v159
	v_cvt_pk_bf16_f32 v42, v42, v43
	ds_write2_b32 v111, v163, v42 offset0:136 offset1:204
	v_pk_add_f32 v[42:43], v[156:157], 1.0 op_sel_hi:[1,0] neg_lo:[1,0] neg_hi:[1,0]
	v_add_f32_e32 v32, v32, v44
	v_add_f32_e32 v34, v34, v45
	v_pk_mul_f32 v[40:41], v[40:41], v[160:161]
	v_pk_mul_f32 v[42:43], v[42:43], v[158:159]
	v_sub_f32_e32 v158, v32, v33
	v_sub_f32_e32 v159, v34, v35
	v_cvt_pk_bf16_f32 v160, v40, v41
	v_cvt_pk_bf16_f32 v156, v42, v43
	v_exp_f32_e32 v158, v158
	v_exp_f32_e32 v159, v159
	ds_write2_b32 v162, v160, v156 offset0:136 offset1:204
	v_exp_f32_e32 v156, v44
	v_exp_f32_e32 v157, v45
	v_lshlrev_b32_e32 v44, 16, v122
	v_and_b32_e32 v45, 0xffff0000, v122
	v_sub_f32_e32 v160, v33, v32
	v_pk_mul_f32 v[44:45], v[158:159], v[44:45]
	v_add_f32_e32 v32, v32, v46
	v_sub_f32_e32 v161, v35, v34
	v_cvt_pk_bf16_f32 v162, v44, v45
	v_pk_add_f32 v[44:45], v[156:157], 1.0 op_sel_hi:[1,0] neg_lo:[1,0] neg_hi:[1,0]
	v_exp_f32_e32 v156, v46
	v_add_f32_e32 v34, v34, v47
	v_sub_f32_e32 v46, v32, v33
	v_exp_f32_e32 v158, v46
	v_sub_f32_e32 v46, v34, v35
	v_exp_f32_e32 v159, v46
	v_exp_f32_e32 v157, v47
	v_lshlrev_b32_e32 v46, 16, v123
	v_and_b32_e32 v47, 0xffff0000, v123
	v_pk_mul_f32 v[46:47], v[158:159], v[46:47]
	v_exp_f32_e32 v160, v160
	v_cvt_pk_bf16_f32 v158, v46, v47
	v_sub_f32_e32 v46, v33, v32
	v_sub_f32_e32 v47, v35, v34
	v_exp_f32_e32 v161, v161
	v_exp_f32_e32 v46, v46
	v_exp_f32_e32 v47, v47
	v_add_u32_e32 v163, 0x400, v111
	v_pk_add_f32 v[156:157], v[156:157], 1.0 op_sel_hi:[1,0] neg_lo:[1,0] neg_hi:[1,0]
	v_add_f32_e32 v32, v32, v48
	v_add_f32_e32 v34, v34, v49
	v_pk_mul_f32 v[44:45], v[44:45], v[160:161]
	ds_write2_b32 v163, v162, v158 offset0:16 offset1:84
	v_pk_mul_f32 v[46:47], v[156:157], v[46:47]
	v_sub_f32_e32 v158, v32, v33
	v_sub_f32_e32 v159, v34, v35
	v_cvt_pk_bf16_f32 v160, v44, v45
	v_cvt_pk_bf16_f32 v156, v46, v47
	v_add_u32_e32 v162, 0x4800, v111
	v_exp_f32_e32 v158, v158
	v_exp_f32_e32 v159, v159
	ds_write2_b32 v162, v160, v156 offset0:16 offset1:84
	v_exp_f32_e32 v156, v48
	v_exp_f32_e32 v157, v49
	v_lshlrev_b32_e32 v48, 16, v126
	v_and_b32_e32 v49, 0xffff0000, v126
	v_sub_f32_e32 v160, v33, v32
	v_pk_mul_f32 v[48:49], v[158:159], v[48:49]
	v_add_f32_e32 v32, v32, v50
	v_sub_f32_e32 v161, v35, v34
	v_cvt_pk_bf16_f32 v164, v48, v49
	v_pk_add_f32 v[48:49], v[156:157], 1.0 op_sel_hi:[1,0] neg_lo:[1,0] neg_hi:[1,0]
	v_exp_f32_e32 v156, v50
	v_add_f32_e32 v34, v34, v51
	v_sub_f32_e32 v50, v32, v33
	v_exp_f32_e32 v158, v50
	v_sub_f32_e32 v50, v34, v35
	v_exp_f32_e32 v159, v50
	v_exp_f32_e32 v157, v51
	v_lshlrev_b32_e32 v50, 16, v127
	v_and_b32_e32 v51, 0xffff0000, v127
	v_pk_mul_f32 v[50:51], v[158:159], v[50:51]
	v_sub_f32_e32 v158, v33, v32
	v_sub_f32_e32 v159, v35, v34
	v_exp_f32_e32 v160, v160
	v_exp_f32_e32 v161, v161
	v_exp_f32_e32 v158, v158
	v_exp_f32_e32 v159, v159
	v_cvt_pk_bf16_f32 v50, v50, v51
	ds_write2_b32 v163, v164, v50 offset0:152 offset1:220
	v_pk_add_f32 v[50:51], v[156:157], 1.0 op_sel_hi:[1,0] neg_lo:[1,0] neg_hi:[1,0]
	v_add_f32_e32 v32, v32, v52
	v_add_f32_e32 v34, v34, v53
	v_pk_mul_f32 v[48:49], v[48:49], v[160:161]
	v_pk_mul_f32 v[50:51], v[50:51], v[158:159]
	v_sub_f32_e32 v158, v32, v33
	v_sub_f32_e32 v159, v34, v35
	v_cvt_pk_bf16_f32 v160, v48, v49
	v_cvt_pk_bf16_f32 v156, v50, v51
	v_exp_f32_e32 v158, v158
	v_exp_f32_e32 v159, v159
	ds_write2_b32 v162, v160, v156 offset0:152 offset1:220
	v_exp_f32_e32 v156, v52
	v_exp_f32_e32 v157, v53
	v_lshlrev_b32_e32 v52, 16, v130
	v_and_b32_e32 v53, 0xffff0000, v130
	v_sub_f32_e32 v160, v33, v32
	v_pk_mul_f32 v[52:53], v[158:159], v[52:53]
	v_add_f32_e32 v32, v32, v54
	v_sub_f32_e32 v161, v35, v34
	v_cvt_pk_bf16_f32 v162, v52, v53
	v_pk_add_f32 v[52:53], v[156:157], 1.0 op_sel_hi:[1,0] neg_lo:[1,0] neg_hi:[1,0]
	v_exp_f32_e32 v156, v54
	v_add_f32_e32 v34, v34, v55
	v_sub_f32_e32 v54, v32, v33
	v_exp_f32_e32 v158, v54
	v_sub_f32_e32 v54, v34, v35
	v_exp_f32_e32 v159, v54
	v_exp_f32_e32 v157, v55
	v_lshlrev_b32_e32 v54, 16, v131
	v_and_b32_e32 v55, 0xffff0000, v131
	v_pk_mul_f32 v[54:55], v[158:159], v[54:55]
	v_exp_f32_e32 v160, v160
	v_cvt_pk_bf16_f32 v158, v54, v55
	v_sub_f32_e32 v54, v33, v32
	v_sub_f32_e32 v55, v35, v34
	v_exp_f32_e32 v161, v161
	v_exp_f32_e32 v54, v54
	v_exp_f32_e32 v55, v55
	v_add_u32_e32 v163, 0x800, v111
	v_pk_add_f32 v[156:157], v[156:157], 1.0 op_sel_hi:[1,0] neg_lo:[1,0] neg_hi:[1,0]
	v_add_f32_e32 v32, v32, v56
	v_add_f32_e32 v34, v34, v57
	v_pk_mul_f32 v[52:53], v[52:53], v[160:161]
	ds_write2_b32 v163, v162, v158 offset0:32 offset1:100
	v_pk_mul_f32 v[54:55], v[156:157], v[54:55]
	v_sub_f32_e32 v158, v32, v33
	v_sub_f32_e32 v159, v34, v35
	v_cvt_pk_bf16_f32 v160, v52, v53
	v_cvt_pk_bf16_f32 v156, v54, v55
	v_add_u32_e32 v162, 0x4c00, v111
	v_exp_f32_e32 v158, v158
	v_exp_f32_e32 v159, v159
	ds_write2_b32 v162, v160, v156 offset0:32 offset1:100
	v_exp_f32_e32 v156, v56
	v_exp_f32_e32 v157, v57
	v_lshlrev_b32_e32 v56, 16, v135
	v_and_b32_e32 v57, 0xffff0000, v135
	v_sub_f32_e32 v160, v33, v32
	v_pk_mul_f32 v[56:57], v[158:159], v[56:57]
	v_add_f32_e32 v32, v32, v60
	v_sub_f32_e32 v161, v35, v34
	v_cvt_pk_bf16_f32 v164, v56, v57
	v_pk_add_f32 v[56:57], v[156:157], 1.0 op_sel_hi:[1,0] neg_lo:[1,0] neg_hi:[1,0]
	v_exp_f32_e32 v156, v60
	v_add_f32_e32 v34, v34, v61
	v_sub_f32_e32 v60, v32, v33
	v_exp_f32_e32 v158, v60
	v_sub_f32_e32 v60, v34, v35
	v_exp_f32_e32 v159, v60
	v_exp_f32_e32 v157, v61
	v_lshlrev_b32_e32 v60, 16, v136
	v_and_b32_e32 v61, 0xffff0000, v136
	v_pk_mul_f32 v[60:61], v[158:159], v[60:61]
	v_sub_f32_e32 v158, v33, v32
	v_sub_f32_e32 v159, v35, v34
	v_exp_f32_e32 v160, v160
	v_exp_f32_e32 v161, v161
	v_exp_f32_e32 v158, v158
	v_exp_f32_e32 v159, v159
	v_cvt_pk_bf16_f32 v60, v60, v61
	ds_write2_b32 v163, v164, v60 offset0:168 offset1:236
	v_pk_add_f32 v[60:61], v[156:157], 1.0 op_sel_hi:[1,0] neg_lo:[1,0] neg_hi:[1,0]
	v_add_f32_e32 v32, v32, v92
	v_add_f32_e32 v34, v34, v93
	v_pk_mul_f32 v[56:57], v[56:57], v[160:161]
	v_pk_mul_f32 v[60:61], v[60:61], v[158:159]
	v_sub_f32_e32 v158, v32, v33
	v_sub_f32_e32 v159, v34, v35
	v_cvt_pk_bf16_f32 v160, v56, v57
	v_cvt_pk_bf16_f32 v156, v60, v61
	v_exp_f32_e32 v158, v158
	v_exp_f32_e32 v159, v159
	ds_write2_b32 v162, v160, v156 offset0:168 offset1:236
	v_exp_f32_e32 v156, v92
	v_exp_f32_e32 v157, v93
	v_lshlrev_b32_e32 v92, 16, v139
	v_and_b32_e32 v93, 0xffff0000, v139
	v_sub_f32_e32 v160, v33, v32
	v_pk_mul_f32 v[92:93], v[158:159], v[92:93]
	v_add_f32_e32 v32, v32, v94
	v_sub_f32_e32 v161, v35, v34
	v_cvt_pk_bf16_f32 v162, v92, v93
	v_pk_add_f32 v[92:93], v[156:157], 1.0 op_sel_hi:[1,0] neg_lo:[1,0] neg_hi:[1,0]
	v_exp_f32_e32 v156, v94
	v_add_f32_e32 v34, v34, v95
	v_sub_f32_e32 v94, v32, v33
	v_exp_f32_e32 v158, v94
	v_sub_f32_e32 v94, v34, v35
	v_exp_f32_e32 v159, v94
	v_exp_f32_e32 v157, v95
	v_lshlrev_b32_e32 v94, 16, v140
	v_and_b32_e32 v95, 0xffff0000, v140
	v_pk_mul_f32 v[94:95], v[158:159], v[94:95]
	v_exp_f32_e32 v160, v160
	v_cvt_pk_bf16_f32 v158, v94, v95
	v_sub_f32_e32 v94, v33, v32
	v_sub_f32_e32 v95, v35, v34
	v_exp_f32_e32 v161, v161
	v_exp_f32_e32 v94, v94
	v_exp_f32_e32 v95, v95
	v_add_u32_e32 v163, 0xc00, v111
	v_pk_add_f32 v[156:157], v[156:157], 1.0 op_sel_hi:[1,0] neg_lo:[1,0] neg_hi:[1,0]
	v_add_f32_e32 v32, v32, v62
	v_add_f32_e32 v34, v34, v63
	v_pk_mul_f32 v[92:93], v[92:93], v[160:161]
	ds_write2_b32 v163, v162, v158 offset0:48 offset1:116
	v_pk_mul_f32 v[94:95], v[156:157], v[94:95]
	v_sub_f32_e32 v158, v32, v33
	v_sub_f32_e32 v159, v34, v35
	v_cvt_pk_bf16_f32 v160, v92, v93
	v_cvt_pk_bf16_f32 v156, v94, v95
	v_add_u32_e32 v162, 0x5000, v111
	v_exp_f32_e32 v158, v158
	v_exp_f32_e32 v159, v159
	ds_write2_b32 v162, v160, v156 offset0:48 offset1:116
	v_exp_f32_e32 v156, v62
	v_exp_f32_e32 v157, v63
	v_lshlrev_b32_e32 v62, 16, v143
	v_and_b32_e32 v63, 0xffff0000, v143
	v_sub_f32_e32 v160, v33, v32
	v_pk_mul_f32 v[62:63], v[158:159], v[62:63]
	v_add_f32_e32 v32, v32, v58
	v_sub_f32_e32 v161, v35, v34
	v_cvt_pk_bf16_f32 v164, v62, v63
	v_pk_add_f32 v[62:63], v[156:157], 1.0 op_sel_hi:[1,0] neg_lo:[1,0] neg_hi:[1,0]
	v_exp_f32_e32 v156, v58
	v_add_f32_e32 v34, v34, v59
	v_sub_f32_e32 v58, v32, v33
	v_exp_f32_e32 v158, v58
	v_sub_f32_e32 v58, v34, v35
	v_exp_f32_e32 v159, v58
	v_exp_f32_e32 v157, v59
	v_lshlrev_b32_e32 v58, 16, v144
	v_and_b32_e32 v59, 0xffff0000, v144
	v_sub_f32_e32 v32, v33, v32
	v_pk_mul_f32 v[58:59], v[158:159], v[58:59]
	v_exp_f32_e32 v158, v32
	v_sub_f32_e32 v32, v35, v34
	v_exp_f32_e32 v160, v160
	v_exp_f32_e32 v161, v161
	v_exp_f32_e32 v159, v32
	v_cvt_pk_bf16_f32 v32, v58, v59
	v_pk_add_f32 v[58:59], v[156:157], 1.0 op_sel_hi:[1,0] neg_lo:[1,0] neg_hi:[1,0]
	v_pk_mul_f32 v[62:63], v[62:63], v[160:161]
	v_pk_mul_f32 v[58:59], v[58:59], v[158:159]
	v_add_f32_e32 v73, v33, v73
	v_add_f32_e32 v155, v35, v155
	v_cvt_pk_bf16_f32 v160, v62, v63
	ds_write2_b32 v163, v164, v32 offset0:184 offset1:252
	v_cvt_pk_bf16_f32 v32, v58, v59
	ds_write2_b32 v162, v160, v32 offset0:184 offset1:252
	s_and_saveexec_b64 s[60:61], s[44:45]
	s_cbranch_execz .LBB0_1479
	v_exp_f32_e32 v159, v155
	v_exp_f32_e32 v158, v73
	v_exp_f32_e32 v157, v35
	v_exp_f32_e32 v156, v33
	ds_write_b64 v102, v[158:159]
	ds_write_b64 v103, v[156:157]
.LBB0_1479:
	s_or_b64 exec, exec, s[60:61]
	v_lshlrev_b32_e32 v32, 16, v150
	v_lshlrev_b32_e32 v34, 16, v148
	v_lshlrev_b32_e32 v158, 16, v154
	v_lshlrev_b32_e32 v160, 16, v152
	v_or_b32_sdwa v157, v149, v32 dst_sel:DWORD dst_unused:UNUSED_PAD src0_sel:WORD_0 src1_sel:DWORD
	v_or_b32_sdwa v156, v147, v34 dst_sel:DWORD dst_unused:UNUSED_PAD src0_sel:WORD_0 src1_sel:DWORD
	v_or_b32_sdwa v159, v153, v158 dst_sel:DWORD dst_unused:UNUSED_PAD src0_sel:WORD_0 src1_sel:DWORD
	v_or_b32_sdwa v158, v151, v160 dst_sel:DWORD dst_unused:UNUSED_PAD src0_sel:WORD_0 src1_sel:DWORD
	v_and_b32_e32 v32, 0xffff0000, v150
	v_and_b32_e32 v34, 0xffff0000, v148
	ds_write_b128 v112, v[156:159] offset:35840
	v_or_b32_sdwa v157, v149, v32 dst_sel:DWORD dst_unused:UNUSED_PAD src0_sel:WORD_1 src1_sel:DWORD
	v_or_b32_sdwa v156, v147, v34 dst_sel:DWORD dst_unused:UNUSED_PAD src0_sel:WORD_1 src1_sel:DWORD
	v_and_b32_e32 v32, 0xffff0000, v154
	v_and_b32_e32 v34, 0xffff0000, v152
	s_add_i32 s75, s75, 1
	v_or_b32_sdwa v159, v153, v32 dst_sel:DWORD dst_unused:UNUSED_PAD src0_sel:WORD_1 src1_sel:DWORD
	v_or_b32_sdwa v158, v151, v34 dst_sel:DWORD dst_unused:UNUSED_PAD src0_sel:WORD_1 src1_sel:DWORD
	v_cmp_lt_u32_e32 vcc, s75, v132
	ds_write_b128 v112, v[156:159] offset:35984
	s_and_saveexec_b64 s[60:61], vcc
	s_cbranch_execz .LBB0_1476
	v_mov_b64_e32 v[144:145], v[90:91]
	v_mov_b64_e32 v[150:151], v[86:87]
	v_mov_b64_e32 v[146:147], v[88:89]
	global_load_dword v69, v[144:145], off
	global_load_dword v71, v[144:145], off offset:2048
	global_load_dword v75, v[146:147], off
	global_load_dword v77, v[146:147], off offset:2048
	v_add_co_u32_e32 v120, vcc, 0x1000, v144
	s_nop 1
	v_addc_co_u32_e32 v121, vcc, 0, v145, vcc
	v_add_co_u32_e32 v122, vcc, 0x1000, v146
	s_nop 1
	v_addc_co_u32_e32 v123, vcc, 0, v147, vcc
	v_add_co_u32_e32 v124, vcc, s62, v144
	global_load_dword v79, v[120:121], off
	global_load_dword v119, v[120:121], off offset:2048
	s_nop 0
	global_load_dword v120, v[122:123], off
	global_load_dword v121, v[122:123], off offset:2048
	v_addc_co_u32_e32 v125, vcc, 0, v145, vcc
	v_add_co_u32_e32 v126, vcc, s62, v146
	s_nop 1
	v_addc_co_u32_e32 v127, vcc, 0, v147, vcc
	v_add_co_u32_e32 v128, vcc, s72, v144
	global_load_dword v122, v[124:125], off
	global_load_dword v123, v[124:125], off offset:2048
	s_nop 0
	global_load_dword v124, v[126:127], off
	global_load_dword v125, v[126:127], off offset:2048
	v_addc_co_u32_e32 v129, vcc, 0, v145, vcc
	v_add_co_u32_e32 v130, vcc, s72, v146
	s_nop 1
	v_addc_co_u32_e32 v131, vcc, 0, v147, vcc
	v_add_co_u32_e32 v134, vcc, s63, v144
	global_load_dword v126, v[128:129], off
	global_load_dword v127, v[128:129], off offset:2048
	s_nop 0
	global_load_dword v128, v[130:131], off
	global_load_dword v129, v[130:131], off offset:2048
	v_addc_co_u32_e32 v135, vcc, 0, v145, vcc
	v_add_co_u32_e32 v136, vcc, s63, v146
	s_nop 1
	v_addc_co_u32_e32 v137, vcc, 0, v147, vcc
	global_load_dword v130, v[134:135], off
	global_load_dword v131, v[134:135], off offset:2048
	global_load_dword v133, v[136:137], off
	s_nop 0
	global_load_dword v134, v[136:137], off offset:2048
	v_add_co_u32_e32 v136, vcc, s73, v144
	s_nop 1
	v_addc_co_u32_e32 v137, vcc, 0, v145, vcc
	v_add_co_u32_e32 v138, vcc, s73, v146
	s_nop 1
	v_addc_co_u32_e32 v139, vcc, 0, v147, vcc
	v_add_co_u32_e32 v140, vcc, s64, v144
	global_load_dword v135, v[136:137], off
	s_nop 0
	global_load_dword v136, v[136:137], off offset:2048
	s_nop 0
	global_load_dword v137, v[138:139], off
	s_nop 0
	global_load_dword v138, v[138:139], off offset:2048
	v_addc_co_u32_e32 v141, vcc, 0, v145, vcc
	v_add_co_u32_e32 v142, vcc, s64, v146
	s_nop 1
	v_addc_co_u32_e32 v143, vcc, 0, v147, vcc
	v_add_co_u32_e32 v144, vcc, 0x7000, v144
	global_load_dword v139, v[140:141], off
	s_nop 0
	global_load_dword v140, v[140:141], off offset:2048
	s_nop 0
	global_load_dword v141, v[142:143], off
	s_nop 0
	global_load_dword v142, v[142:143], off offset:2048
	v_addc_co_u32_e32 v145, vcc, 0, v145, vcc
	v_add_co_u32_e32 v146, vcc, 0x7000, v146
	s_nop 1
	v_addc_co_u32_e32 v147, vcc, 0, v147, vcc
	v_add_co_u32_e32 v152, vcc, 0x1000, v150
	global_load_dword v143, v[144:145], off
	s_nop 0
	global_load_dword v144, v[144:145], off offset:2048
	s_nop 0
	global_load_dword v145, v[146:147], off
	s_nop 0
	global_load_dword v146, v[146:147], off offset:2048
	s_nop 0
	global_load_dword v147, v[150:151], off
	global_load_dword v148, v[150:151], off offset:2048
	v_addc_co_u32_e32 v153, vcc, 0, v151, vcc
	v_add_co_u32_e32 v156, vcc, 0x2000, v150
	s_nop 1
	v_addc_co_u32_e32 v157, vcc, 0, v151, vcc
	v_add_co_u32_e32 v158, vcc, 0x3000, v150
	s_nop 1
	v_addc_co_u32_e32 v159, vcc, 0, v151, vcc
	global_load_dword v149, v[152:153], off
	global_load_dword v150, v[152:153], off offset:2048
	global_load_dword v151, v[156:157], off
	s_nop 0
	global_load_dword v152, v[156:157], off offset:2048
	global_load_dword v153, v[158:159], off
	global_load_dword v154, v[158:159], off offset:2048
	s_branch .LBB0_1476
.LBB0_1481:
	s_or_b64 exec, exec, s[58:59]
	s_and_saveexec_b64 s[58:59], s[38:39]
	s_cbranch_execz .LBB0_1472
	v_lshlrev_b64 v[32:33], 16, v[82:83]
	v_lshl_add_u64 v[32:33], s[52:53], 0, v[32:33]
	v_lshl_add_u64 v[32:33], v[80:81], 2, v[32:33]
	s_waitcnt vmcnt(0)
	v_mov_b32_e32 v75, v65
	v_lshl_add_u64 v[32:33], v[32:33], 0, v[74:75]
	v_mov_b32_e32 v77, v65
	v_lshl_add_u64 v[32:33], v[32:33], 0, v[76:77]
	v_mov_b32_e32 v79, v65
	v_lshl_add_u64 v[32:33], v[32:33], 0, v[78:79]
	global_store_dword v[32:33], v12, off
	global_store_dword v[32:33], v13, off offset:512
	global_store_dword v[32:33], v14, off offset:1024
	global_store_dword v[32:33], v15, off offset:1536
	v_add_co_u32_e32 v12, vcc, s62, v32
	s_nop 1
	v_addc_co_u32_e32 v13, vcc, 0, v33, vcc
	global_store_dword v[12:13], v0, off
	global_store_dword v[12:13], v1, off offset:512
	global_store_dword v[12:13], v2, off offset:1024
	global_store_dword v[12:13], v3, off offset:1536
	v_add_co_u32_e32 v0, vcc, s63, v32
	s_nop 1
	v_addc_co_u32_e32 v1, vcc, 0, v33, vcc
	global_store_dword v[0:1], v8, off
	global_store_dword v[0:1], v9, off offset:512
	global_store_dword v[0:1], v10, off offset:1024
	global_store_dword v[0:1], v11, off offset:1536
	v_add_co_u32_e32 v0, vcc, s64, v32
	s_nop 1
	v_addc_co_u32_e32 v1, vcc, 0, v33, vcc
	global_store_dword v[0:1], v4, off
	global_store_dword v[0:1], v5, off offset:512
	global_store_dword v[0:1], v6, off offset:1024
	global_store_dword v[0:1], v7, off offset:1536
	v_add_co_u32_e32 v0, vcc, s65, v32
	s_nop 1
	v_addc_co_u32_e32 v1, vcc, 0, v33, vcc
	global_store_dword v[0:1], v20, off
	global_store_dword v[0:1], v21, off offset:512
	global_store_dword v[0:1], v22, off offset:1024
	global_store_dword v[0:1], v23, off offset:1536
	v_add_co_u32_e32 v0, vcc, s66, v32
	s_nop 1
	v_addc_co_u32_e32 v1, vcc, 0, v33, vcc
	global_store_dword v[0:1], v16, off
	global_store_dword v[0:1], v17, off offset:512
	global_store_dword v[0:1], v18, off offset:1024
	global_store_dword v[0:1], v19, off offset:1536
	v_add_co_u32_e32 v0, vcc, 0xc000, v32
	s_nop 1
	v_addc_co_u32_e32 v1, vcc, 0, v33, vcc
	global_store_dword v[0:1], v24, off
	global_store_dword v[0:1], v25, off offset:512
	global_store_dword v[0:1], v26, off offset:1024
	global_store_dword v[0:1], v27, off offset:1536
	v_add_co_u32_e32 v0, vcc, 0xe000, v32
	s_nop 1
	v_addc_co_u32_e32 v1, vcc, 0, v33, vcc
	global_store_dword v[0:1], v28, off
	global_store_dword v[0:1], v29, off offset:512
	global_store_dword v[0:1], v30, off offset:1024
	global_store_dword v[0:1], v31, off offset:1536
	s_branch .LBB0_1472

.LBB0_1490:
	v_add_u32_e32 v0, s56, v100
	s_movk_i32 s42, 0x7f
	v_add_u32_e32 v1, 0xffffff80, v0
	v_cmp_lt_i32_e64 s[42:43], s42, v0
	v_cmp_gt_i32_e32 vcc, s33, v0
	v_mov_b32_e32 v3, 0
	v_cndmask_b32_e64 v0, v0, v1, s[42:43]
	v_lshrrev_b32_e32 v1, 31, v0
	v_add_u32_e32 v1, v0, v1
	v_and_b32_e32 v2, 0x3fffffe, v1
	v_bfe_u32 v34, v1, 1, 3
	v_ashrrev_i32_e32 v1, 31, v0
	v_lshrrev_b32_e32 v1, 28, v1
	v_sub_u32_e32 v2, v0, v2
	v_add_u32_e32 v0, v0, v1
	v_ashrrev_i32_e32 v32, 4, v0
	v_lshlrev_b32_e32 v58, 6, v2
	v_lshlrev_b32_e32 v1, 4, v32
	v_ashrrev_i32_e32 v59, 31, v58
	v_mov_b32_e32 v0, 0
	v_or3_b32 v60, v1, v34, 8
	v_mov_b32_e32 v1, 0
	v_mov_b32_e32 v2, 0
	v_mov_b32_e32 v4, 0
	v_mov_b32_e32 v5, 0
	v_mov_b32_e32 v6, 0
	v_mov_b32_e32 v7, 0
	v_mov_b32_e32 v12, 0
	v_mov_b32_e32 v13, 0
	v_mov_b32_e32 v14, 0
	v_mov_b32_e32 v15, 0
	v_mov_b32_e32 v8, 0
	v_mov_b32_e32 v9, 0
	v_mov_b32_e32 v10, 0
	v_mov_b32_e32 v11, 0
	v_mov_b32_e32 v20, 0
	v_mov_b32_e32 v21, 0
	v_mov_b32_e32 v22, 0
	v_mov_b32_e32 v23, 0
	v_mov_b32_e32 v16, 0
	v_mov_b32_e32 v17, 0
	v_mov_b32_e32 v18, 0
	v_mov_b32_e32 v19, 0
	v_mov_b32_e32 v28, 0
	v_mov_b32_e32 v29, 0
	v_mov_b32_e32 v30, 0
	v_mov_b32_e32 v31, 0
	v_mov_b32_e32 v24, 0
	v_mov_b32_e32 v25, 0
	v_mov_b32_e32 v26, 0
	v_mov_b32_e32 v27, 0
	s_and_saveexec_b64 s[52:53], vcc
	s_cbranch_execz .LBB0_1492
	v_ashrrev_i32_e32 v61, 31, v60
	v_readlane_b32 s80, v241, 18
	v_lshlrev_b64 v[0:1], 16, v[60:61]
	v_readlane_b32 s90, v241, 28
	v_readlane_b32 s91, v241, 29
	s_waitcnt vmcnt(0)
	v_mov_b32_e32 v67, v57
	v_mov_b32_e32 v69, v57
	v_lshl_add_u64 v[0:1], s[90:91], 0, v[0:1]
	v_lshl_add_u64 v[0:1], v[58:59], 2, v[0:1]
	v_lshl_add_u64 v[0:1], v[0:1], 0, v[66:67]
	v_lshl_add_u64 v[0:1], v[0:1], 0, v[68:69]
	v_lshlrev_b32_e32 v56, 2, v122
	v_lshl_add_u64 v[24:25], v[0:1], 0, v[56:57]
	v_readlane_b32 s81, v241, 19
	v_add_co_u32_e32 v8, vcc, s57, v24
	v_readlane_b32 s82, v241, 20
	s_nop 0
	v_addc_co_u32_e32 v9, vcc, 0, v25, vcc
	global_load_dword v0, v[24:25], off
	global_load_dword v1, v[24:25], off offset:512
	global_load_dword v2, v[24:25], off offset:1024
	global_load_dword v3, v[24:25], off offset:1536
	global_load_dword v4, v[8:9], off
	global_load_dword v5, v[8:9], off offset:512
	global_load_dword v6, v[8:9], off offset:1024
	global_load_dword v7, v[8:9], off offset:1536
	v_add_co_u32_e32 v8, vcc, s58, v24
	v_readlane_b32 s83, v241, 21
	s_nop 0
	v_addc_co_u32_e32 v9, vcc, 0, v25, vcc
	v_add_co_u32_e32 v16, vcc, s59, v24
	v_readlane_b32 s84, v241, 22
	s_nop 0
	v_addc_co_u32_e32 v17, vcc, 0, v25, vcc
	global_load_dword v12, v[8:9], off
	global_load_dword v13, v[8:9], off offset:512
	global_load_dword v14, v[8:9], off offset:1024
	global_load_dword v15, v[8:9], off offset:1536
	s_nop 0
	global_load_dword v8, v[16:17], off
	global_load_dword v9, v[16:17], off offset:512
	global_load_dword v10, v[16:17], off offset:1024
	global_load_dword v11, v[16:17], off offset:1536
	v_add_co_u32_e32 v16, vcc, s60, v24
	v_readlane_b32 s85, v241, 23
	s_nop 0
	v_addc_co_u32_e32 v17, vcc, 0, v25, vcc
	v_add_co_u32_e32 v26, vcc, s61, v24
	v_readlane_b32 s86, v241, 24
	s_nop 0
	v_addc_co_u32_e32 v27, vcc, 0, v25, vcc
	global_load_dword v20, v[16:17], off
	global_load_dword v21, v[16:17], off offset:512
	global_load_dword v22, v[16:17], off offset:1024
	global_load_dword v23, v[16:17], off offset:1536
	s_nop 0
	global_load_dword v16, v[26:27], off
	global_load_dword v17, v[26:27], off offset:512
	global_load_dword v18, v[26:27], off offset:1024
	global_load_dword v19, v[26:27], off offset:1536
	v_add_co_u32_e32 v26, vcc, 0xc000, v24
	v_readlane_b32 s87, v241, 25
	s_nop 0
	v_addc_co_u32_e32 v27, vcc, 0, v25, vcc
	v_add_co_u32_e32 v36, vcc, 0xe000, v24
	v_readlane_b32 s88, v241, 26
	s_nop 0
	v_addc_co_u32_e32 v37, vcc, 0, v25, vcc
	global_load_dword v28, v[26:27], off
	global_load_dword v29, v[26:27], off offset:512
	global_load_dword v30, v[26:27], off offset:1024
	global_load_dword v31, v[26:27], off offset:1536
	global_load_dword v24, v[36:37], off
	global_load_dword v25, v[36:37], off offset:512
	s_nop 0
	global_load_dword v26, v[36:37], off offset:1024
	global_load_dword v27, v[36:37], off offset:1536
	v_readlane_b32 s89, v241, 27
	v_readlane_b32 s92, v241, 30
	v_readlane_b32 s93, v241, 31
	v_readlane_b32 s94, v241, 32
	v_readlane_b32 s95, v241, 33
	v_readlane_b32 s80, v241, 37
	v_readlane_b32 s92, v241, 49
	v_readlane_b32 s93, v241, 50
	v_readlane_b32 s94, v241, 51
	v_readlane_b32 s95, v241, 52
	v_readlane_b32 s81, v241, 38
	v_readlane_b32 s82, v241, 39
	v_readlane_b32 s83, v241, 40
	v_readlane_b32 s84, v241, 41
	v_readlane_b32 s85, v241, 42
	v_readlane_b32 s86, v241, 43
	v_readlane_b32 s87, v241, 44
	v_readlane_b32 s88, v241, 45
	v_readlane_b32 s89, v241, 46
	v_readlane_b32 s90, v241, 47
	v_readlane_b32 s91, v241, 48
.LBB0_1492:
	s_or_b64 exec, exec, s[52:53]
	v_ashrrev_i32_e32 v33, 31, v32
	v_lshlrev_b64 v[36:37], 11, v[32:33]
	s_mov_b64 s[52:53], 0x2000
	v_lshl_add_u64 v[36:37], v[36:37], 0, s[52:53]
	v_lshlrev_b64 v[32:33], 8, v[32:33]
	v_cndmask_b32_e64 v33, v37, v33, s[42:43]
	v_cndmask_b32_e64 v32, v36, v32, s[42:43]
	v_lshlrev_b64 v[36:37], 11, v[32:33]
	v_cndmask_b32_e64 v61, 32, 4, s[42:43]
	v_lshl_add_u64 v[38:39], s[68:69], 0, v[36:37]
	v_lshlrev_b32_e32 v56, 8, v34
	v_lshl_add_u64 v[40:41], s[44:45], 0, v[36:37]
	v_lshl_add_u64 v[36:37], s[46:47], 0, v[36:37]
	v_lshl_add_u64 v[38:39], v[38:39], 0, v[56:57]
	v_lshl_add_u64 v[40:41], v[40:41], 0, v[56:57]
	v_lshl_add_u64 v[36:37], v[36:37], 0, v[56:57]
	v_add_u32_e32 v56, -1, v61
	v_lshl_add_u64 v[36:37], v[58:59], 1, v[36:37]
	v_lshlrev_b64 v[42:43], 17, v[56:57]
	v_lshl_add_u64 v[44:45], v[38:39], 0, v[42:43]
	v_lshlrev_b32_e32 v56, 2, v102
	v_lshl_add_u64 v[46:47], v[40:41], 0, v[42:43]
	v_lshl_add_u64 v[42:43], v[36:37], 0, v[42:43]
	v_mov_b32_e32 v65, v57
	v_lshl_add_u64 v[44:45], v[44:45], 0, v[56:57]
	v_lshl_add_u64 v[46:47], v[46:47], 0, v[56:57]
	v_lshl_add_u64 v[42:43], v[42:43], 0, v[64:65]
	s_waitcnt vmcnt(0)
	global_load_dword v67, v[44:45], off
	global_load_dword v69, v[44:45], off offset:2048
	global_load_dword v75, v[46:47], off
	global_load_dword v150, v[46:47], off offset:2048
	v_add_co_u32_e32 v48, vcc, s62, v44
	v_lshlrev_b32_e32 v33, 6, v61
	s_nop 0
	v_addc_co_u32_e32 v49, vcc, 0, v45, vcc
	v_add_co_u32_e32 v50, vcc, s62, v46
	v_lshlrev_b32_e32 v34, 7, v34
	s_nop 0
	v_addc_co_u32_e32 v51, vcc, 0, v47, vcc
	global_load_dword v151, v[48:49], off
	global_load_dword v152, v[48:49], off offset:2048
	global_load_dword v153, v[50:51], off
	global_load_dword v154, v[50:51], off offset:2048
	v_add_co_u32_e32 v48, vcc, s57, v44
	v_lshl_add_u64 v[72:73], v[36:37], 0, v[64:65]
	s_nop 0
	v_addc_co_u32_e32 v49, vcc, 0, v45, vcc
	v_add_co_u32_e32 v50, vcc, s57, v46
	v_add3_u32 v65, v142, v33, v32
	s_nop 0
	v_addc_co_u32_e32 v51, vcc, 0, v47, vcc
	global_load_dword v155, v[48:49], off
	global_load_dword v156, v[48:49], off offset:2048
	global_load_dword v157, v[50:51], off
	global_load_dword v158, v[50:51], off offset:2048
	v_add_co_u32_e32 v48, vcc, s63, v44
	s_mov_b32 s66, 1
	s_nop 0
	v_addc_co_u32_e32 v49, vcc, 0, v45, vcc
	v_add_co_u32_e32 v50, vcc, s63, v46
	v_lshl_add_u64 v[62:63], v[38:39], 0, v[56:57]
	s_nop 0
	v_addc_co_u32_e32 v51, vcc, 0, v47, vcc
	global_load_dword v159, v[48:49], off
	global_load_dword v160, v[48:49], off offset:2048
	global_load_dword v161, v[50:51], off
	global_load_dword v162, v[50:51], off offset:2048
	v_add_co_u32_e32 v48, vcc, s58, v44
	v_lshl_add_u64 v[70:71], v[40:41], 0, v[56:57]
	s_nop 0
	v_addc_co_u32_e32 v49, vcc, 0, v45, vcc
	v_add_co_u32_e32 v50, vcc, s58, v46
	v_add_u32_e32 v74, -2, v61
	s_nop 0
	v_addc_co_u32_e32 v51, vcc, 0, v47, vcc
	global_load_dword v163, v[48:49], off
	global_load_dword v165, v[48:49], off offset:2048
	global_load_dword v166, v[50:51], off
	global_load_dword v167, v[50:51], off offset:2048
	v_add_co_u32_e32 v48, vcc, s64, v44
	v_lshlrev_b32_e32 v164, 10, v65
	s_nop 0
	v_addc_co_u32_e32 v49, vcc, 0, v45, vcc
	v_add_co_u32_e32 v50, vcc, s64, v46
	s_mov_b64 s[52:53], 0
	s_nop 0
	v_addc_co_u32_e32 v51, vcc, 0, v47, vcc
	global_load_dword v168, v[48:49], off
	global_load_dword v169, v[48:49], off offset:2048
	global_load_dword v170, v[50:51], off
	global_load_dword v171, v[50:51], off offset:2048
	v_add_co_u32_e32 v48, vcc, s59, v44
	v_lshlrev_b32_e32 v76, 1, v34
	s_nop 0
	v_addc_co_u32_e32 v49, vcc, 0, v45, vcc
	v_add_co_u32_e32 v50, vcc, s59, v46
	s_nop 1
	v_addc_co_u32_e32 v51, vcc, 0, v47, vcc
	v_add_co_u32_e32 v44, vcc, s65, v44
	global_load_dword v172, v[48:49], off
	global_load_dword v173, v[48:49], off offset:2048
	global_load_dword v174, v[50:51], off
	global_load_dword v175, v[50:51], off offset:2048
	v_addc_co_u32_e32 v45, vcc, 0, v45, vcc
	v_add_co_u32_e32 v46, vcc, s65, v46
	s_nop 1
	v_addc_co_u32_e32 v47, vcc, 0, v47, vcc
	global_load_dword v176, v[44:45], off
	global_load_dword v177, v[44:45], off offset:2048
	global_load_dword v187, v[46:47], off
	global_load_dword v188, v[46:47], off offset:2048
	global_load_dword v189, v[42:43], off
	global_load_dword v190, v[42:43], off offset:2048
	v_add_co_u32_e32 v44, vcc, s62, v42
	s_nop 1
	v_addc_co_u32_e32 v45, vcc, 0, v43, vcc
	v_add_co_u32_e32 v46, vcc, s57, v42
	s_nop 1
	v_addc_co_u32_e32 v47, vcc, 0, v43, vcc
	v_add_co_u32_e32 v42, vcc, 0x3000, v42
	s_nop 1
	v_addc_co_u32_e32 v43, vcc, 0, v43, vcc
	global_load_dword v191, v[44:45], off
	global_load_dword v192, v[44:45], off offset:2048
	global_load_dword v193, v[46:47], off
	global_load_dword v194, v[46:47], off offset:2048
	global_load_dword v195, v[42:43], off
	global_load_dword v196, v[42:43], off offset:2048
	s_waitcnt vmcnt(0)
	s_branch .LBB0_1494

.LBB0_1494:
	s_waitcnt vmcnt(4) lgkmcnt(0)
	v_lshlrev_b32_e32 v46, 16, v75
	v_and_b32_e32 v47, 0xffff0000, v75
	v_lshlrev_b32_e32 v48, 16, v150
	v_and_b32_e32 v49, 0xffff0000, v150
	v_pk_add_f32 v[32:33], v[46:47], 0 op_sel_hi:[1,0]
	v_lshlrev_b32_e32 v50, 16, v153
	v_and_b32_e32 v51, 0xffff0000, v153
	v_pk_add_f32 v[32:33], v[32:33], v[48:49]
	v_lshlrev_b32_e32 v54, 16, v154
	v_and_b32_e32 v55, 0xffff0000, v154
	v_pk_add_f32 v[32:33], v[32:33], v[50:51]
	v_lshlrev_b32_e32 v88, 16, v157
	v_and_b32_e32 v89, 0xffff0000, v157
	v_pk_add_f32 v[32:33], v[32:33], v[54:55]
	v_lshlrev_b32_e32 v86, 16, v158
	v_pk_add_f32 v[32:33], v[32:33], v[88:89]
	v_and_b32_e32 v87, 0xffff0000, v158
	v_lshlrev_b32_e32 v84, 16, v161
	v_and_b32_e32 v85, 0xffff0000, v161
	v_pk_add_f32 v[32:33], v[32:33], v[86:87]
	v_lshlrev_b32_e32 v82, 16, v162
	v_and_b32_e32 v83, 0xffff0000, v162
	v_pk_add_f32 v[32:33], v[32:33], v[84:85]
	v_lshlrev_b32_e32 v80, 16, v166
	v_and_b32_e32 v81, 0xffff0000, v166
	v_pk_add_f32 v[32:33], v[32:33], v[82:83]
	v_lshlrev_b32_e32 v78, 16, v167
	v_and_b32_e32 v79, 0xffff0000, v167
	v_pk_add_f32 v[32:33], v[32:33], v[80:81]
	v_lshlrev_b32_e32 v52, 16, v170
	v_and_b32_e32 v53, 0xffff0000, v170
	v_pk_add_f32 v[32:33], v[32:33], v[78:79]
	v_lshlrev_b32_e32 v36, 16, v171
	v_and_b32_e32 v37, 0xffff0000, v171
	v_pk_add_f32 v[32:33], v[32:33], v[52:53]
	v_lshlrev_b32_e32 v42, 16, v174
	v_and_b32_e32 v43, 0xffff0000, v174
	v_pk_add_f32 v[32:33], v[32:33], v[36:37]
	v_lshlrev_b32_e32 v90, 16, v175
	v_and_b32_e32 v91, 0xffff0000, v175
	v_pk_add_f32 v[32:33], v[32:33], v[42:43]
	v_lshlrev_b32_e32 v44, 16, v187
	v_and_b32_e32 v45, 0xffff0000, v187
	v_pk_add_f32 v[32:33], v[32:33], v[90:91]
	v_lshlrev_b32_e32 v38, 16, v188
	v_and_b32_e32 v39, 0xffff0000, v188
	v_pk_add_f32 v[32:33], v[32:33], v[44:45]
	v_add_u32_e32 v34, v101, v103
	v_pk_add_f32 v[32:33], v[32:33], v[38:39]
	ds_write_b64 v34, v[32:33]
	s_waitcnt lgkmcnt(0)
	s_barrier
	ds_read_b64 v[32:33], v101
	ds_read_b64 v[34:35], v104
	ds_read_b64 v[40:41], v106
	ds_read_b64 v[92:93], v105
	v_exp_f32_e32 v96, v38
	v_exp_f32_e32 v97, v39
	s_waitcnt lgkmcnt(2)
	v_add_f32_e32 v56, v32, v34
	v_add_f32_e32 v77, v33, v35
	s_waitcnt lgkmcnt(1)
	v_cndmask_b32_e64 v32, v40, 0, s[2:3]
	s_waitcnt lgkmcnt(0)
	v_cndmask_b32_e64 v33, 0, v92, s[6:7]
	v_add_f32_e32 v32, v33, v32
	v_cndmask_b32_e64 v33, 0, v34, s[8:9]
	v_add_f32_e32 v32, v33, v32
	v_cndmask_b32_e64 v33, v41, 0, s[2:3]
	v_cndmask_b32_e64 v34, 0, v93, s[6:7]
	v_add_f32_e32 v33, v34, v33
	v_cndmask_b32_e64 v34, 0, v35, s[8:9]
	v_add_f32_e32 v94, v34, v33
	v_mov_b32_e32 v33, v92
	v_mov_b32_e32 v34, v38
	v_mov_b32_e32 v35, v40
	v_mov_b32_e32 v95, v93
	v_mov_b32_e32 v40, v39
	v_pk_add_f32 v[34:35], v[32:33], v[34:35]
	v_pk_add_f32 v[38:39], v[94:95], v[40:41]
	v_sub_f32_e32 v32, v34, v35
	v_sub_f32_e32 v33, v38, v39
	v_exp_f32_e32 v32, v32
	v_exp_f32_e32 v33, v33
	v_lshlrev_b32_e32 v40, 16, v177
	v_and_b32_e32 v41, 0xffff0000, v177
	v_add_u32_e32 v98, v107, v121
	v_pk_mul_f32 v[32:33], v[32:33], v[40:41]
	v_sub_f32_e32 v40, v35, v34
	v_sub_f32_e32 v41, v39, v38
	v_exp_f32_e32 v40, v40
	v_exp_f32_e32 v41, v41
	v_cvt_pk_bf16_f32 v94, v32, v33
	v_pk_add_f32 v[32:33], v[96:97], 1.0 op_sel_hi:[1,0] neg_lo:[1,0] neg_hi:[1,0]
	v_add_f32_e32 v34, v34, v44
	v_pk_mul_f32 v[40:41], v[32:33], v[40:41]
	v_sub_f32_e32 v33, v34, v35
	v_add_f32_e32 v38, v38, v45
	v_exp_f32_e32 v92, v33
	v_sub_f32_e32 v33, v38, v39
	v_exp_f32_e32 v93, v33
	v_exp_f32_e32 v32, v44
	v_exp_f32_e32 v33, v45
	v_lshlrev_b32_e32 v44, 16, v176
	v_and_b32_e32 v45, 0xffff0000, v176
	v_pk_mul_f32 v[44:45], v[92:93], v[44:45]
	v_pk_add_f32 v[32:33], v[32:33], 1.0 op_sel_hi:[1,0] neg_lo:[1,0] neg_hi:[1,0]
	v_cvt_pk_bf16_f32 v92, v44, v45
	v_sub_f32_e32 v44, v35, v34
	v_sub_f32_e32 v45, v39, v38
	v_exp_f32_e32 v44, v44
	v_exp_f32_e32 v45, v45
	v_cvt_pk_bf16_f32 v95, v40, v41
	v_add_u32_e32 v97, 0x5000, v98
	v_add_f32_e32 v34, v34, v90
	v_pk_mul_f32 v[44:45], v[32:33], v[44:45]
	v_add_f32_e32 v38, v38, v91
	v_cvt_pk_bf16_f32 v32, v44, v45
	ds_write2_b32 v97, v32, v95 offset0:184 offset1:252
	v_exp_f32_e32 v32, v90
	v_exp_f32_e32 v33, v91
	v_sub_f32_e32 v90, v34, v35
	v_sub_f32_e32 v91, v38, v39
	v_exp_f32_e32 v90, v90
	v_exp_f32_e32 v91, v91
	v_add_u32_e32 v96, 0xc00, v98
	ds_write2_b32 v96, v92, v94 offset0:184 offset1:252
	v_lshlrev_b32_e32 v92, 16, v173
	v_and_b32_e32 v93, 0xffff0000, v173
	v_sub_f32_e32 v94, v35, v34
	v_pk_mul_f32 v[90:91], v[90:91], v[92:93]
	v_add_f32_e32 v34, v34, v42
	v_sub_f32_e32 v95, v39, v38
	v_cvt_pk_bf16_f32 v197, v90, v91
	v_exp_f32_e32 v90, v42
	v_sub_f32_e32 v42, v34, v35
	v_add_f32_e32 v38, v38, v43
	v_exp_f32_e32 v92, v42
	v_sub_f32_e32 v42, v38, v39
	v_exp_f32_e32 v93, v42
	v_exp_f32_e32 v91, v43
	v_lshlrev_b32_e32 v42, 16, v172
	v_and_b32_e32 v43, 0xffff0000, v172
	v_pk_mul_f32 v[42:43], v[92:93], v[42:43]
	v_sub_f32_e32 v92, v35, v34
	v_sub_f32_e32 v93, v39, v38
	v_exp_f32_e32 v94, v94
	v_exp_f32_e32 v95, v95
	v_exp_f32_e32 v92, v92
	v_exp_f32_e32 v93, v93
	v_cvt_pk_bf16_f32 v42, v42, v43
	v_pk_add_f32 v[32:33], v[32:33], 1.0 op_sel_hi:[1,0] neg_lo:[1,0] neg_hi:[1,0]
	ds_write2_b32 v96, v42, v197 offset0:48 offset1:116
	v_pk_add_f32 v[42:43], v[90:91], 1.0 op_sel_hi:[1,0] neg_lo:[1,0] neg_hi:[1,0]
	v_pk_mul_f32 v[32:33], v[32:33], v[94:95]
	v_pk_mul_f32 v[42:43], v[42:43], v[92:93]
	v_cvt_pk_bf16_f32 v94, v32, v33
	v_cvt_pk_bf16_f32 v90, v42, v43
	v_add_f32_e32 v34, v34, v36
	v_add_f32_e32 v38, v38, v37
	ds_write2_b32 v97, v90, v94 offset0:48 offset1:116
	v_exp_f32_e32 v90, v36
	v_exp_f32_e32 v91, v37
	v_sub_f32_e32 v36, v34, v35
	v_sub_f32_e32 v37, v38, v39
	v_exp_f32_e32 v36, v36
	v_exp_f32_e32 v37, v37
	v_lshlrev_b32_e32 v92, 16, v169
	v_and_b32_e32 v93, 0xffff0000, v169
	v_sub_f32_e32 v94, v35, v34
	v_pk_mul_f32 v[36:37], v[36:37], v[92:93]
	v_add_f32_e32 v34, v34, v52
	v_sub_f32_e32 v95, v39, v38
	v_cvt_pk_bf16_f32 v96, v36, v37
	v_pk_add_f32 v[36:37], v[90:91], 1.0 op_sel_hi:[1,0] neg_lo:[1,0] neg_hi:[1,0]
	v_exp_f32_e32 v90, v52
	v_sub_f32_e32 v52, v34, v35
	v_add_f32_e32 v38, v38, v53
	v_exp_f32_e32 v92, v52
	v_sub_f32_e32 v52, v38, v39
	v_exp_f32_e32 v93, v52
	v_exp_f32_e32 v91, v53
	v_lshlrev_b32_e32 v52, 16, v168
	v_and_b32_e32 v53, 0xffff0000, v168
	v_pk_mul_f32 v[52:53], v[92:93], v[52:53]
	v_exp_f32_e32 v94, v94
	v_cvt_pk_bf16_f32 v92, v52, v53
	v_sub_f32_e32 v52, v35, v34
	v_sub_f32_e32 v53, v39, v38
	v_exp_f32_e32 v95, v95
	v_exp_f32_e32 v52, v52
	v_exp_f32_e32 v53, v53
	v_pk_add_f32 v[90:91], v[90:91], 1.0 op_sel_hi:[1,0] neg_lo:[1,0] neg_hi:[1,0]
	v_pk_mul_f32 v[36:37], v[36:37], v[94:95]
	v_add_u32_e32 v97, 0x800, v98
	v_pk_mul_f32 v[52:53], v[90:91], v[52:53]
	v_cvt_pk_bf16_f32 v94, v36, v37
	ds_write2_b32 v97, v92, v96 offset0:168 offset1:236
	v_cvt_pk_bf16_f32 v90, v52, v53
	v_add_u32_e32 v96, 0x4c00, v98
	v_add_f32_e32 v34, v34, v78
	v_add_f32_e32 v38, v38, v79
	ds_write2_b32 v96, v90, v94 offset0:168 offset1:236
	v_exp_f32_e32 v90, v78
	v_exp_f32_e32 v91, v79
	v_sub_f32_e32 v78, v34, v35
	v_sub_f32_e32 v79, v38, v39
	v_exp_f32_e32 v78, v78
	v_exp_f32_e32 v79, v79
	v_lshlrev_b32_e32 v92, 16, v165
	v_and_b32_e32 v93, 0xffff0000, v165
	v_sub_f32_e32 v94, v35, v34
	v_pk_mul_f32 v[78:79], v[78:79], v[92:93]
	v_add_f32_e32 v34, v34, v80
	v_sub_f32_e32 v95, v39, v38
	v_cvt_pk_bf16_f32 v197, v78, v79
	v_pk_add_f32 v[78:79], v[90:91], 1.0 op_sel_hi:[1,0] neg_lo:[1,0] neg_hi:[1,0]
	v_exp_f32_e32 v90, v80
	v_sub_f32_e32 v80, v34, v35
	v_add_f32_e32 v38, v38, v81
	v_exp_f32_e32 v92, v80
	v_sub_f32_e32 v80, v38, v39
	v_exp_f32_e32 v93, v80
	v_exp_f32_e32 v91, v81
	v_lshlrev_b32_e32 v80, 16, v163
	v_and_b32_e32 v81, 0xffff0000, v163
	v_pk_mul_f32 v[80:81], v[92:93], v[80:81]
	v_sub_f32_e32 v92, v35, v34
	v_sub_f32_e32 v93, v39, v38
	v_exp_f32_e32 v94, v94
	v_exp_f32_e32 v95, v95
	v_exp_f32_e32 v92, v92
	v_exp_f32_e32 v93, v93
	v_cvt_pk_bf16_f32 v80, v80, v81
	ds_write2_b32 v97, v80, v197 offset0:32 offset1:100
	v_pk_add_f32 v[80:81], v[90:91], 1.0 op_sel_hi:[1,0] neg_lo:[1,0] neg_hi:[1,0]
	v_pk_mul_f32 v[78:79], v[78:79], v[94:95]
	v_pk_mul_f32 v[80:81], v[80:81], v[92:93]
	v_cvt_pk_bf16_f32 v94, v78, v79
	v_cvt_pk_bf16_f32 v90, v80, v81
	v_add_f32_e32 v34, v34, v82
	v_add_f32_e32 v38, v38, v83
	ds_write2_b32 v96, v90, v94 offset0:32 offset1:100
	v_exp_f32_e32 v90, v82
	v_exp_f32_e32 v91, v83
	v_sub_f32_e32 v82, v34, v35
	v_sub_f32_e32 v83, v38, v39
	v_exp_f32_e32 v82, v82
	v_exp_f32_e32 v83, v83
	v_lshlrev_b32_e32 v92, 16, v160
	v_and_b32_e32 v93, 0xffff0000, v160
	v_sub_f32_e32 v94, v35, v34
	v_pk_mul_f32 v[82:83], v[82:83], v[92:93]
	v_add_f32_e32 v34, v34, v84
	v_sub_f32_e32 v95, v39, v38
	v_cvt_pk_bf16_f32 v96, v82, v83
	v_pk_add_f32 v[82:83], v[90:91], 1.0 op_sel_hi:[1,0] neg_lo:[1,0] neg_hi:[1,0]
	v_exp_f32_e32 v90, v84
	v_add_f32_e32 v38, v38, v85
	v_sub_f32_e32 v84, v34, v35
	v_exp_f32_e32 v92, v84
	v_sub_f32_e32 v84, v38, v39
	v_exp_f32_e32 v93, v84
	v_exp_f32_e32 v91, v85
	v_lshlrev_b32_e32 v84, 16, v159
	v_and_b32_e32 v85, 0xffff0000, v159
	v_pk_mul_f32 v[84:85], v[92:93], v[84:85]
	v_exp_f32_e32 v94, v94
	v_cvt_pk_bf16_f32 v92, v84, v85
	v_sub_f32_e32 v84, v35, v34
	v_sub_f32_e32 v85, v39, v38
	v_exp_f32_e32 v95, v95
	v_exp_f32_e32 v84, v84
	v_exp_f32_e32 v85, v85
	v_add_u32_e32 v97, 0x400, v98
	v_pk_add_f32 v[90:91], v[90:91], 1.0 op_sel_hi:[1,0] neg_lo:[1,0] neg_hi:[1,0]
	v_add_f32_e32 v34, v34, v86
	v_add_f32_e32 v38, v38, v87
	v_pk_mul_f32 v[82:83], v[82:83], v[94:95]
	ds_write2_b32 v97, v92, v96 offset0:152 offset1:220
	v_pk_mul_f32 v[84:85], v[90:91], v[84:85]
	v_sub_f32_e32 v92, v34, v35
	v_sub_f32_e32 v93, v38, v39
	v_cvt_pk_bf16_f32 v94, v82, v83
	v_cvt_pk_bf16_f32 v90, v84, v85
	v_add_u32_e32 v96, 0x4800, v98
	v_exp_f32_e32 v92, v92
	v_exp_f32_e32 v93, v93
	ds_write2_b32 v96, v90, v94 offset0:152 offset1:220
	v_exp_f32_e32 v90, v86
	v_exp_f32_e32 v91, v87
	v_lshlrev_b32_e32 v86, 16, v156
	v_and_b32_e32 v87, 0xffff0000, v156
	v_sub_f32_e32 v94, v35, v34
	v_pk_mul_f32 v[86:87], v[92:93], v[86:87]
	v_add_f32_e32 v34, v34, v88
	v_sub_f32_e32 v95, v39, v38
	v_cvt_pk_bf16_f32 v197, v86, v87
	v_pk_add_f32 v[86:87], v[90:91], 1.0 op_sel_hi:[1,0] neg_lo:[1,0] neg_hi:[1,0]
	v_exp_f32_e32 v90, v88
	v_add_f32_e32 v38, v38, v89
	v_sub_f32_e32 v88, v34, v35
	v_exp_f32_e32 v92, v88
	v_sub_f32_e32 v88, v38, v39
	v_exp_f32_e32 v93, v88
	v_exp_f32_e32 v91, v89
	v_lshlrev_b32_e32 v88, 16, v155
	v_and_b32_e32 v89, 0xffff0000, v155
	v_pk_mul_f32 v[88:89], v[92:93], v[88:89]
	v_sub_f32_e32 v92, v35, v34
	v_sub_f32_e32 v93, v39, v38
	v_exp_f32_e32 v94, v94
	v_exp_f32_e32 v95, v95
	v_exp_f32_e32 v92, v92
	v_exp_f32_e32 v93, v93
	v_cvt_pk_bf16_f32 v88, v88, v89
	ds_write2_b32 v97, v88, v197 offset0:16 offset1:84
	v_pk_add_f32 v[88:89], v[90:91], 1.0 op_sel_hi:[1,0] neg_lo:[1,0] neg_hi:[1,0]
	v_add_f32_e32 v34, v34, v54
	v_add_f32_e32 v38, v38, v55
	v_pk_mul_f32 v[86:87], v[86:87], v[94:95]
	v_pk_mul_f32 v[88:89], v[88:89], v[92:93]
	v_sub_f32_e32 v92, v34, v35
	v_sub_f32_e32 v93, v38, v39
	v_cvt_pk_bf16_f32 v94, v86, v87
	v_cvt_pk_bf16_f32 v90, v88, v89
	v_exp_f32_e32 v92, v92
	v_exp_f32_e32 v93, v93
	ds_write2_b32 v96, v90, v94 offset0:16 offset1:84
	v_exp_f32_e32 v90, v54
	v_exp_f32_e32 v91, v55
	v_sub_f32_e32 v94, v35, v34
	v_sub_f32_e32 v95, v39, v38
	v_exp_f32_e32 v94, v94
	v_exp_f32_e32 v95, v95
	v_lshlrev_b32_e32 v54, 16, v152
	v_and_b32_e32 v55, 0xffff0000, v152
	v_pk_mul_f32 v[54:55], v[92:93], v[54:55]
	v_add_f32_e32 v34, v34, v50
	v_cvt_pk_bf16_f32 v96, v54, v55
	v_pk_add_f32 v[54:55], v[90:91], 1.0 op_sel_hi:[1,0] neg_lo:[1,0] neg_hi:[1,0]
	v_add_f32_e32 v38, v38, v51
	v_pk_mul_f32 v[90:91], v[54:55], v[94:95]
	v_exp_f32_e32 v54, v50
	v_sub_f32_e32 v50, v34, v35
	v_exp_f32_e32 v92, v50
	v_sub_f32_e32 v50, v38, v39
	v_exp_f32_e32 v93, v50
	v_exp_f32_e32 v55, v51
	v_lshlrev_b32_e32 v50, 16, v151
	v_and_b32_e32 v51, 0xffff0000, v151
	v_pk_mul_f32 v[50:51], v[92:93], v[50:51]
	v_sub_f32_e32 v92, v35, v34
	v_sub_f32_e32 v93, v39, v38
	v_exp_f32_e32 v92, v92
	v_exp_f32_e32 v93, v93
	v_cvt_pk_bf16_f32 v50, v50, v51
	ds_write2_b32 v98, v50, v96 offset0:136 offset1:204
	v_pk_add_f32 v[50:51], v[54:55], 1.0 op_sel_hi:[1,0] neg_lo:[1,0] neg_hi:[1,0]
	v_add_f32_e32 v34, v34, v48
	v_add_f32_e32 v38, v38, v49
	v_pk_mul_f32 v[92:93], v[50:51], v[92:93]
	v_sub_f32_e32 v54, v34, v35
	v_sub_f32_e32 v55, v38, v39
	v_cvt_pk_bf16_f32 v94, v90, v91
	v_cvt_pk_bf16_f32 v50, v92, v93
	v_add_u32_e32 v197, 0x4400, v98
	v_exp_f32_e32 v54, v54
	v_exp_f32_e32 v55, v55
	ds_write2_b32 v197, v50, v94 offset0:136 offset1:204
	v_exp_f32_e32 v50, v48
	v_exp_f32_e32 v51, v49
	v_sub_f32_e32 v94, v35, v34
	v_sub_f32_e32 v95, v39, v38
	v_exp_f32_e32 v94, v94
	v_exp_f32_e32 v95, v95
	v_lshlrev_b32_e32 v48, 16, v69
	v_and_b32_e32 v49, 0xffff0000, v69
	v_pk_mul_f32 v[48:49], v[54:55], v[48:49]
	v_add_f32_e32 v34, v34, v46
	v_cvt_pk_bf16_f32 v54, v48, v49
	v_pk_add_f32 v[48:49], v[50:51], 1.0 op_sel_hi:[1,0] neg_lo:[1,0] neg_hi:[1,0]
	v_add_f32_e32 v38, v38, v47
	v_pk_mul_f32 v[94:95], v[48:49], v[94:95]
	v_exp_f32_e32 v48, v46
	v_sub_f32_e32 v46, v34, v35
	v_exp_f32_e32 v50, v46
	v_sub_f32_e32 v46, v38, v39
	v_exp_f32_e32 v51, v46
	v_exp_f32_e32 v49, v47
	v_lshlrev_b32_e32 v46, 16, v67
	v_and_b32_e32 v47, 0xffff0000, v67
	v_sub_f32_e32 v34, v35, v34
	v_pk_mul_f32 v[46:47], v[50:51], v[46:47]
	v_exp_f32_e32 v50, v34
	v_sub_f32_e32 v34, v39, v38
	v_exp_f32_e32 v51, v34
	v_cvt_pk_bf16_f32 v34, v46, v47
	v_pk_add_f32 v[46:47], v[48:49], 1.0 op_sel_hi:[1,0] neg_lo:[1,0] neg_hi:[1,0]
	v_add_f32_e32 v56, v56, v35
	v_pk_mul_f32 v[96:97], v[46:47], v[50:51]
	v_add_f32_e32 v77, v77, v39
	v_cvt_pk_bf16_f32 v55, v94, v95
	ds_write2_b32 v98, v34, v54 offset1:68
	v_cvt_pk_bf16_f32 v34, v96, v97
	ds_write2_b32 v197, v34, v55 offset1:68
	s_and_saveexec_b64 s[54:55], s[8:9]
	s_cbranch_execz .LBB0_1496
	v_exp_f32_e32 v49, v77
	v_exp_f32_e32 v48, v56
	v_exp_f32_e32 v47, v39
	v_exp_f32_e32 v46, v35
	ds_write_b64 v110, v[48:49]
	ds_write_b64 v111, v[46:47]
.LBB0_1496:
	s_or_b64 exec, exec, s[54:55]
	v_lshlrev_b32_e32 v34, 16, v192
	v_lshlrev_b32_e32 v38, 16, v190
	v_lshlrev_b32_e32 v48, 16, v196
	v_lshlrev_b32_e32 v50, 16, v194
	v_or_b32_sdwa v47, v191, v34 dst_sel:DWORD dst_unused:UNUSED_PAD src0_sel:WORD_0 src1_sel:DWORD
	v_or_b32_sdwa v46, v189, v38 dst_sel:DWORD dst_unused:UNUSED_PAD src0_sel:WORD_0 src1_sel:DWORD
	v_add_u32_e32 v34, v108, v109
	v_or_b32_sdwa v49, v195, v48 dst_sel:DWORD dst_unused:UNUSED_PAD src0_sel:WORD_0 src1_sel:DWORD
	v_or_b32_sdwa v48, v193, v50 dst_sel:DWORD dst_unused:UNUSED_PAD src0_sel:WORD_0 src1_sel:DWORD
	v_and_b32_e32 v38, 0xffff0000, v192
	ds_write_b128 v34, v[46:49] offset:35840
	v_and_b32_e32 v46, 0xffff0000, v190
	v_or_b32_sdwa v47, v191, v38 dst_sel:DWORD dst_unused:UNUSED_PAD src0_sel:WORD_1 src1_sel:DWORD
	v_and_b32_e32 v38, 0xffff0000, v196
	v_and_b32_e32 v48, 0xffff0000, v194
	v_or_b32_sdwa v46, v189, v46 dst_sel:DWORD dst_unused:UNUSED_PAD src0_sel:WORD_1 src1_sel:DWORD
	v_or_b32_sdwa v49, v195, v38 dst_sel:DWORD dst_unused:UNUSED_PAD src0_sel:WORD_1 src1_sel:DWORD
	v_or_b32_sdwa v48, v193, v48 dst_sel:DWORD dst_unused:UNUSED_PAD src0_sel:WORD_1 src1_sel:DWORD
	v_cmp_lt_u32_e32 vcc, s66, v61
	ds_write_b128 v34, v[46:49] offset:35984
	s_and_saveexec_b64 s[54:55], vcc
	s_cbranch_execz .LBB0_1493
	v_ashrrev_i32_e32 v75, 31, v74
	v_lshlrev_b64 v[46:47], 17, v[74:75]
	v_lshl_add_u64 v[48:49], v[62:63], 0, v[46:47]
	v_lshl_add_u64 v[50:51], v[70:71], 0, v[46:47]
	v_lshl_add_u64 v[46:47], v[72:73], 0, v[46:47]
	global_load_dword v67, v[48:49], off
	global_load_dword v69, v[48:49], off offset:2048
	global_load_dword v75, v[50:51], off
	global_load_dword v150, v[50:51], off offset:2048
	v_add_co_u32_e32 v54, vcc, 0x1000, v48
	s_nop 1
	v_addc_co_u32_e32 v55, vcc, 0, v49, vcc
	v_add_co_u32_e32 v154, vcc, 0x1000, v50
	s_nop 1
	v_addc_co_u32_e32 v155, vcc, 0, v51, vcc
	global_load_dword v151, v[54:55], off
	global_load_dword v152, v[54:55], off offset:2048
	global_load_dword v153, v[154:155], off
	s_nop 0
	global_load_dword v154, v[154:155], off offset:2048
	v_add_co_u32_e32 v54, vcc, s57, v48
	s_nop 1
	v_addc_co_u32_e32 v55, vcc, 0, v49, vcc
	v_add_co_u32_e32 v158, vcc, s57, v50
	s_nop 1
	v_addc_co_u32_e32 v159, vcc, 0, v51, vcc
	global_load_dword v155, v[54:55], off
	global_load_dword v156, v[54:55], off offset:2048
	global_load_dword v157, v[158:159], off
	s_nop 0
	global_load_dword v158, v[158:159], off offset:2048
	v_add_co_u32_e32 v54, vcc, s63, v48
	s_nop 1
	v_addc_co_u32_e32 v55, vcc, 0, v49, vcc
	v_add_co_u32_e32 v162, vcc, s63, v50
	s_nop 1
	v_addc_co_u32_e32 v163, vcc, 0, v51, vcc
	global_load_dword v159, v[54:55], off
	global_load_dword v160, v[54:55], off offset:2048
	global_load_dword v161, v[162:163], off
	s_nop 0
	global_load_dword v162, v[162:163], off offset:2048
	v_add_co_u32_e32 v54, vcc, s58, v48
	s_nop 1
	v_addc_co_u32_e32 v55, vcc, 0, v49, vcc
	v_add_co_u32_e32 v168, vcc, s58, v50
	s_nop 1
	v_addc_co_u32_e32 v169, vcc, 0, v51, vcc
	global_load_dword v163, v[54:55], off
	global_load_dword v165, v[54:55], off offset:2048
	global_load_dword v166, v[168:169], off
	global_load_dword v167, v[168:169], off offset:2048
	v_add_co_u32_e32 v54, vcc, s64, v48
	s_nop 1
	v_addc_co_u32_e32 v55, vcc, 0, v49, vcc
	v_add_co_u32_e32 v172, vcc, s64, v50
	s_nop 1
	v_addc_co_u32_e32 v173, vcc, 0, v51, vcc
	global_load_dword v168, v[54:55], off
	global_load_dword v169, v[54:55], off offset:2048
	global_load_dword v170, v[172:173], off
	global_load_dword v171, v[172:173], off offset:2048
	v_add_co_u32_e32 v54, vcc, s59, v48
	s_nop 1
	v_addc_co_u32_e32 v55, vcc, 0, v49, vcc
	v_add_co_u32_e32 v176, vcc, s59, v50
	s_nop 1
	v_addc_co_u32_e32 v177, vcc, 0, v51, vcc
	v_add_co_u32_e32 v48, vcc, 0x7000, v48
	global_load_dword v172, v[54:55], off
	global_load_dword v173, v[54:55], off offset:2048
	global_load_dword v174, v[176:177], off
	global_load_dword v175, v[176:177], off offset:2048
	v_addc_co_u32_e32 v49, vcc, 0, v49, vcc
	v_add_co_u32_e32 v50, vcc, 0x7000, v50
	s_nop 1
	v_addc_co_u32_e32 v51, vcc, 0, v51, vcc
	global_load_dword v176, v[48:49], off
	global_load_dword v177, v[48:49], off offset:2048
	global_load_dword v187, v[50:51], off
	global_load_dword v188, v[50:51], off offset:2048
	global_load_dword v189, v[46:47], off
	global_load_dword v190, v[46:47], off offset:2048
	v_add_co_u32_e32 v48, vcc, 0x1000, v46
	s_nop 1
	v_addc_co_u32_e32 v49, vcc, 0, v47, vcc
	v_add_co_u32_e32 v50, vcc, 0x2000, v46
	s_nop 1
	v_addc_co_u32_e32 v51, vcc, 0, v47, vcc
	v_add_co_u32_e32 v46, vcc, 0x3000, v46
	s_nop 1
	v_addc_co_u32_e32 v47, vcc, 0, v47, vcc
	global_load_dword v191, v[48:49], off
	global_load_dword v192, v[48:49], off offset:2048
	global_load_dword v193, v[50:51], off
	global_load_dword v194, v[50:51], off offset:2048
	global_load_dword v195, v[46:47], off
	global_load_dword v196, v[46:47], off offset:2048
	s_branch .LBB0_1493
.LBB0_1498:
	s_or_b64 exec, exec, s[52:53]
	s_and_saveexec_b64 s[52:53], s[42:43]
	s_cbranch_execz .LBB0_1489
	v_ashrrev_i32_e32 v61, 31, v60
	v_lshlrev_b64 v[32:33], 16, v[60:61]
	v_lshl_add_u64 v[32:33], s[48:49], 0, v[32:33]
	v_lshl_add_u64 v[32:33], v[58:59], 2, v[32:33]
	s_waitcnt vmcnt(0)
	v_mov_b32_e32 v67, v57
	v_lshl_add_u64 v[32:33], v[32:33], 0, v[66:67]
	v_mov_b32_e32 v69, v57
	v_lshl_add_u64 v[32:33], v[32:33], 0, v[68:69]
	v_lshlrev_b32_e32 v56, 2, v122
	v_lshl_add_u64 v[32:33], v[32:33], 0, v[56:57]
	global_store_dword v[32:33], v0, off
	global_store_dword v[32:33], v1, off offset:512
	global_store_dword v[32:33], v2, off offset:1024
	global_store_dword v[32:33], v3, off offset:1536
	v_add_co_u32_e32 v0, vcc, s57, v32
	s_nop 1
	v_addc_co_u32_e32 v1, vcc, 0, v33, vcc
	global_store_dword v[0:1], v4, off
	global_store_dword v[0:1], v5, off offset:512
	global_store_dword v[0:1], v6, off offset:1024
	global_store_dword v[0:1], v7, off offset:1536
	v_add_co_u32_e32 v0, vcc, s58, v32
	s_nop 1
	v_addc_co_u32_e32 v1, vcc, 0, v33, vcc
	global_store_dword v[0:1], v12, off
	global_store_dword v[0:1], v13, off offset:512
	global_store_dword v[0:1], v14, off offset:1024
	global_store_dword v[0:1], v15, off offset:1536
	v_add_co_u32_e32 v0, vcc, s59, v32
	s_nop 1
	v_addc_co_u32_e32 v1, vcc, 0, v33, vcc
	global_store_dword v[0:1], v8, off
	global_store_dword v[0:1], v9, off offset:512
	global_store_dword v[0:1], v10, off offset:1024
	global_store_dword v[0:1], v11, off offset:1536
	v_add_co_u32_e32 v0, vcc, s60, v32
	s_nop 1
	v_addc_co_u32_e32 v1, vcc, 0, v33, vcc
	global_store_dword v[0:1], v20, off
	global_store_dword v[0:1], v21, off offset:512
	global_store_dword v[0:1], v22, off offset:1024
	global_store_dword v[0:1], v23, off offset:1536
	v_add_co_u32_e32 v0, vcc, s61, v32
	s_nop 1
	v_addc_co_u32_e32 v1, vcc, 0, v33, vcc
	global_store_dword v[0:1], v16, off
	global_store_dword v[0:1], v17, off offset:512
	global_store_dword v[0:1], v18, off offset:1024
	global_store_dword v[0:1], v19, off offset:1536
	v_add_co_u32_e32 v0, vcc, 0xc000, v32
	s_nop 1
	v_addc_co_u32_e32 v1, vcc, 0, v33, vcc
	global_store_dword v[0:1], v28, off
	global_store_dword v[0:1], v29, off offset:512
	global_store_dword v[0:1], v30, off offset:1024
	global_store_dword v[0:1], v31, off offset:1536
	v_add_co_u32_e32 v0, vcc, 0xe000, v32
	s_nop 1
	v_addc_co_u32_e32 v1, vcc, 0, v33, vcc
	global_store_dword v[0:1], v24, off
	global_store_dword v[0:1], v25, off offset:512
	global_store_dword v[0:1], v26, off offset:1024
	global_store_dword v[0:1], v27, off offset:1536
	s_branch .LBB0_1489

.LBB0_1503:
	v_add_u32_e32 v0, s60, v100
	s_movk_i32 s40, 0x80
	v_cmp_gt_i32_e32 vcc, s40, v0
	v_add_u32_e32 v1, 0xffffff80, v0
	v_cmp_lt_i32_e64 s[40:41], s33, v0
	v_mov_b32_e32 v12, v71
	v_mov_b32_e32 v13, v71
	v_cndmask_b32_e64 v0, v0, v1, s[40:41]
	v_lshrrev_b32_e32 v1, 31, v0
	v_add_u32_e32 v1, v0, v1
	v_and_b32_e32 v2, 0x3fffffe, v1
	v_bfe_u32 v34, v1, 1, 3
	v_ashrrev_i32_e32 v1, 31, v0
	v_lshrrev_b32_e32 v1, 28, v1
	v_sub_u32_e32 v2, v0, v2
	v_add_u32_e32 v0, v0, v1
	v_ashrrev_i32_e32 v32, 4, v0
	v_lshlrev_b32_e32 v74, 6, v2
	v_lshl_or_b32 v76, v32, 4, v34
	s_waitcnt vmcnt(0)
	v_ashrrev_i32_e32 v75, 31, v74
	v_ashrrev_i32_e32 v77, 31, v76
	v_mov_b32_e32 v14, v71
	v_mov_b32_e32 v15, v71
	v_mov_b32_e32 v0, v71
	v_mov_b32_e32 v1, v71
	v_mov_b32_e32 v2, v71
	v_mov_b32_e32 v3, v71
	v_mov_b32_e32 v8, v71
	v_mov_b32_e32 v9, v71
	v_mov_b32_e32 v10, v71
	v_mov_b32_e32 v11, v71
	v_mov_b32_e32 v4, v71
	v_mov_b32_e32 v5, v71
	v_mov_b32_e32 v6, v71
	v_mov_b32_e32 v7, v71
	v_mov_b32_e32 v20, v71
	v_mov_b32_e32 v21, v71
	v_mov_b32_e32 v22, v71
	v_mov_b32_e32 v23, v71
	v_mov_b32_e32 v16, v71
	v_mov_b32_e32 v17, v71
	v_mov_b32_e32 v18, v71
	v_mov_b32_e32 v19, v71
	v_mov_b32_e32 v24, v71
	v_mov_b32_e32 v25, v71
	v_mov_b32_e32 v26, v71
	v_mov_b32_e32 v27, v71
	v_mov_b32_e32 v28, v71
	v_mov_b32_e32 v29, v71
	v_mov_b32_e32 v30, v71
	v_mov_b32_e32 v31, v71
	s_and_saveexec_b64 s[56:57], vcc
	s_cbranch_execz .LBB0_1505
	v_readlane_b32 s80, v241, 18
	v_lshlrev_b64 v[0:1], 16, v[76:77]
	v_readlane_b32 s90, v241, 28
	v_readlane_b32 s91, v241, 29
	v_mov_b32_e32 v67, v71
	v_mov_b32_e32 v69, v71
	v_lshl_add_u64 v[0:1], s[90:91], 0, v[0:1]
	v_lshl_add_u64 v[0:1], v[74:75], 2, v[0:1]
	v_lshl_add_u64 v[0:1], v[0:1], 0, v[66:67]
	v_lshl_add_u64 v[0:1], v[0:1], 0, v[68:69]
	v_mov_b32_e32 v73, v71
	v_lshl_add_u64 v[24:25], v[0:1], 0, v[72:73]
	v_readlane_b32 s81, v241, 19
	v_add_co_u32_e32 v4, vcc, s61, v24
	v_readlane_b32 s82, v241, 20
	s_nop 0
	v_addc_co_u32_e32 v5, vcc, 0, v25, vcc
	global_load_dword v12, v[24:25], off
	global_load_dword v13, v[24:25], off offset:512
	global_load_dword v14, v[24:25], off offset:1024
	global_load_dword v15, v[24:25], off offset:1536
	global_load_dword v0, v[4:5], off
	global_load_dword v1, v[4:5], off offset:512
	global_load_dword v2, v[4:5], off offset:1024
	global_load_dword v3, v[4:5], off offset:1536
	v_add_co_u32_e32 v4, vcc, s62, v24
	v_readlane_b32 s83, v241, 21
	s_nop 0
	v_addc_co_u32_e32 v5, vcc, 0, v25, vcc
	v_add_co_u32_e32 v16, vcc, s63, v24
	v_readlane_b32 s84, v241, 22
	s_nop 0
	v_addc_co_u32_e32 v17, vcc, 0, v25, vcc
	global_load_dword v8, v[4:5], off
	global_load_dword v9, v[4:5], off offset:512
	global_load_dword v10, v[4:5], off offset:1024
	global_load_dword v11, v[4:5], off offset:1536
	s_nop 0
	global_load_dword v4, v[16:17], off
	global_load_dword v5, v[16:17], off offset:512
	global_load_dword v6, v[16:17], off offset:1024
	global_load_dword v7, v[16:17], off offset:1536
	v_add_co_u32_e32 v16, vcc, s64, v24
	v_readlane_b32 s85, v241, 23
	s_nop 0
	v_addc_co_u32_e32 v17, vcc, 0, v25, vcc
	v_add_co_u32_e32 v26, vcc, s65, v24
	v_readlane_b32 s86, v241, 24
	s_nop 0
	v_addc_co_u32_e32 v27, vcc, 0, v25, vcc
	v_add_co_u32_e32 v28, vcc, 0xc000, v24
	global_load_dword v20, v[16:17], off
	global_load_dword v21, v[16:17], off offset:512
	global_load_dword v22, v[16:17], off offset:1024
	global_load_dword v23, v[16:17], off offset:1536
	s_nop 0
	global_load_dword v16, v[26:27], off
	global_load_dword v17, v[26:27], off offset:512
	global_load_dword v18, v[26:27], off offset:1024
	global_load_dword v19, v[26:27], off offset:1536
	v_addc_co_u32_e32 v29, vcc, 0, v25, vcc
	v_add_co_u32_e32 v36, vcc, 0xe000, v24
	v_readlane_b32 s87, v241, 25
	s_nop 0
	v_addc_co_u32_e32 v37, vcc, 0, v25, vcc
	global_load_dword v24, v[28:29], off
	global_load_dword v25, v[28:29], off offset:512
	global_load_dword v26, v[28:29], off offset:1024
	global_load_dword v27, v[28:29], off offset:1536
	s_nop 0
	global_load_dword v28, v[36:37], off
	global_load_dword v29, v[36:37], off offset:512
	global_load_dword v30, v[36:37], off offset:1024
	global_load_dword v31, v[36:37], off offset:1536
	v_readlane_b32 s88, v241, 26
	v_readlane_b32 s89, v241, 27
	v_readlane_b32 s92, v241, 30
	v_readlane_b32 s93, v241, 31
	v_readlane_b32 s94, v241, 32
	v_readlane_b32 s95, v241, 33
	v_readlane_b32 s80, v241, 37
	v_readlane_b32 s92, v241, 49
	v_readlane_b32 s93, v241, 50
	v_readlane_b32 s94, v241, 51
	v_readlane_b32 s95, v241, 52
	v_readlane_b32 s81, v241, 38
	v_readlane_b32 s82, v241, 39
	v_readlane_b32 s83, v241, 40
	v_readlane_b32 s84, v241, 41
	v_readlane_b32 s85, v241, 42
	v_readlane_b32 s86, v241, 43
	v_readlane_b32 s87, v241, 44
	v_readlane_b32 s88, v241, 45
	v_readlane_b32 s89, v241, 46
	v_readlane_b32 s90, v241, 47
	v_readlane_b32 s91, v241, 48
.LBB0_1505:
	s_or_b64 exec, exec, s[56:57]
	v_ashrrev_i32_e32 v33, 31, v32
	v_lshlrev_b64 v[36:37], 11, v[32:33]
	s_mov_b64 s[56:57], 0x2000
	v_lshl_add_u64 v[36:37], v[36:37], 0, s[56:57]
	v_lshlrev_b64 v[32:33], 8, v[32:33]
	v_cndmask_b32_e64 v33, v37, v33, s[40:41]
	v_cndmask_b32_e64 v32, v36, v32, s[40:41]
	v_lshlrev_b64 v[32:33], 11, v[32:33]
	v_lshl_add_u64 v[36:37], s[68:69], 0, v[32:33]
	v_lshlrev_b32_e32 v70, 8, v34
	v_lshl_add_u64 v[38:39], s[46:47], 0, v[32:33]
	v_lshl_add_u64 v[34:35], v[36:37], 0, v[70:71]
	v_lshl_add_u64 v[36:37], s[44:45], 0, v[32:33]
	v_lshl_add_u64 v[38:39], v[38:39], 0, v[70:71]
	v_lshlrev_b64 v[40:41], 1, v[74:75]
	v_lshl_add_u64 v[32:33], s[48:49], 0, v[32:33]
	v_lshl_add_u64 v[36:37], v[36:37], 0, v[70:71]
	v_lshl_add_u64 v[38:39], v[38:39], 0, v[40:41]
	v_lshl_add_u64 v[32:33], v[32:33], 0, v[70:71]
	v_lshlrev_b32_e32 v70, 2, v102
	v_mov_b32_e32 v65, v71
	v_lshl_add_u64 v[34:35], v[34:35], 0, v[70:71]
	v_lshl_add_u64 v[36:37], v[36:37], 0, v[70:71]
	v_lshl_add_u64 v[38:39], v[38:39], 0, v[64:65]
	v_mov_b64_e32 v[42:43], v[38:39]
	v_mov_b64_e32 v[44:45], v[36:37]
	v_mov_b64_e32 v[46:47], v[34:35]
	global_load_dword v65, v[46:47], off
	global_load_dword v67, v[46:47], off offset:2048
	global_load_dword v69, v[44:45], off
	global_load_dword v73, v[44:45], off offset:2048
	v_add_co_u32_e32 v48, vcc, s66, v46
	v_lshl_add_u64 v[32:33], v[32:33], 0, v[40:41]
	s_nop 0
	v_addc_co_u32_e32 v49, vcc, 0, v47, vcc
	v_add_co_u32_e32 v50, vcc, s66, v44
	v_lshlrev_b32_e32 v70, 1, v112
	s_nop 0
	v_addc_co_u32_e32 v51, vcc, 0, v45, vcc
	global_load_dword v96, v[48:49], off
	global_load_dword v97, v[48:49], off offset:2048
	global_load_dword v98, v[50:51], off
	global_load_dword v122, v[50:51], off offset:2048
	v_add_co_u32_e32 v48, vcc, s61, v46
	v_cndmask_b32_e64 v133, 32, 4, s[40:41]
	s_nop 0
	v_addc_co_u32_e32 v49, vcc, 0, v47, vcc
	v_add_co_u32_e32 v50, vcc, s61, v44
	s_mov_b32 s74, 0
	s_nop 0
	v_addc_co_u32_e32 v51, vcc, 0, v45, vcc
	global_load_dword v123, v[48:49], off
	global_load_dword v124, v[48:49], off offset:2048
	global_load_dword v125, v[50:51], off
	global_load_dword v126, v[50:51], off offset:2048
	v_add_co_u32_e32 v48, vcc, s67, v46
	v_lshl_add_u64 v[78:79], v[32:33], 0, v[70:71]
	s_nop 0
	v_addc_co_u32_e32 v49, vcc, 0, v47, vcc
	v_add_co_u32_e32 v50, vcc, s67, v44
	v_lshl_add_u64 v[80:81], v[38:39], 0, s[54:55]
	s_nop 0
	v_addc_co_u32_e32 v51, vcc, 0, v45, vcc
	global_load_dword v127, v[48:49], off
	global_load_dword v128, v[48:49], off offset:2048
	global_load_dword v129, v[50:51], off
	global_load_dword v130, v[50:51], off offset:2048
	v_add_co_u32_e32 v48, vcc, s62, v46
	v_lshl_add_u64 v[82:83], v[36:37], 0, s[54:55]
	s_nop 0
	v_addc_co_u32_e32 v49, vcc, 0, v47, vcc
	v_add_co_u32_e32 v50, vcc, s62, v44
	v_lshl_add_u64 v[84:85], v[34:35], 0, s[54:55]
	s_nop 0
	v_addc_co_u32_e32 v51, vcc, 0, v45, vcc
	global_load_dword v131, v[48:49], off
	global_load_dword v132, v[48:49], off offset:2048
	global_load_dword v134, v[50:51], off
	global_load_dword v135, v[50:51], off offset:2048
	v_add_co_u32_e32 v48, vcc, s72, v46
	s_mov_b64 s[56:57], 0
	s_nop 0
	v_addc_co_u32_e32 v49, vcc, 0, v47, vcc
	v_add_co_u32_e32 v50, vcc, s72, v44
	v_mov_b32_e32 v70, v90
	s_nop 0
	v_addc_co_u32_e32 v51, vcc, 0, v45, vcc
	global_load_dword v136, v[48:49], off
	global_load_dword v137, v[48:49], off offset:2048
	global_load_dword v138, v[50:51], off
	global_load_dword v139, v[50:51], off offset:2048
	v_add_co_u32_e32 v48, vcc, s63, v46
	s_nop 1
	v_addc_co_u32_e32 v49, vcc, 0, v47, vcc
	v_add_co_u32_e32 v50, vcc, s63, v44
	s_nop 1
	v_addc_co_u32_e32 v51, vcc, 0, v45, vcc
	v_add_co_u32_e32 v46, vcc, s73, v46
	global_load_dword v140, v[48:49], off
	global_load_dword v141, v[48:49], off offset:2048
	global_load_dword v142, v[50:51], off
	global_load_dword v143, v[50:51], off offset:2048
	v_addc_co_u32_e32 v47, vcc, 0, v47, vcc
	v_add_co_u32_e32 v44, vcc, s73, v44
	s_nop 1
	v_addc_co_u32_e32 v45, vcc, 0, v45, vcc
	global_load_dword v144, v[46:47], off
	global_load_dword v145, v[46:47], off offset:2048
	global_load_dword v146, v[44:45], off
	global_load_dword v147, v[44:45], off offset:2048
	global_load_dword v148, v[42:43], off
	global_load_dword v149, v[42:43], off offset:2048
	v_add_co_u32_e32 v44, vcc, s66, v42
	s_nop 1
	v_addc_co_u32_e32 v45, vcc, 0, v43, vcc
	v_add_co_u32_e32 v46, vcc, s61, v42
	s_nop 1
	v_addc_co_u32_e32 v47, vcc, 0, v43, vcc
	v_add_co_u32_e32 v42, vcc, 0x3000, v42
	s_nop 1
	v_addc_co_u32_e32 v43, vcc, 0, v43, vcc
	global_load_dword v150, v[44:45], off
	global_load_dword v151, v[44:45], off offset:2048
	global_load_dword v152, v[46:47], off
	global_load_dword v153, v[46:47], off offset:2048
	global_load_dword v154, v[42:43], off
	global_load_dword v155, v[42:43], off offset:2048
	s_waitcnt vmcnt(0)
	s_branch .LBB0_1507

.LBB0_1507:
	s_waitcnt vmcnt(4) lgkmcnt(0)
	v_lshlrev_b32_e32 v34, 16, v69
	v_and_b32_e32 v35, 0xffff0000, v69
	v_lshlrev_b32_e32 v38, 16, v73
	v_and_b32_e32 v39, 0xffff0000, v73
	v_pk_add_f32 v[32:33], v[34:35], 0 op_sel_hi:[1,0]
	v_lshlrev_b32_e32 v40, 16, v98
	v_and_b32_e32 v41, 0xffff0000, v98
	v_pk_add_f32 v[32:33], v[32:33], v[38:39]
	v_lshlrev_b32_e32 v42, 16, v122
	v_and_b32_e32 v43, 0xffff0000, v122
	v_pk_add_f32 v[32:33], v[32:33], v[40:41]
	v_lshlrev_b32_e32 v44, 16, v125
	v_and_b32_e32 v45, 0xffff0000, v125
	v_pk_add_f32 v[32:33], v[32:33], v[42:43]
	v_lshlrev_b32_e32 v46, 16, v126
	v_pk_add_f32 v[32:33], v[32:33], v[44:45]
	v_and_b32_e32 v47, 0xffff0000, v126
	v_lshlrev_b32_e32 v48, 16, v129
	v_and_b32_e32 v49, 0xffff0000, v129
	v_pk_add_f32 v[32:33], v[32:33], v[46:47]
	v_lshlrev_b32_e32 v50, 16, v130
	v_and_b32_e32 v51, 0xffff0000, v130
	v_pk_add_f32 v[32:33], v[32:33], v[48:49]
	v_lshlrev_b32_e32 v52, 16, v134
	v_and_b32_e32 v53, 0xffff0000, v134
	v_pk_add_f32 v[32:33], v[32:33], v[50:51]
	v_lshlrev_b32_e32 v54, 16, v135
	v_and_b32_e32 v55, 0xffff0000, v135
	v_pk_add_f32 v[32:33], v[32:33], v[52:53]
	v_lshlrev_b32_e32 v56, 16, v138
	v_and_b32_e32 v57, 0xffff0000, v138
	v_pk_add_f32 v[32:33], v[32:33], v[54:55]
	v_lshlrev_b32_e32 v60, 16, v139
	v_and_b32_e32 v61, 0xffff0000, v139
	v_pk_add_f32 v[32:33], v[32:33], v[56:57]
	v_lshlrev_b32_e32 v86, 16, v142
	v_and_b32_e32 v87, 0xffff0000, v142
	v_pk_add_f32 v[32:33], v[32:33], v[60:61]
	v_lshlrev_b32_e32 v88, 16, v143
	v_and_b32_e32 v89, 0xffff0000, v143
	v_pk_add_f32 v[32:33], v[32:33], v[86:87]
	v_lshlrev_b32_e32 v62, 16, v146
	v_and_b32_e32 v63, 0xffff0000, v146
	v_pk_add_f32 v[32:33], v[32:33], v[88:89]
	v_lshlrev_b32_e32 v58, 16, v147
	v_and_b32_e32 v59, 0xffff0000, v147
	v_pk_add_f32 v[32:33], v[32:33], v[62:63]
	v_add_u32_e32 v36, v101, v103
	v_pk_add_f32 v[32:33], v[32:33], v[58:59]
	ds_write_b64 v36, v[32:33]
	s_waitcnt lgkmcnt(0)
	s_barrier
	ds_read_b64 v[32:33], v105
	ds_read_b64 v[36:37], v106
	ds_read_b64 v[156:157], v101
	ds_read_b64 v[158:159], v104
	v_mov_b32_e32 v162, v34
	v_exp_f32_e32 v160, v34
	s_waitcnt lgkmcnt(2)
	v_add_f32_e32 v164, v32, v36
	v_add_f32_e32 v165, v33, v37
	s_waitcnt lgkmcnt(1)
	v_cndmask_b32_e64 v36, v156, 0, s[42:43]
	s_waitcnt lgkmcnt(0)
	v_cndmask_b32_e64 v37, 0, v158, s[2:3]
	v_add_f32_e32 v36, v36, v37
	v_cndmask_b32_e64 v32, 0, v32, s[4:5]
	v_add_f32_e32 v32, v36, v32
	v_cndmask_b32_e64 v36, v157, 0, s[42:43]
	v_cndmask_b32_e64 v37, 0, v159, s[2:3]
	v_add_f32_e32 v36, v36, v37
	v_cndmask_b32_e64 v33, 0, v33, s[4:5]
	v_add_f32_e32 v36, v36, v33
	v_mov_b32_e32 v33, v156
	v_mov_b32_e32 v163, v158
	v_mov_b32_e32 v37, v157
	v_mov_b32_e32 v158, v35
	v_exp_f32_e32 v161, v35
	v_pk_add_f32 v[32:33], v[32:33], v[162:163]
	v_pk_add_f32 v[34:35], v[36:37], v[158:159]
	v_sub_f32_e32 v36, v32, v33
	v_sub_f32_e32 v37, v34, v35
	v_exp_f32_e32 v36, v36
	v_exp_f32_e32 v37, v37
	v_lshlrev_b32_e32 v158, 16, v65
	v_and_b32_e32 v159, 0xffff0000, v65
	v_add_f32_e32 v156, v33, v164
	v_pk_mul_f32 v[36:37], v[36:37], v[158:159]
	v_sub_f32_e32 v158, v33, v32
	v_sub_f32_e32 v159, v35, v34
	v_exp_f32_e32 v158, v158
	v_exp_f32_e32 v159, v159
	v_cvt_pk_bf16_f32 v162, v36, v37
	v_pk_add_f32 v[36:37], v[160:161], 1.0 op_sel_hi:[1,0] neg_lo:[1,0] neg_hi:[1,0]
	v_add_f32_e32 v32, v32, v38
	v_pk_mul_f32 v[36:37], v[36:37], v[158:159]
	v_exp_f32_e32 v158, v38
	v_sub_f32_e32 v38, v32, v33
	v_add_f32_e32 v34, v34, v39
	v_exp_f32_e32 v160, v38
	v_sub_f32_e32 v38, v34, v35
	v_exp_f32_e32 v161, v38
	v_exp_f32_e32 v159, v39
	v_lshlrev_b32_e32 v38, 16, v67
	v_and_b32_e32 v39, 0xffff0000, v67
	v_pk_mul_f32 v[38:39], v[160:161], v[38:39]
	v_sub_f32_e32 v160, v33, v32
	v_sub_f32_e32 v161, v35, v34
	v_exp_f32_e32 v160, v160
	v_exp_f32_e32 v161, v161
	v_add_u32_e32 v164, v107, v121
	v_cvt_pk_bf16_f32 v38, v38, v39
	ds_write2_b32 v164, v162, v38 offset1:68
	v_pk_add_f32 v[38:39], v[158:159], 1.0 op_sel_hi:[1,0] neg_lo:[1,0] neg_hi:[1,0]
	v_add_f32_e32 v157, v35, v165
	v_pk_mul_f32 v[38:39], v[38:39], v[160:161]
	v_cvt_pk_bf16_f32 v163, v36, v37
	v_cvt_pk_bf16_f32 v158, v38, v39
	v_add_u32_e32 v165, 0x4400, v164
	v_add_f32_e32 v32, v32, v40
	v_add_f32_e32 v34, v34, v41
	ds_write2_b32 v165, v163, v158 offset1:68
	v_exp_f32_e32 v158, v40
	v_exp_f32_e32 v159, v41
	v_sub_f32_e32 v40, v32, v33
	v_sub_f32_e32 v41, v34, v35
	v_exp_f32_e32 v40, v40
	v_exp_f32_e32 v41, v41
	v_lshlrev_b32_e32 v160, 16, v96
	v_and_b32_e32 v161, 0xffff0000, v96
	v_sub_f32_e32 v162, v33, v32
	v_pk_mul_f32 v[40:41], v[40:41], v[160:161]
	v_add_f32_e32 v32, v32, v42
	v_sub_f32_e32 v163, v35, v34
	v_cvt_pk_bf16_f32 v166, v40, v41
	v_pk_add_f32 v[40:41], v[158:159], 1.0 op_sel_hi:[1,0] neg_lo:[1,0] neg_hi:[1,0]
	v_exp_f32_e32 v158, v42
	v_sub_f32_e32 v42, v32, v33
	v_add_f32_e32 v34, v34, v43
	v_exp_f32_e32 v160, v42
	v_sub_f32_e32 v42, v34, v35
	v_exp_f32_e32 v161, v42
	v_exp_f32_e32 v159, v43
	v_lshlrev_b32_e32 v42, 16, v97
	v_and_b32_e32 v43, 0xffff0000, v97
	v_pk_mul_f32 v[42:43], v[160:161], v[42:43]
	v_sub_f32_e32 v160, v33, v32
	v_sub_f32_e32 v161, v35, v34
	v_exp_f32_e32 v162, v162
	v_exp_f32_e32 v163, v163
	v_exp_f32_e32 v160, v160
	v_exp_f32_e32 v161, v161
	v_cvt_pk_bf16_f32 v42, v42, v43
	ds_write2_b32 v164, v166, v42 offset0:136 offset1:204
	v_pk_add_f32 v[42:43], v[158:159], 1.0 op_sel_hi:[1,0] neg_lo:[1,0] neg_hi:[1,0]
	v_add_f32_e32 v32, v32, v44
	v_add_f32_e32 v34, v34, v45
	v_pk_mul_f32 v[40:41], v[40:41], v[162:163]
	v_pk_mul_f32 v[42:43], v[42:43], v[160:161]
	v_sub_f32_e32 v160, v32, v33
	v_sub_f32_e32 v161, v34, v35
	v_cvt_pk_bf16_f32 v162, v40, v41
	v_cvt_pk_bf16_f32 v158, v42, v43
	v_exp_f32_e32 v160, v160
	v_exp_f32_e32 v161, v161
	ds_write2_b32 v165, v162, v158 offset0:136 offset1:204
	v_exp_f32_e32 v158, v44
	v_exp_f32_e32 v159, v45
	v_lshlrev_b32_e32 v44, 16, v123
	v_and_b32_e32 v45, 0xffff0000, v123
	v_sub_f32_e32 v162, v33, v32
	v_pk_mul_f32 v[44:45], v[160:161], v[44:45]
	v_add_f32_e32 v32, v32, v46
	v_sub_f32_e32 v163, v35, v34
	v_cvt_pk_bf16_f32 v165, v44, v45
	v_pk_add_f32 v[44:45], v[158:159], 1.0 op_sel_hi:[1,0] neg_lo:[1,0] neg_hi:[1,0]
	v_exp_f32_e32 v158, v46
	v_add_f32_e32 v34, v34, v47
	v_sub_f32_e32 v46, v32, v33
	v_exp_f32_e32 v160, v46
	v_sub_f32_e32 v46, v34, v35
	v_exp_f32_e32 v161, v46
	v_exp_f32_e32 v159, v47
	v_lshlrev_b32_e32 v46, 16, v124
	v_and_b32_e32 v47, 0xffff0000, v124
	v_pk_mul_f32 v[46:47], v[160:161], v[46:47]
	v_exp_f32_e32 v162, v162
	v_cvt_pk_bf16_f32 v160, v46, v47
	v_sub_f32_e32 v46, v33, v32
	v_sub_f32_e32 v47, v35, v34
	v_exp_f32_e32 v163, v163
	v_exp_f32_e32 v46, v46
	v_exp_f32_e32 v47, v47
	v_add_u32_e32 v166, 0x400, v164
	v_pk_add_f32 v[158:159], v[158:159], 1.0 op_sel_hi:[1,0] neg_lo:[1,0] neg_hi:[1,0]
	v_add_f32_e32 v32, v32, v48
	v_add_f32_e32 v34, v34, v49
	v_pk_mul_f32 v[44:45], v[44:45], v[162:163]
	ds_write2_b32 v166, v165, v160 offset0:16 offset1:84
	v_pk_mul_f32 v[46:47], v[158:159], v[46:47]
	v_sub_f32_e32 v160, v32, v33
	v_sub_f32_e32 v161, v34, v35
	v_cvt_pk_bf16_f32 v162, v44, v45
	v_cvt_pk_bf16_f32 v158, v46, v47
	v_add_u32_e32 v165, 0x4800, v164
	v_exp_f32_e32 v160, v160
	v_exp_f32_e32 v161, v161
	ds_write2_b32 v165, v162, v158 offset0:16 offset1:84
	v_exp_f32_e32 v158, v48
	v_exp_f32_e32 v159, v49
	v_lshlrev_b32_e32 v48, 16, v127
	v_and_b32_e32 v49, 0xffff0000, v127
	v_sub_f32_e32 v162, v33, v32
	v_pk_mul_f32 v[48:49], v[160:161], v[48:49]
	v_add_f32_e32 v32, v32, v50
	v_sub_f32_e32 v163, v35, v34
	v_cvt_pk_bf16_f32 v167, v48, v49
	v_pk_add_f32 v[48:49], v[158:159], 1.0 op_sel_hi:[1,0] neg_lo:[1,0] neg_hi:[1,0]
	v_exp_f32_e32 v158, v50
	v_add_f32_e32 v34, v34, v51
	v_sub_f32_e32 v50, v32, v33
	v_exp_f32_e32 v160, v50
	v_sub_f32_e32 v50, v34, v35
	v_exp_f32_e32 v161, v50
	v_exp_f32_e32 v159, v51
	v_lshlrev_b32_e32 v50, 16, v128
	v_and_b32_e32 v51, 0xffff0000, v128
	v_pk_mul_f32 v[50:51], v[160:161], v[50:51]
	v_sub_f32_e32 v160, v33, v32
	v_sub_f32_e32 v161, v35, v34
	v_exp_f32_e32 v162, v162
	v_exp_f32_e32 v163, v163
	v_exp_f32_e32 v160, v160
	v_exp_f32_e32 v161, v161
	v_cvt_pk_bf16_f32 v50, v50, v51
	ds_write2_b32 v166, v167, v50 offset0:152 offset1:220
	v_pk_add_f32 v[50:51], v[158:159], 1.0 op_sel_hi:[1,0] neg_lo:[1,0] neg_hi:[1,0]
	v_add_f32_e32 v32, v32, v52
	v_add_f32_e32 v34, v34, v53
	v_pk_mul_f32 v[48:49], v[48:49], v[162:163]
	v_pk_mul_f32 v[50:51], v[50:51], v[160:161]
	v_sub_f32_e32 v160, v32, v33
	v_sub_f32_e32 v161, v34, v35
	v_cvt_pk_bf16_f32 v162, v48, v49
	v_cvt_pk_bf16_f32 v158, v50, v51
	v_exp_f32_e32 v160, v160
	v_exp_f32_e32 v161, v161
	ds_write2_b32 v165, v162, v158 offset0:152 offset1:220
	v_exp_f32_e32 v158, v52
	v_exp_f32_e32 v159, v53
	v_lshlrev_b32_e32 v52, 16, v131
	v_and_b32_e32 v53, 0xffff0000, v131
	v_sub_f32_e32 v162, v33, v32
	v_pk_mul_f32 v[52:53], v[160:161], v[52:53]
	v_add_f32_e32 v32, v32, v54
	v_sub_f32_e32 v163, v35, v34
	v_cvt_pk_bf16_f32 v165, v52, v53
	v_pk_add_f32 v[52:53], v[158:159], 1.0 op_sel_hi:[1,0] neg_lo:[1,0] neg_hi:[1,0]
	v_exp_f32_e32 v158, v54
	v_add_f32_e32 v34, v34, v55
	v_sub_f32_e32 v54, v32, v33
	v_exp_f32_e32 v160, v54
	v_sub_f32_e32 v54, v34, v35
	v_exp_f32_e32 v161, v54
	v_exp_f32_e32 v159, v55
	v_lshlrev_b32_e32 v54, 16, v132
	v_and_b32_e32 v55, 0xffff0000, v132
	v_pk_mul_f32 v[54:55], v[160:161], v[54:55]
	v_exp_f32_e32 v162, v162
	v_cvt_pk_bf16_f32 v160, v54, v55
	v_sub_f32_e32 v54, v33, v32
	v_sub_f32_e32 v55, v35, v34
	v_exp_f32_e32 v163, v163
	v_exp_f32_e32 v54, v54
	v_exp_f32_e32 v55, v55
	v_add_u32_e32 v166, 0x800, v164
	v_pk_add_f32 v[158:159], v[158:159], 1.0 op_sel_hi:[1,0] neg_lo:[1,0] neg_hi:[1,0]
	v_add_f32_e32 v32, v32, v56
	v_add_f32_e32 v34, v34, v57
	v_pk_mul_f32 v[52:53], v[52:53], v[162:163]
	ds_write2_b32 v166, v165, v160 offset0:32 offset1:100
	v_pk_mul_f32 v[54:55], v[158:159], v[54:55]
	v_sub_f32_e32 v160, v32, v33
	v_sub_f32_e32 v161, v34, v35
	v_cvt_pk_bf16_f32 v162, v52, v53
	v_cvt_pk_bf16_f32 v158, v54, v55
	v_add_u32_e32 v165, 0x4c00, v164
	v_exp_f32_e32 v160, v160
	v_exp_f32_e32 v161, v161
	ds_write2_b32 v165, v162, v158 offset0:32 offset1:100
	v_exp_f32_e32 v158, v56
	v_exp_f32_e32 v159, v57
	v_lshlrev_b32_e32 v56, 16, v136
	v_and_b32_e32 v57, 0xffff0000, v136
	v_sub_f32_e32 v162, v33, v32
	v_pk_mul_f32 v[56:57], v[160:161], v[56:57]
	v_add_f32_e32 v32, v32, v60
	v_sub_f32_e32 v163, v35, v34
	v_cvt_pk_bf16_f32 v167, v56, v57
	v_pk_add_f32 v[56:57], v[158:159], 1.0 op_sel_hi:[1,0] neg_lo:[1,0] neg_hi:[1,0]
	v_exp_f32_e32 v158, v60
	v_add_f32_e32 v34, v34, v61
	v_sub_f32_e32 v60, v32, v33
	v_exp_f32_e32 v160, v60
	v_sub_f32_e32 v60, v34, v35
	v_exp_f32_e32 v161, v60
	v_exp_f32_e32 v159, v61
	v_lshlrev_b32_e32 v60, 16, v137
	v_and_b32_e32 v61, 0xffff0000, v137
	v_pk_mul_f32 v[60:61], v[160:161], v[60:61]
	v_sub_f32_e32 v160, v33, v32
	v_sub_f32_e32 v161, v35, v34
	v_exp_f32_e32 v162, v162
	v_exp_f32_e32 v163, v163
	v_exp_f32_e32 v160, v160
	v_exp_f32_e32 v161, v161
	v_cvt_pk_bf16_f32 v60, v60, v61
	ds_write2_b32 v166, v167, v60 offset0:168 offset1:236
	v_pk_add_f32 v[60:61], v[158:159], 1.0 op_sel_hi:[1,0] neg_lo:[1,0] neg_hi:[1,0]
	v_add_f32_e32 v32, v32, v86
	v_add_f32_e32 v34, v34, v87
	v_pk_mul_f32 v[56:57], v[56:57], v[162:163]
	v_pk_mul_f32 v[60:61], v[60:61], v[160:161]
	v_sub_f32_e32 v160, v32, v33
	v_sub_f32_e32 v161, v34, v35
	v_cvt_pk_bf16_f32 v162, v56, v57
	v_cvt_pk_bf16_f32 v158, v60, v61
	v_exp_f32_e32 v160, v160
	v_exp_f32_e32 v161, v161
	ds_write2_b32 v165, v162, v158 offset0:168 offset1:236
	v_exp_f32_e32 v158, v86
	v_exp_f32_e32 v159, v87
	v_lshlrev_b32_e32 v86, 16, v140
	v_and_b32_e32 v87, 0xffff0000, v140
	v_sub_f32_e32 v162, v33, v32
	v_pk_mul_f32 v[86:87], v[160:161], v[86:87]
	v_add_f32_e32 v32, v32, v88
	v_sub_f32_e32 v163, v35, v34
	v_cvt_pk_bf16_f32 v165, v86, v87
	v_pk_add_f32 v[86:87], v[158:159], 1.0 op_sel_hi:[1,0] neg_lo:[1,0] neg_hi:[1,0]
	v_exp_f32_e32 v158, v88
	v_add_f32_e32 v34, v34, v89
	v_sub_f32_e32 v88, v32, v33
	v_exp_f32_e32 v160, v88
	v_sub_f32_e32 v88, v34, v35
	v_exp_f32_e32 v161, v88
	v_exp_f32_e32 v159, v89
	v_lshlrev_b32_e32 v88, 16, v141
	v_and_b32_e32 v89, 0xffff0000, v141
	v_pk_mul_f32 v[88:89], v[160:161], v[88:89]
	v_exp_f32_e32 v162, v162
	v_cvt_pk_bf16_f32 v160, v88, v89
	v_sub_f32_e32 v88, v33, v32
	v_sub_f32_e32 v89, v35, v34
	v_exp_f32_e32 v163, v163
	v_exp_f32_e32 v88, v88
	v_exp_f32_e32 v89, v89
	v_add_u32_e32 v166, 0xc00, v164
	v_pk_add_f32 v[158:159], v[158:159], 1.0 op_sel_hi:[1,0] neg_lo:[1,0] neg_hi:[1,0]
	v_add_f32_e32 v32, v32, v62
	v_add_f32_e32 v34, v34, v63
	v_pk_mul_f32 v[86:87], v[86:87], v[162:163]
	ds_write2_b32 v166, v165, v160 offset0:48 offset1:116
	v_pk_mul_f32 v[88:89], v[158:159], v[88:89]
	v_sub_f32_e32 v160, v32, v33
	v_sub_f32_e32 v161, v34, v35
	v_cvt_pk_bf16_f32 v162, v86, v87
	v_cvt_pk_bf16_f32 v158, v88, v89
	v_add_u32_e32 v164, 0x5000, v164
	v_exp_f32_e32 v160, v160
	v_exp_f32_e32 v161, v161
	ds_write2_b32 v164, v162, v158 offset0:48 offset1:116
	v_exp_f32_e32 v158, v62
	v_exp_f32_e32 v159, v63
	v_lshlrev_b32_e32 v62, 16, v144
	v_and_b32_e32 v63, 0xffff0000, v144
	v_sub_f32_e32 v162, v33, v32
	v_pk_mul_f32 v[62:63], v[160:161], v[62:63]
	v_add_f32_e32 v32, v32, v58
	v_sub_f32_e32 v163, v35, v34
	v_cvt_pk_bf16_f32 v165, v62, v63
	v_pk_add_f32 v[62:63], v[158:159], 1.0 op_sel_hi:[1,0] neg_lo:[1,0] neg_hi:[1,0]
	v_exp_f32_e32 v158, v58
	v_add_f32_e32 v34, v34, v59
	v_sub_f32_e32 v58, v32, v33
	v_exp_f32_e32 v160, v58
	v_sub_f32_e32 v58, v34, v35
	v_exp_f32_e32 v161, v58
	v_exp_f32_e32 v159, v59
	v_lshlrev_b32_e32 v58, 16, v145
	v_and_b32_e32 v59, 0xffff0000, v145
	v_sub_f32_e32 v32, v33, v32
	v_pk_mul_f32 v[58:59], v[160:161], v[58:59]
	v_exp_f32_e32 v160, v32
	v_sub_f32_e32 v32, v35, v34
	v_exp_f32_e32 v162, v162
	v_exp_f32_e32 v163, v163
	v_exp_f32_e32 v161, v32
	v_cvt_pk_bf16_f32 v32, v58, v59
	v_pk_add_f32 v[58:59], v[158:159], 1.0 op_sel_hi:[1,0] neg_lo:[1,0] neg_hi:[1,0]
	v_pk_mul_f32 v[62:63], v[62:63], v[162:163]
	v_pk_mul_f32 v[58:59], v[58:59], v[160:161]
	v_cvt_pk_bf16_f32 v162, v62, v63
	ds_write2_b32 v166, v165, v32 offset0:184 offset1:252
	v_cvt_pk_bf16_f32 v32, v58, v59
	ds_write2_b32 v164, v162, v32 offset0:184 offset1:252
	s_and_saveexec_b64 s[58:59], s[42:43]
	s_cbranch_execz .LBB0_1509
	v_exp_f32_e32 v161, v157
	v_exp_f32_e32 v160, v156
	v_exp_f32_e32 v159, v35
	v_exp_f32_e32 v158, v33
	ds_write_b64 v110, v[160:161]
	ds_write_b64 v111, v[158:159]
.LBB0_1509:
	s_or_b64 exec, exec, s[58:59]
	v_lshlrev_b32_e32 v32, 16, v151
	v_lshlrev_b32_e32 v34, 16, v149
	v_lshlrev_b32_e32 v160, 16, v155
	v_lshlrev_b32_e32 v162, 16, v153
	v_or_b32_sdwa v159, v150, v32 dst_sel:DWORD dst_unused:UNUSED_PAD src0_sel:WORD_0 src1_sel:DWORD
	v_or_b32_sdwa v158, v148, v34 dst_sel:DWORD dst_unused:UNUSED_PAD src0_sel:WORD_0 src1_sel:DWORD
	v_add_u32_e32 v32, v108, v109
	v_or_b32_sdwa v161, v154, v160 dst_sel:DWORD dst_unused:UNUSED_PAD src0_sel:WORD_0 src1_sel:DWORD
	v_or_b32_sdwa v160, v152, v162 dst_sel:DWORD dst_unused:UNUSED_PAD src0_sel:WORD_0 src1_sel:DWORD
	v_and_b32_e32 v34, 0xffff0000, v151
	ds_write_b128 v32, v[158:161] offset:35840
	v_and_b32_e32 v158, 0xffff0000, v149
	v_or_b32_sdwa v159, v150, v34 dst_sel:DWORD dst_unused:UNUSED_PAD src0_sel:WORD_1 src1_sel:DWORD
	v_and_b32_e32 v34, 0xffff0000, v155
	v_and_b32_e32 v160, 0xffff0000, v153
	s_add_i32 s74, s74, 1
	v_or_b32_sdwa v158, v148, v158 dst_sel:DWORD dst_unused:UNUSED_PAD src0_sel:WORD_1 src1_sel:DWORD
	v_or_b32_sdwa v161, v154, v34 dst_sel:DWORD dst_unused:UNUSED_PAD src0_sel:WORD_1 src1_sel:DWORD
	v_or_b32_sdwa v160, v152, v160 dst_sel:DWORD dst_unused:UNUSED_PAD src0_sel:WORD_1 src1_sel:DWORD
	v_cmp_lt_u32_e32 vcc, s74, v133
	ds_write_b128 v32, v[158:161] offset:35984
	s_and_saveexec_b64 s[58:59], vcc
	s_cbranch_execz .LBB0_1506
	v_mov_b64_e32 v[144:145], v[82:83]
	v_mov_b64_e32 v[146:147], v[84:85]
	v_mov_b64_e32 v[150:151], v[80:81]
	global_load_dword v65, v[146:147], off
	global_load_dword v67, v[146:147], off offset:2048
	global_load_dword v69, v[144:145], off
	global_load_dword v73, v[144:145], off offset:2048
	v_add_co_u32_e32 v122, vcc, 0x1000, v146
	s_nop 1
	v_addc_co_u32_e32 v123, vcc, 0, v147, vcc
	v_add_co_u32_e32 v124, vcc, 0x1000, v144
	s_nop 1
	v_addc_co_u32_e32 v125, vcc, 0, v145, vcc
	global_load_dword v96, v[122:123], off
	global_load_dword v97, v[122:123], off offset:2048
	global_load_dword v98, v[124:125], off
	s_nop 0
	global_load_dword v122, v[124:125], off offset:2048
	v_add_co_u32_e32 v124, vcc, s61, v146
	s_nop 1
	v_addc_co_u32_e32 v125, vcc, 0, v147, vcc
	v_add_co_u32_e32 v126, vcc, s61, v144
	s_nop 1
	v_addc_co_u32_e32 v127, vcc, 0, v145, vcc
	v_add_co_u32_e32 v128, vcc, s67, v146
	global_load_dword v123, v[124:125], off
	s_nop 0
	global_load_dword v124, v[124:125], off offset:2048
	s_nop 0
	global_load_dword v125, v[126:127], off
	s_nop 0
	global_load_dword v126, v[126:127], off offset:2048
	v_addc_co_u32_e32 v129, vcc, 0, v147, vcc
	v_add_co_u32_e32 v130, vcc, s67, v144
	s_nop 1
	v_addc_co_u32_e32 v131, vcc, 0, v145, vcc
	v_add_co_u32_e32 v134, vcc, s62, v146
	global_load_dword v127, v[128:129], off
	s_nop 0
	global_load_dword v128, v[128:129], off offset:2048
	s_nop 0
	global_load_dword v129, v[130:131], off
	s_nop 0
	global_load_dword v130, v[130:131], off offset:2048
	v_addc_co_u32_e32 v135, vcc, 0, v147, vcc
	v_add_co_u32_e32 v136, vcc, s62, v144
	s_nop 1
	v_addc_co_u32_e32 v137, vcc, 0, v145, vcc
	v_add_co_u32_e32 v138, vcc, s72, v146
	global_load_dword v131, v[134:135], off
	global_load_dword v132, v[134:135], off offset:2048
	s_nop 0
	global_load_dword v134, v[136:137], off
	global_load_dword v135, v[136:137], off offset:2048
	v_addc_co_u32_e32 v139, vcc, 0, v147, vcc
	v_add_co_u32_e32 v140, vcc, s72, v144
	s_nop 1
	v_addc_co_u32_e32 v141, vcc, 0, v145, vcc
	v_add_co_u32_e32 v142, vcc, s63, v146
	global_load_dword v136, v[138:139], off
	global_load_dword v137, v[138:139], off offset:2048
	s_nop 0
	global_load_dword v138, v[140:141], off
	global_load_dword v139, v[140:141], off offset:2048
	v_addc_co_u32_e32 v143, vcc, 0, v147, vcc
	v_add_co_u32_e32 v148, vcc, s63, v144
	s_nop 1
	v_addc_co_u32_e32 v149, vcc, 0, v145, vcc
	v_add_co_u32_e32 v146, vcc, 0x7000, v146
	global_load_dword v140, v[142:143], off
	global_load_dword v141, v[142:143], off offset:2048
	s_nop 0
	global_load_dword v142, v[148:149], off
	global_load_dword v143, v[148:149], off offset:2048
	v_addc_co_u32_e32 v147, vcc, 0, v147, vcc
	v_add_co_u32_e32 v148, vcc, 0x7000, v144
	s_nop 1
	v_addc_co_u32_e32 v149, vcc, 0, v145, vcc
	v_add_co_u32_e32 v152, vcc, 0x1000, v150
	global_load_dword v144, v[146:147], off
	global_load_dword v145, v[146:147], off offset:2048
	s_nop 0
	global_load_dword v146, v[148:149], off
	global_load_dword v147, v[148:149], off offset:2048
	s_nop 0
	global_load_dword v148, v[150:151], off
	global_load_dword v149, v[150:151], off offset:2048
	v_addc_co_u32_e32 v153, vcc, 0, v151, vcc
	v_add_co_u32_e32 v154, vcc, 0x2000, v150
	s_nop 1
	v_addc_co_u32_e32 v155, vcc, 0, v151, vcc
	v_add_co_u32_e32 v158, vcc, 0x3000, v150
	s_nop 1
	v_addc_co_u32_e32 v159, vcc, 0, v151, vcc
	global_load_dword v150, v[152:153], off
	global_load_dword v151, v[152:153], off offset:2048
	s_nop 0
	global_load_dword v152, v[154:155], off
	global_load_dword v153, v[154:155], off offset:2048
	s_nop 0
	global_load_dword v154, v[158:159], off
	global_load_dword v155, v[158:159], off offset:2048
	s_branch .LBB0_1506
.LBB0_1511:
	s_or_b64 exec, exec, s[56:57]
	s_and_saveexec_b64 s[56:57], s[40:41]
	s_cbranch_execz .LBB0_1502
	v_lshlrev_b64 v[32:33], 16, v[76:77]
	v_lshl_add_u64 v[32:33], s[50:51], 0, v[32:33]
	v_lshl_add_u64 v[32:33], v[74:75], 2, v[32:33]
	s_waitcnt vmcnt(0)
	v_mov_b32_e32 v67, v71
	v_lshl_add_u64 v[32:33], v[32:33], 0, v[66:67]
	v_mov_b32_e32 v69, v71
	v_lshl_add_u64 v[32:33], v[32:33], 0, v[68:69]
	v_mov_b32_e32 v73, v71
	v_lshl_add_u64 v[32:33], v[32:33], 0, v[72:73]
	global_store_dword v[32:33], v12, off
	global_store_dword v[32:33], v13, off offset:512
	global_store_dword v[32:33], v14, off offset:1024
	global_store_dword v[32:33], v15, off offset:1536
	v_add_co_u32_e32 v12, vcc, s61, v32
	s_nop 1
	v_addc_co_u32_e32 v13, vcc, 0, v33, vcc
	global_store_dword v[12:13], v0, off
	global_store_dword v[12:13], v1, off offset:512
	global_store_dword v[12:13], v2, off offset:1024
	global_store_dword v[12:13], v3, off offset:1536
	v_add_co_u32_e32 v0, vcc, s62, v32
	s_nop 1
	v_addc_co_u32_e32 v1, vcc, 0, v33, vcc
	global_store_dword v[0:1], v8, off
	global_store_dword v[0:1], v9, off offset:512
	global_store_dword v[0:1], v10, off offset:1024
	global_store_dword v[0:1], v11, off offset:1536
	v_add_co_u32_e32 v0, vcc, s63, v32
	s_nop 1
	v_addc_co_u32_e32 v1, vcc, 0, v33, vcc
	global_store_dword v[0:1], v4, off
	global_store_dword v[0:1], v5, off offset:512
	global_store_dword v[0:1], v6, off offset:1024
	global_store_dword v[0:1], v7, off offset:1536
	v_add_co_u32_e32 v0, vcc, s64, v32
	s_nop 1
	v_addc_co_u32_e32 v1, vcc, 0, v33, vcc
	global_store_dword v[0:1], v20, off
	global_store_dword v[0:1], v21, off offset:512
	global_store_dword v[0:1], v22, off offset:1024
	global_store_dword v[0:1], v23, off offset:1536
	v_add_co_u32_e32 v0, vcc, s65, v32
	s_nop 1
	v_addc_co_u32_e32 v1, vcc, 0, v33, vcc
	global_store_dword v[0:1], v16, off
	global_store_dword v[0:1], v17, off offset:512
	global_store_dword v[0:1], v18, off offset:1024
	global_store_dword v[0:1], v19, off offset:1536
	v_add_co_u32_e32 v0, vcc, 0xc000, v32
	s_nop 1
	v_addc_co_u32_e32 v1, vcc, 0, v33, vcc
	global_store_dword v[0:1], v24, off
	global_store_dword v[0:1], v25, off offset:512
	global_store_dword v[0:1], v26, off offset:1024
	global_store_dword v[0:1], v27, off offset:1536
	v_add_co_u32_e32 v0, vcc, 0xe000, v32
	s_nop 1
	v_addc_co_u32_e32 v1, vcc, 0, v33, vcc
	global_store_dword v[0:1], v28, off
	global_store_dword v[0:1], v29, off offset:512
	global_store_dword v[0:1], v30, off offset:1024
	global_store_dword v[0:1], v31, off offset:1536
	s_branch .LBB0_1502

.LBB0_2224:
	ds_bpermute_b32 v0, v187, v175
	ds_bpermute_b32 v1, v187, v174
	s_lshl_b32 s2, s15, 1
	v_mov_b32_e32 v149, v145
	s_add_i32 s28, s28, s78
	s_waitcnt lgkmcnt(1)
	v_add_f32_e32 v0, v175, v0
	ds_bpermute_b32 v2, v186, v0
	s_waitcnt lgkmcnt(1)
	v_add_f32_e32 v1, v174, v1
	ds_bpermute_b32 v3, v186, v1
	s_cmpk_gt_i32 s28, 0x5ff
	s_waitcnt lgkmcnt(1)
	v_add_f32_e32 v0, v0, v2
	s_waitcnt lgkmcnt(0)
	v_add_f32_e32 v1, v1, v3
	v_rcp_f32_e32 v10, v0
	v_rcp_f32_e32 v0, v1
	s_nop 0
	v_mul_f32_e32 v12, v189, v0
	v_pk_mul_f32 v[2:3], v[78:79], v[12:13] op_sel_hi:[1,0]
	v_pk_mul_f32 v[6:7], v[70:71], v[12:13] op_sel_hi:[1,0]
	v_pk_fma_f32 v[4:5], v[74:75], v[10:11], v[2:3] op_sel_hi:[1,0,1] neg_lo:[0,0,1] neg_hi:[0,0,1]
	v_lshl_add_u64 v[2:3], s[4:5], 0, v[152:153]
	v_lshl_add_u64 v[2:3], v[2:3], 0, s[2:3]
	v_lshl_add_u64 v[2:3], v[2:3], 0, v[148:149]
	global_load_dwordx2 v[74:75], v[2:3], off
	v_pk_fma_f32 v[66:67], v[66:67], v[10:11], v[6:7] op_sel_hi:[1,0,1] neg_lo:[0,0,1] neg_hi:[0,0,1]
	global_load_dwordx4 v[6:9], v[146:147], off offset:512
	v_pk_mul_f32 v[68:69], v[68:69], v[12:13] op_sel_hi:[1,0]
	v_pk_mul_f32 v[0:1], v[76:77], v[12:13] op_sel_hi:[1,0]
	v_pk_fma_f32 v[64:65], v[64:65], v[10:11], v[68:69] op_sel_hi:[1,0,1] neg_lo:[0,0,1] neg_hi:[0,0,1]
	v_pk_mul_f32 v[62:63], v[62:63], v[12:13] op_sel_hi:[1,0]
	v_pk_mul_f32 v[68:69], v[64:65], v[64:65]
	v_pk_mul_f32 v[60:61], v[60:61], v[12:13] op_sel_hi:[1,0]
	v_pk_mul_f32 v[54:55], v[54:55], v[12:13] op_sel_hi:[1,0]
	v_pk_mul_f32 v[52:53], v[52:53], v[12:13] op_sel_hi:[1,0]
	v_pk_mul_f32 v[46:47], v[46:47], v[12:13] op_sel_hi:[1,0]
	v_pk_mul_f32 v[44:45], v[44:45], v[12:13] op_sel_hi:[1,0]
	v_pk_mul_f32 v[38:39], v[38:39], v[12:13] op_sel_hi:[1,0]
	v_pk_mul_f32 v[36:37], v[36:37], v[12:13] op_sel_hi:[1,0]
	v_pk_mul_f32 v[30:31], v[30:31], v[12:13] op_sel_hi:[1,0]
	v_pk_mul_f32 v[28:29], v[28:29], v[12:13] op_sel_hi:[1,0]
	v_pk_mul_f32 v[22:23], v[22:23], v[12:13] op_sel_hi:[1,0]
	v_pk_mul_f32 v[12:13], v[20:21], v[12:13] op_sel_hi:[1,0]
	v_pk_fma_f32 v[0:1], v[72:73], v[10:11], v[0:1] op_sel_hi:[1,0,1] neg_lo:[0,0,1] neg_hi:[0,0,1]
	v_pk_mul_f32 v[70:71], v[66:67], v[66:67]
	v_pk_fma_f32 v[58:59], v[58:59], v[10:11], v[62:63] op_sel_hi:[1,0,1] neg_lo:[0,0,1] neg_hi:[0,0,1]
	v_pk_fma_f32 v[56:57], v[56:57], v[10:11], v[60:61] op_sel_hi:[1,0,1] neg_lo:[0,0,1] neg_hi:[0,0,1]
	v_pk_fma_f32 v[50:51], v[50:51], v[10:11], v[54:55] op_sel_hi:[1,0,1] neg_lo:[0,0,1] neg_hi:[0,0,1]
	v_pk_fma_f32 v[48:49], v[48:49], v[10:11], v[52:53] op_sel_hi:[1,0,1] neg_lo:[0,0,1] neg_hi:[0,0,1]
	v_pk_fma_f32 v[42:43], v[42:43], v[10:11], v[46:47] op_sel_hi:[1,0,1] neg_lo:[0,0,1] neg_hi:[0,0,1]
	v_pk_fma_f32 v[40:41], v[40:41], v[10:11], v[44:45] op_sel_hi:[1,0,1] neg_lo:[0,0,1] neg_hi:[0,0,1]
	v_pk_fma_f32 v[34:35], v[34:35], v[10:11], v[38:39] op_sel_hi:[1,0,1] neg_lo:[0,0,1] neg_hi:[0,0,1]
	v_pk_fma_f32 v[32:33], v[32:33], v[10:11], v[36:37] op_sel_hi:[1,0,1] neg_lo:[0,0,1] neg_hi:[0,0,1]
	v_pk_fma_f32 v[26:27], v[26:27], v[10:11], v[30:31] op_sel_hi:[1,0,1] neg_lo:[0,0,1] neg_hi:[0,0,1]
	v_pk_fma_f32 v[24:25], v[24:25], v[10:11], v[28:29] op_sel_hi:[1,0,1] neg_lo:[0,0,1] neg_hi:[0,0,1]
	v_pk_fma_f32 v[18:19], v[18:19], v[10:11], v[22:23] op_sel_hi:[1,0,1] neg_lo:[0,0,1] neg_hi:[0,0,1]
	v_pk_fma_f32 v[10:11], v[16:17], v[10:11], v[12:13] op_sel_hi:[1,0,1] neg_lo:[0,0,1] neg_hi:[0,0,1]
	v_add_f32_e32 v16, v68, v69
	v_add_f32_e32 v16, v70, v16
	v_pk_mul_f32 v[60:61], v[56:57], v[56:57]
	v_add_f32_e32 v16, v71, v16
	v_add_f32_e32 v16, v60, v16
	v_pk_mul_f32 v[62:63], v[58:59], v[58:59]
	v_add_f32_e32 v16, v61, v16
	v_add_f32_e32 v16, v62, v16
	v_pk_mul_f32 v[52:53], v[48:49], v[48:49]
	v_add_f32_e32 v16, v63, v16
	v_add_f32_e32 v16, v52, v16
	v_pk_mul_f32 v[54:55], v[50:51], v[50:51]
	v_add_f32_e32 v16, v53, v16
	v_add_f32_e32 v16, v54, v16
	v_pk_mul_f32 v[44:45], v[40:41], v[40:41]
	v_add_f32_e32 v16, v55, v16
	v_add_f32_e32 v16, v44, v16
	v_pk_mul_f32 v[46:47], v[42:43], v[42:43]
	v_add_f32_e32 v16, v45, v16
	v_add_f32_e32 v16, v46, v16
	v_pk_mul_f32 v[36:37], v[32:33], v[32:33]
	v_add_f32_e32 v16, v47, v16
	v_add_f32_e32 v16, v36, v16
	v_pk_mul_f32 v[38:39], v[34:35], v[34:35]
	v_add_f32_e32 v16, v37, v16
	v_add_f32_e32 v16, v38, v16
	v_pk_mul_f32 v[28:29], v[24:25], v[24:25]
	v_add_f32_e32 v16, v39, v16
	v_add_f32_e32 v16, v28, v16
	v_pk_mul_f32 v[30:31], v[26:27], v[26:27]
	v_add_f32_e32 v16, v29, v16
	v_add_f32_e32 v16, v30, v16
	v_pk_mul_f32 v[12:13], v[10:11], v[10:11]
	v_add_f32_e32 v16, v31, v16
	v_add_f32_e32 v12, v12, v16
	v_pk_mul_f32 v[22:23], v[18:19], v[18:19]
	v_add_f32_e32 v12, v13, v12
	v_add_f32_e32 v12, v22, v12
	v_pk_mul_f32 v[14:15], v[0:1], v[0:1]
	v_add_f32_e32 v12, v23, v12
	v_add_f32_e32 v12, v14, v12
	v_pk_mul_f32 v[72:73], v[4:5], v[4:5]
	v_add_f32_e32 v12, v15, v12
	v_add_f32_e32 v12, v72, v12
	v_add_f32_e32 v12, v73, v12
	global_load_dwordx4 v[244:247], v[146:147], off offset:576
	global_load_dwordx4 v[36:39], v[146:147], off offset:640
	global_load_dwordx4 v[44:47], v[146:147], off offset:704
	global_load_dwordx4 v[52:55], v[146:147], off offset:768
	global_load_dwordx4 v[60:63], v[146:147], off offset:832
	global_load_dwordx4 v[68:71], v[146:147], off offset:896
	global_load_dwordx4 v[76:79], v[146:147], off offset:960
	ds_bpermute_b32 v13, v187, v12
	s_waitcnt vmcnt(8)
	v_and_b32_e32 v23, 0xffff0000, v75
	v_lshlrev_b32_e32 v20, 16, v74
	s_waitcnt lgkmcnt(0)
	v_add_f32_e32 v21, v12, v13
	ds_bpermute_b32 v22, v186, v21
	global_load_dwordx2 v[12:13], v[2:3], off offset:32
	global_load_dwordx2 v[14:15], v[2:3], off offset:64
	global_load_dwordx2 v[16:17], v[2:3], off offset:96
	global_load_dwordx2 v[248:249], v[2:3], off offset:128
	global_load_dwordx2 v[250:251], v[2:3], off offset:160
	global_load_dwordx2 v[252:253], v[2:3], off offset:192
	global_load_dwordx2 v[254:255], v[2:3], off offset:224
	s_waitcnt lgkmcnt(0)
	v_add_f32_e32 v21, v21, v22
	v_fmamk_f32 v21, v21, 0x3c000000, v212
	v_mul_f32_e32 v22, 0x4b800000, v21
	v_cmp_gt_f32_e32 vcc, s27, v21
	s_nop 1
	v_cndmask_b32_e32 v21, v21, v22, vcc
	v_rsq_f32_e32 v28, v21
	v_lshlrev_b32_e32 v22, 16, v75
	v_and_b32_e32 v21, 0xffff0000, v74
	v_mul_f32_e32 v29, 0x45800000, v28
	v_cndmask_b32_e32 v28, v28, v29, vcc
	v_mul_f32_e32 v28, 0x3ee34c56, v28
	v_pk_mul_f32 v[30:31], v[66:67], v[28:29] op_sel_hi:[1,0]
	v_pk_mul_f32 v[10:11], v[10:11], v[28:29] op_sel_hi:[1,0]
	s_waitcnt vmcnt(14)
	v_pk_mul_f32 v[8:9], v[8:9], v[30:31]
	v_pk_mul_f32 v[4:5], v[4:5], v[28:29] op_sel_hi:[1,0]
	v_pk_mul_f32 v[8:9], v[8:9], v[22:23]
	v_pk_mul_f32 v[22:23], v[64:65], v[28:29] op_sel_hi:[1,0]
	v_pk_mul_f32 v[0:1], v[0:1], v[28:29] op_sel_hi:[1,0]
	v_pk_mul_f32 v[6:7], v[6:7], v[22:23]
	v_pk_mul_f32 v[22:23], v[56:57], v[28:29] op_sel_hi:[1,0]
	v_pk_mul_f32 v[6:7], v[6:7], v[20:21]
	v_pk_mul_f32 v[20:21], v[58:59], v[28:29] op_sel_hi:[1,0]
	v_cvt_pk_bf16_f32 v6, v6, v7
	v_cvt_pk_bf16_f32 v7, v8, v9
	global_store_dwordx2 v[2:3], v[6:7], off
	s_waitcnt vmcnt(7)
	v_lshlrev_b32_e32 v30, 16, v12
	v_and_b32_e32 v31, 0xffff0000, v12
	v_lshlrev_b32_e32 v12, 16, v13
	v_and_b32_e32 v13, 0xffff0000, v13
	v_pk_mul_f32 v[8:9], v[246:247], v[20:21]
	v_pk_mul_f32 v[6:7], v[244:245], v[22:23]
	v_pk_mul_f32 v[8:9], v[8:9], v[12:13]
	v_pk_mul_f32 v[6:7], v[6:7], v[30:31]
	v_pk_mul_f32 v[12:13], v[50:51], v[28:29] op_sel_hi:[1,0]
	v_cvt_pk_bf16_f32 v6, v6, v7
	v_cvt_pk_bf16_f32 v7, v8, v9
	global_store_dwordx2 v[2:3], v[6:7], off offset:32
	v_pk_mul_f32 v[20:21], v[48:49], v[28:29] op_sel_hi:[1,0]
	s_waitcnt vmcnt(7)
	v_lshlrev_b32_e32 v22, 16, v14
	v_and_b32_e32 v23, 0xffff0000, v14
	v_lshlrev_b32_e32 v14, 16, v15
	v_and_b32_e32 v15, 0xffff0000, v15
	v_pk_mul_f32 v[30:31], v[32:33], v[28:29] op_sel_hi:[1,0]
	v_pk_mul_f32 v[8:9], v[38:39], v[12:13]
	v_pk_mul_f32 v[6:7], v[36:37], v[20:21]
	v_pk_mul_f32 v[8:9], v[8:9], v[14:15]
	v_pk_mul_f32 v[6:7], v[6:7], v[22:23]
	v_pk_mul_f32 v[14:15], v[42:43], v[28:29] op_sel_hi:[1,0]
	v_cvt_pk_bf16_f32 v6, v6, v7
	v_cvt_pk_bf16_f32 v7, v8, v9
	global_store_dwordx2 v[2:3], v[6:7], off offset:64
	s_nop 0
	v_pk_mul_f32 v[20:21], v[40:41], v[28:29] op_sel_hi:[1,0]
	s_waitcnt vmcnt(7)
	v_lshlrev_b32_e32 v22, 16, v16
	v_and_b32_e32 v23, 0xffff0000, v16
	v_lshlrev_b32_e32 v16, 16, v17
	v_and_b32_e32 v17, 0xffff0000, v17
	v_pk_mul_f32 v[8:9], v[46:47], v[14:15]
	v_pk_mul_f32 v[6:7], v[44:45], v[20:21]
	v_pk_mul_f32 v[8:9], v[8:9], v[16:17]
	v_pk_mul_f32 v[6:7], v[6:7], v[22:23]
	v_pk_mul_f32 v[22:23], v[34:35], v[28:29] op_sel_hi:[1,0]
	v_cvt_pk_bf16_f32 v6, v6, v7
	v_cvt_pk_bf16_f32 v7, v8, v9
	global_store_dwordx2 v[2:3], v[6:7], off offset:96
	s_nop 0
	s_waitcnt vmcnt(7)
	v_lshlrev_b32_e32 v32, 16, v248
	v_and_b32_e32 v33, 0xffff0000, v248
	v_lshlrev_b32_e32 v12, 16, v249
	v_and_b32_e32 v13, 0xffff0000, v249
	v_pk_mul_f32 v[8:9], v[54:55], v[22:23]
	v_pk_mul_f32 v[6:7], v[52:53], v[30:31]
	v_pk_mul_f32 v[8:9], v[8:9], v[12:13]
	v_pk_mul_f32 v[6:7], v[6:7], v[32:33]
	v_pk_mul_f32 v[12:13], v[26:27], v[28:29] op_sel_hi:[1,0]
	v_cvt_pk_bf16_f32 v6, v6, v7
	v_cvt_pk_bf16_f32 v7, v8, v9
	global_store_dwordx2 v[2:3], v[6:7], off offset:128
	v_pk_mul_f32 v[22:23], v[24:25], v[28:29] op_sel_hi:[1,0]
	s_waitcnt vmcnt(7)
	v_lshlrev_b32_e32 v24, 16, v250
	v_and_b32_e32 v25, 0xffff0000, v250
	v_lshlrev_b32_e32 v14, 16, v251
	v_and_b32_e32 v15, 0xffff0000, v251
	v_pk_mul_f32 v[8:9], v[62:63], v[12:13]
	v_pk_mul_f32 v[6:7], v[60:61], v[22:23]
	v_pk_mul_f32 v[8:9], v[8:9], v[14:15]
	v_pk_mul_f32 v[6:7], v[6:7], v[24:25]
	v_pk_mul_f32 v[12:13], v[18:19], v[28:29] op_sel_hi:[1,0]
	v_cvt_pk_bf16_f32 v6, v6, v7
	v_cvt_pk_bf16_f32 v7, v8, v9
	global_store_dwordx2 v[2:3], v[6:7], off offset:160
	s_waitcnt vmcnt(7)
	v_lshlrev_b32_e32 v14, 16, v252
	v_and_b32_e32 v15, 0xffff0000, v252
	v_lshlrev_b32_e32 v16, 16, v253
	v_and_b32_e32 v17, 0xffff0000, v253
	v_pk_mul_f32 v[8:9], v[12:13], v[70:71]
	v_pk_mul_f32 v[6:7], v[10:11], v[68:69]
	v_pk_mul_f32 v[8:9], v[8:9], v[16:17]
	v_pk_mul_f32 v[6:7], v[6:7], v[14:15]
	s_waitcnt vmcnt(6)
	v_lshlrev_b32_e32 v10, 16, v254
	v_cvt_pk_bf16_f32 v6, v6, v7
	v_cvt_pk_bf16_f32 v7, v8, v9
	global_store_dwordx2 v[2:3], v[6:7], off offset:192
	v_and_b32_e32 v11, 0xffff0000, v254
	v_lshlrev_b32_e32 v12, 16, v255
	v_and_b32_e32 v13, 0xffff0000, v255
	v_pk_mul_f32 v[4:5], v[4:5], v[78:79]
	v_pk_mul_f32 v[0:1], v[0:1], v[76:77]
	v_pk_mul_f32 v[4:5], v[4:5], v[12:13]
	v_pk_mul_f32 v[0:1], v[0:1], v[10:11]
	s_nop 0
	v_cvt_pk_bf16_f32 v0, v0, v1
	v_cvt_pk_bf16_f32 v1, v4, v5
	global_store_dwordx2 v[2:3], v[0:1], off offset:224
	s_cbranch_scc1 .LBB0_2252
